# FFT: ds_read2_b64 split into ds_read_b64 pairs (address-overwriting half last), stores issued right after their producers, barrier only on first batch pair
# speedup vs baseline: 1.0136x; 1.0021x over previous
.LBB0_291:
	v_lshrrev_b32_e32 v0, 3, v66
	v_add_u32_e32 v1, 0x200, v66
	v_and_b32_e32 v0, 0x1ffffff0, v0
	v_lshrrev_b32_e32 v1, 3, v1
	v_and_b32_e32 v1, 0x1ffffff0, v1
	v_mad_u64_u32 v[82:83], s[40:41], v0, s25, v[60:61]
	v_mov_b32_e32 v86, v65
	v_mov_b32_e32 v140, v65
	v_mad_u64_u32 v[84:85], s[40:41], v1, s25, v[60:61]
	v_add_u32_e32 v16, 0x2000, v82
	ds_read_b64 v[134:135], v82
	ds_read_b64 v[136:137], v82 offset:1032
	ds_read_b64 v[12:13], v84
	ds_read_b64 v[14:15], v84 offset:1032
	ds_read_b64 v[142:143], v16 offset:64
	ds_read_b64 v[144:145], v16 offset:1096
	v_add_u32_e32 v16, 0x2000, v84
	v_add_u32_e32 v0, 0x800, v82
	ds_read_b64 v[28:29], v16 offset:64
	ds_read_b64 v[30:31], v16 offset:1096
	v_add_u32_e32 v16, 0x2800, v82
	ds_read_b64 v[48:49], v0 offset:16
	ds_read_b64 v[50:51], v0 offset:1048
	ds_read_b64 v[52:53], v16 offset:80
	ds_read_b64 v[54:55], v16 offset:1112
	v_add_u32_e32 v0, 0x800, v84
	v_add_u32_e32 v16, 0x2800, v84
	ds_read_b64 v[8:9], v0 offset:16
	ds_read_b64 v[10:11], v0 offset:1048
	v_add_u32_e32 v0, 0x1000, v82
	ds_read_b64 v[24:25], v16 offset:80
	ds_read_b64 v[26:27], v16 offset:1112
	v_add_u32_e32 v16, 0x3000, v82
	s_waitcnt lgkmcnt(10)
	v_pk_add_f32 v[132:133], v[134:135], v[142:143]
	v_pk_add_f32 v[130:131], v[134:135], v[142:143] neg_lo:[0,1] neg_hi:[0,1]
	v_pk_add_f32 v[134:135], v[136:137], v[144:145]
	v_pk_add_f32 v[136:137], v[136:137], v[144:145] neg_lo:[0,1] neg_hi:[0,1]
	ds_read_b64 v[40:41], v0 offset:32
	ds_read_b64 v[42:43], v0 offset:1064
	ds_read_b64 v[44:45], v16 offset:96
	ds_read_b64 v[46:47], v16 offset:1128
	v_pk_mul_f32 v[138:139], v[136:137], s[42:43] op_sel_hi:[0,1]
	s_mov_b32 s65, s42
	v_add_u32_e32 v0, 0x1000, v84
	v_add_u32_e32 v16, 0x3000, v84
	v_pk_fma_f32 v[136:137], v[136:137], s[64:65], v[138:139] op_sel:[1,0,0]
	s_waitcnt lgkmcnt(8)
	v_pk_add_f32 v[138:139], v[48:49], v[52:53]
	v_pk_add_f32 v[48:49], v[48:49], v[52:53] neg_lo:[0,1] neg_hi:[0,1]
	ds_read_b64 v[4:5], v0 offset:32
	ds_read_b64 v[6:7], v0 offset:1064
	v_add_u32_e32 v0, 0x1800, v82
	ds_read_b64 v[20:21], v16 offset:96
	ds_read_b64 v[22:23], v16 offset:1128
	v_add_u32_e32 v16, 0x3800, v82
	v_mul_f32_e32 v52, 0x3f3504f3, v49
	ds_read_b64 v[32:33], v0 offset:48
	ds_read_b64 v[34:35], v0 offset:1080
	ds_read_b64 v[36:37], v16 offset:112
	ds_read_b64 v[38:39], v16 offset:1144
	v_pk_fma_f32 v[48:49], v[48:49], s[56:57], v[52:53] op_sel_hi:[0,1,0]
	v_pk_add_f32 v[52:53], v[50:51], v[54:55]
	v_pk_add_f32 v[50:51], v[50:51], v[54:55] neg_lo:[0,1] neg_hi:[0,1]
	s_mov_b32 s66, s64
	v_pk_mul_f32 v[54:55], v[50:51], s[66:67] op_sel_hi:[0,1]
	s_mov_b32 s44, s42
	s_mov_b32 s45, s64
	v_cvt_f32_i32_e32 v83, v86
	v_pk_fma_f32 v[50:51], v[50:51], s[44:45], v[54:55] op_sel:[1,0,0]
	s_waitcnt lgkmcnt(8)
	v_pk_add_f32 v[54:55], v[40:41], v[44:45]
	v_pk_add_f32 v[40:41], v[40:41], v[44:45] neg_lo:[0,1] neg_hi:[0,1]
	s_mov_b32 s58, s43
	v_xor_b32_e32 v45, 0x80000000, v40
	v_mov_b32_e32 v44, v41
	v_pk_add_f32 v[40:41], v[42:43], v[46:47]
	v_pk_add_f32 v[42:43], v[42:43], v[46:47] neg_lo:[0,1] neg_hi:[0,1]
	s_mov_b32 s59, s67
	v_pk_mul_f32 v[46:47], v[42:43], s[58:59] op_sel_hi:[0,1]
	v_pk_fma_f32 v[42:43], v[42:43], s[42:43], v[46:47] op_sel:[1,0,0]
	s_waitcnt lgkmcnt(0)
	v_pk_add_f32 v[46:47], v[32:33], v[36:37]
	v_pk_add_f32 v[32:33], v[32:33], v[36:37] neg_lo:[0,1] neg_hi:[0,1]
	v_mul_f32_e32 v83, 0x3a000000, v83
	v_mul_f32_e32 v36, 0xbf3504f3, v32
	v_cos_f32_e32 v94, v83
	v_pk_fma_f32 v[32:33], v[32:33], s[56:57], v[36:37] op_sel:[1,0,0] op_sel_hi:[1,1,0]
	v_pk_add_f32 v[36:37], v[34:35], v[38:39]
	v_pk_add_f32 v[34:35], v[34:35], v[38:39] neg_lo:[0,1] neg_hi:[0,1]
	s_mov_b32 s40, s67
	s_mov_b32 s41, s43
	v_sin_f32_e32 v98, v83
	v_pk_mul_f32 v[38:39], v[34:35], s[40:41] op_sel_hi:[0,1]
	v_pk_fma_f32 v[34:35], v[34:35], s[66:67], v[38:39] op_sel:[1,0,0]
	v_pk_add_f32 v[38:39], v[132:133], v[54:55]
	v_pk_add_f32 v[54:55], v[132:133], v[54:55] neg_lo:[0,1] neg_hi:[0,1]
	v_pk_add_f32 v[132:133], v[134:135], v[40:41]
	v_pk_add_f32 v[40:41], v[134:135], v[40:41] neg_lo:[0,1] neg_hi:[0,1]
	v_mov_b32_e32 v99, v94
	v_mul_f32_e32 v134, 0x3f3504f3, v41
	v_pk_fma_f32 v[40:41], v[40:41], s[56:57], v[134:135] op_sel_hi:[0,1,0]
	v_pk_add_f32 v[134:135], v[138:139], v[46:47]
	v_pk_add_f32 v[46:47], v[138:139], v[46:47] neg_lo:[0,1] neg_hi:[0,1]
	v_xor_b32_e32 v95, 0x80000000, v98
	v_pk_mul_f32 v[86:87], v[98:99], v[98:99] op_sel_hi:[1,0] neg_lo:[0,1] neg_hi:[0,1]
	v_xor_b32_e32 v139, 0x80000000, v46
	v_mov_b32_e32 v138, v47
	v_pk_add_f32 v[46:47], v[52:53], v[36:37]
	v_pk_add_f32 v[36:37], v[52:53], v[36:37] neg_lo:[0,1] neg_hi:[0,1]
	v_pk_fma_f32 v[100:101], v[94:95], v[94:95], v[86:87] op_sel_hi:[1,0,1]
	v_mul_f32_e32 v52, 0xbf3504f3, v36
	v_pk_mul_f32 v[86:87], v[98:99], v[100:101] op_sel:[0,1]
	v_pk_fma_f32 v[36:37], v[36:37], s[56:57], v[52:53] op_sel:[1,0,0] op_sel_hi:[1,1,0]
	v_pk_add_f32 v[52:53], v[130:131], v[44:45]
	v_pk_add_f32 v[44:45], v[130:131], v[44:45] neg_lo:[0,1] neg_hi:[0,1]
	v_pk_add_f32 v[130:131], v[136:137], v[42:43]
	v_pk_add_f32 v[42:43], v[136:137], v[42:43] neg_lo:[0,1] neg_hi:[0,1]
	v_pk_fma_f32 v[102:103], v[94:95], v[100:101], v[86:87] op_sel_hi:[1,0,1]
	v_pk_mul_f32 v[86:87], v[100:101], v[100:101] op_sel:[1,1] op_sel_hi:[1,0] neg_lo:[0,1]
	v_mul_f32_e32 v136, 0x3f3504f3, v43
	v_pk_fma_f32 v[106:107], v[100:101], v[100:101], v[86:87] op_sel_hi:[1,0,1]
	v_pk_fma_f32 v[42:43], v[42:43], s[56:57], v[136:137] op_sel_hi:[0,1,0]
	v_pk_add_f32 v[136:137], v[48:49], v[32:33]
	v_pk_add_f32 v[32:33], v[48:49], v[32:33] neg_lo:[0,1] neg_hi:[0,1]
	v_pk_mul_f32 v[86:87], v[98:99], v[106:107] op_sel:[0,1]
	v_xor_b32_e32 v49, 0x80000000, v32
	v_mov_b32_e32 v48, v33
	v_pk_add_f32 v[32:33], v[50:51], v[34:35]
	v_pk_add_f32 v[34:35], v[50:51], v[34:35] neg_lo:[0,1] neg_hi:[0,1]
	v_pk_fma_f32 v[108:109], v[94:95], v[106:107], v[86:87] op_sel_hi:[1,0,1]
	v_pk_mul_f32 v[86:87], v[100:101], v[106:107] op_sel:[1,1] op_sel_hi:[0,1] neg_lo:[1,0]
	v_mul_f32_e32 v50, 0xbf3504f3, v34
	v_pk_fma_f32 v[110:111], v[100:101], v[106:107], v[86:87] op_sel_hi:[1,0,1]
	v_pk_mul_f32 v[86:87], v[106:107], v[102:103] op_sel:[1,1] op_sel_hi:[1,0] neg_lo:[0,1]
	v_pk_fma_f32 v[34:35], v[34:35], s[56:57], v[50:51] op_sel:[1,0,0] op_sel_hi:[1,1,0]
	v_pk_add_f32 v[50:51], v[38:39], v[134:135]
	v_pk_add_f32 v[38:39], v[38:39], v[134:135] neg_lo:[0,1] neg_hi:[0,1]
	v_pk_add_f32 v[134:135], v[132:133], v[46:47]
	v_pk_add_f32 v[46:47], v[132:133], v[46:47] neg_lo:[0,1] neg_hi:[0,1]
	v_pk_fma_f32 v[114:115], v[102:103], v[106:107], v[86:87] op_sel_hi:[1,0,1]
	v_pk_mul_f32 v[86:87], v[106:107], v[106:107] op_sel:[1,1] op_sel_hi:[1,0] neg_lo:[0,1]
	v_xor_b32_e32 v133, 0x80000000, v46
	v_mov_b32_e32 v132, v47
	v_pk_add_f32 v[46:47], v[54:55], v[138:139]
	v_pk_add_f32 v[54:55], v[54:55], v[138:139] neg_lo:[0,1] neg_hi:[0,1]
	v_pk_add_f32 v[138:139], v[40:41], v[36:37]
	v_pk_add_f32 v[36:37], v[40:41], v[36:37] neg_lo:[0,1] neg_hi:[0,1]
	v_pk_fma_f32 v[116:117], v[106:107], v[106:107], v[86:87] op_sel_hi:[1,0,1]
	v_xor_b32_e32 v41, 0x80000000, v36
	v_mov_b32_e32 v40, v37
	v_pk_add_f32 v[36:37], v[52:53], v[136:137]
	v_pk_add_f32 v[52:53], v[52:53], v[136:137] neg_lo:[0,1] neg_hi:[0,1]
	v_pk_add_f32 v[136:137], v[130:131], v[32:33]
	v_pk_add_f32 v[32:33], v[130:131], v[32:33] neg_lo:[0,1] neg_hi:[0,1]
	v_pk_mul_f32 v[86:87], v[98:99], v[116:117] op_sel:[0,1]
	v_xor_b32_e32 v131, 0x80000000, v32
	v_mov_b32_e32 v130, v33
	v_pk_add_f32 v[32:33], v[44:45], v[48:49]
	v_pk_add_f32 v[44:45], v[44:45], v[48:49] neg_lo:[0,1] neg_hi:[0,1]
	v_pk_add_f32 v[48:49], v[42:43], v[34:35]
	v_pk_add_f32 v[34:35], v[42:43], v[34:35] neg_lo:[0,1] neg_hi:[0,1]
	v_pk_fma_f32 v[112:113], v[94:95], v[116:117], v[86:87] op_sel_hi:[1,0,1]
	v_pk_mul_f32 v[86:87], v[100:101], v[116:117] op_sel:[1,1] op_sel_hi:[0,1] neg_lo:[1,0]
	v_xor_b32_e32 v43, 0x80000000, v34
	v_mov_b32_e32 v42, v35
	v_pk_add_f32 v[34:35], v[50:51], v[134:135]
	v_pk_add_f32 v[50:51], v[50:51], v[134:135] neg_lo:[0,1] neg_hi:[0,1]
	v_pk_add_f32 v[134:135], v[38:39], v[132:133]
	v_pk_add_f32 v[38:39], v[38:39], v[132:133] neg_lo:[0,1] neg_hi:[0,1]
	v_pk_add_f32 v[132:133], v[46:47], v[138:139]
	v_pk_add_f32 v[46:47], v[46:47], v[138:139] neg_lo:[0,1] neg_hi:[0,1]
	v_pk_add_f32 v[138:139], v[54:55], v[40:41]
	v_pk_add_f32 v[40:41], v[54:55], v[40:41] neg_lo:[0,1] neg_hi:[0,1]
	v_pk_add_f32 v[54:55], v[36:37], v[136:137]
	v_pk_fma_f32 v[104:105], v[100:101], v[116:117], v[86:87] op_sel_hi:[1,0,1]
	v_pk_mul_f32 v[86:87], v[102:103], v[116:117] op_sel:[1,1] op_sel_hi:[0,1] neg_lo:[1,0]
	v_pk_add_f32 v[36:37], v[36:37], v[136:137] neg_lo:[0,1] neg_hi:[0,1]
	v_pk_add_f32 v[136:137], v[52:53], v[130:131]
	v_pk_add_f32 v[52:53], v[52:53], v[130:131] neg_lo:[0,1] neg_hi:[0,1]
	v_pk_add_f32 v[130:131], v[32:33], v[48:49]
	v_pk_add_f32 v[48:49], v[32:33], v[48:49] neg_lo:[0,1] neg_hi:[0,1]
	v_pk_mul_f32 v[32:33], v[98:99], v[54:55] op_sel:[0,1]
	v_pk_fma_f32 v[96:97], v[102:103], v[116:117], v[86:87] op_sel_hi:[1,0,1]
	v_pk_mul_f32 v[86:87], v[106:107], v[116:117] op_sel:[1,1] op_sel_hi:[0,1] neg_lo:[1,0]
	v_pk_add_f32 v[142:143], v[44:45], v[42:43]
	v_pk_add_f32 v[42:43], v[44:45], v[42:43] neg_lo:[0,1] neg_hi:[0,1]
	v_pk_fma_f32 v[44:45], v[94:95], v[54:55], v[32:33] op_sel_hi:[1,0,1]
	v_pk_mul_f32 v[32:33], v[100:101], v[132:133] op_sel:[1,1] op_sel_hi:[0,1] neg_lo:[1,0]
	v_pk_mul_f32 v[94:95], v[106:107], v[134:135] op_sel:[1,1] op_sel_hi:[0,1] neg_lo:[1,0]
	v_pk_fma_f32 v[86:87], v[106:107], v[116:117], v[86:87] op_sel_hi:[1,0,1]
	v_pk_fma_f32 v[54:55], v[100:101], v[132:133], v[32:33] op_sel_hi:[1,0,1]
	v_pk_fma_f32 v[94:95], v[106:107], v[134:135], v[94:95] op_sel_hi:[1,0,1]
	v_pk_mul_f32 v[100:101], v[110:111], v[138:139] op_sel:[1,1] op_sel_hi:[0,1] neg_lo:[1,0]
	v_pk_fma_f32 v[100:101], v[110:111], v[138:139], v[100:101] op_sel_hi:[1,0,1]
	v_pk_mul_f32 v[106:107], v[116:117], v[50:51] op_sel:[1,1] op_sel_hi:[0,1] neg_lo:[1,0]
	v_pk_add_f32 v[138:139], v[12:13], v[28:29]
	v_pk_add_f32 v[12:13], v[12:13], v[28:29] neg_lo:[0,1] neg_hi:[0,1]
	v_pk_add_f32 v[28:29], v[14:15], v[30:31]
	v_pk_add_f32 v[14:15], v[14:15], v[30:31] neg_lo:[0,1] neg_hi:[0,1]
	v_pk_fma_f32 v[50:51], v[116:117], v[50:51], v[106:107] op_sel_hi:[1,0,1]
	v_pk_mul_f32 v[30:31], v[14:15], s[42:43] op_sel_hi:[0,1]
	v_pk_mul_f32 v[106:107], v[112:113], v[36:37] op_sel:[1,1] op_sel_hi:[0,1] neg_lo:[1,0]
	v_pk_fma_f32 v[14:15], v[14:15], s[64:65], v[30:31] op_sel:[1,0,0]
	v_pk_add_f32 v[30:31], v[8:9], v[24:25]
	v_pk_add_f32 v[8:9], v[8:9], v[24:25] neg_lo:[0,1] neg_hi:[0,1]
	v_add_u32_e32 v0, 0x1800, v84
	v_add_u32_e32 v16, 0x3800, v84
	v_pk_fma_f32 v[36:37], v[112:113], v[36:37], v[106:107] op_sel_hi:[1,0,1]
	v_mul_f32_e32 v24, 0x3f3504f3, v9
	ds_read_b64 v[2:3], v0 offset:1080
	ds_read_b64 v[0:1], v0 offset:48
	ds_read_b64 v[18:19], v16 offset:1144
	ds_read_b64 v[16:17], v16 offset:112
	v_pk_mul_f32 v[106:107], v[104:105], v[46:47] op_sel:[1,1] op_sel_hi:[0,1] neg_lo:[1,0]
	v_pk_fma_f32 v[8:9], v[8:9], s[56:57], v[24:25] op_sel_hi:[0,1,0]
	v_pk_add_f32 v[24:25], v[10:11], v[26:27]
	v_pk_add_f32 v[10:11], v[10:11], v[26:27] neg_lo:[0,1] neg_hi:[0,1]
	v_pk_fma_f32 v[46:47], v[104:105], v[46:47], v[106:107] op_sel_hi:[1,0,1]
	v_pk_mul_f32 v[26:27], v[10:11], s[66:67] op_sel_hi:[0,1]
	v_pk_mul_f32 v[104:105], v[96:97], v[48:49] op_sel:[1,1] op_sel_hi:[0,1] neg_lo:[1,0]
	v_pk_fma_f32 v[10:11], v[10:11], s[44:45], v[26:27] op_sel:[1,0,0]
	v_pk_add_f32 v[26:27], v[4:5], v[20:21]
	v_pk_add_f32 v[4:5], v[4:5], v[20:21] neg_lo:[0,1] neg_hi:[0,1]
	v_pk_mul_f32 v[88:89], v[116:117], v[108:109] op_sel:[1,1] op_sel_hi:[1,0] neg_lo:[0,1]
	v_pk_fma_f32 v[48:49], v[96:97], v[48:49], v[104:105] op_sel_hi:[1,0,1]
	v_xor_b32_e32 v21, 0x80000000, v4
	v_mov_b32_e32 v20, v5
	v_pk_add_f32 v[4:5], v[6:7], v[22:23]
	v_pk_add_f32 v[6:7], v[6:7], v[22:23] neg_lo:[0,1] neg_hi:[0,1]
	v_pk_fma_f32 v[88:89], v[108:109], v[116:117], v[88:89] op_sel_hi:[1,0,1]
	v_pk_mul_f32 v[96:97], v[86:87], v[38:39] op_sel:[1,1] op_sel_hi:[0,1] neg_lo:[1,0]
	v_pk_mul_f32 v[22:23], v[6:7], s[58:59] op_sel_hi:[0,1]
	v_pk_mul_f32 v[90:91], v[116:117], v[110:111] op_sel:[1,1] op_sel_hi:[1,0] neg_lo:[0,1]
	v_pk_fma_f32 v[38:39], v[86:87], v[38:39], v[96:97] op_sel_hi:[1,0,1]
	v_pk_fma_f32 v[6:7], v[6:7], s[42:43], v[22:23] op_sel:[1,0,0]
	s_waitcnt lgkmcnt(0)
	v_pk_add_f32 v[22:23], v[0:1], v[16:17]
	v_pk_add_f32 v[0:1], v[0:1], v[16:17] neg_lo:[0,1] neg_hi:[0,1]
	v_pk_fma_f32 v[90:91], v[110:111], v[116:117], v[90:91] op_sel_hi:[1,0,1]
	v_pk_mul_f32 v[86:87], v[88:89], v[52:53] op_sel:[1,1] op_sel_hi:[0,1] neg_lo:[1,0]
	v_cvt_f32_i32_e32 v83, v140
	v_mul_f32_e32 v16, 0xbf3504f3, v0
	v_pk_mul_f32 v[92:93], v[116:117], v[114:115] op_sel:[1,1] op_sel_hi:[1,0] neg_lo:[0,1]
	v_pk_fma_f32 v[52:53], v[88:89], v[52:53], v[86:87] op_sel_hi:[1,0,1]
	v_pk_fma_f32 v[0:1], v[0:1], s[56:57], v[16:17] op_sel:[1,0,0] op_sel_hi:[1,1,0]
	v_pk_add_f32 v[16:17], v[2:3], v[18:19]
	v_pk_add_f32 v[2:3], v[2:3], v[18:19] neg_lo:[0,1] neg_hi:[0,1]
	v_pk_fma_f32 v[92:93], v[114:115], v[116:117], v[92:93] op_sel_hi:[1,0,1]
	v_pk_mul_f32 v[86:87], v[90:91], v[40:41] op_sel:[1,1] op_sel_hi:[0,1] neg_lo:[1,0]
	v_pk_mul_f32 v[18:19], v[2:3], s[40:41] op_sel_hi:[0,1]
	v_pk_fma_f32 v[40:41], v[90:91], v[40:41], v[86:87] op_sel_hi:[1,0,1]
	v_pk_fma_f32 v[2:3], v[2:3], s[66:67], v[18:19] op_sel:[1,0,0]
	v_pk_add_f32 v[18:19], v[138:139], v[26:27]
	v_pk_add_f32 v[26:27], v[138:139], v[26:27] neg_lo:[0,1] neg_hi:[0,1]
	v_pk_add_f32 v[138:139], v[28:29], v[4:5]
	v_pk_add_f32 v[4:5], v[28:29], v[4:5] neg_lo:[0,1] neg_hi:[0,1]
	v_pk_mul_f32 v[86:87], v[92:93], v[42:43] op_sel:[1,1] op_sel_hi:[0,1] neg_lo:[1,0]
	v_mul_f32_e32 v83, 0x3a000000, v83
	v_mul_f32_e32 v28, 0x3f3504f3, v5
	v_pk_fma_f32 v[42:43], v[92:93], v[42:43], v[86:87] op_sel_hi:[1,0,1]
	v_cos_f32_e32 v86, v83
	v_pk_fma_f32 v[4:5], v[4:5], s[56:57], v[28:29] op_sel_hi:[0,1,0]
	v_pk_add_f32 v[28:29], v[30:31], v[22:23]
	v_pk_add_f32 v[22:23], v[30:31], v[22:23] neg_lo:[0,1] neg_hi:[0,1]
	v_sin_f32_e32 v88, v83
	v_xor_b32_e32 v31, 0x80000000, v22
	v_mov_b32_e32 v30, v23
	v_pk_add_f32 v[22:23], v[24:25], v[16:17]
	v_pk_add_f32 v[16:17], v[24:25], v[16:17] neg_lo:[0,1] neg_hi:[0,1]
	v_mov_b32_e32 v89, v86
	v_mul_f32_e32 v24, 0xbf3504f3, v16
	v_pk_fma_f32 v[16:17], v[16:17], s[56:57], v[24:25] op_sel:[1,0,0] op_sel_hi:[1,1,0]
	v_pk_add_f32 v[24:25], v[12:13], v[20:21]
	v_pk_add_f32 v[12:13], v[12:13], v[20:21] neg_lo:[0,1] neg_hi:[0,1]
	v_pk_add_f32 v[20:21], v[14:15], v[6:7]
	v_pk_add_f32 v[6:7], v[14:15], v[6:7] neg_lo:[0,1] neg_hi:[0,1]
	v_xor_b32_e32 v87, 0x80000000, v88
	v_mul_f32_e32 v14, 0x3f3504f3, v7
	v_pk_mul_f32 v[90:91], v[88:89], v[88:89] op_sel_hi:[1,0] neg_lo:[0,1] neg_hi:[0,1]
	v_pk_fma_f32 v[6:7], v[6:7], s[56:57], v[14:15] op_sel_hi:[0,1,0]
	v_pk_add_f32 v[14:15], v[8:9], v[0:1]
	v_pk_add_f32 v[0:1], v[8:9], v[0:1] neg_lo:[0,1] neg_hi:[0,1]
	v_pk_fma_f32 v[90:91], v[86:87], v[86:87], v[90:91] op_sel_hi:[1,0,1]
	v_xor_b32_e32 v9, 0x80000000, v0
	v_mov_b32_e32 v8, v1
	v_pk_add_f32 v[0:1], v[10:11], v[2:3]
	v_pk_add_f32 v[2:3], v[10:11], v[2:3] neg_lo:[0,1] neg_hi:[0,1]
	v_xor_b32_e32 v96, 0x80000000, v91
	v_mov_b32_e32 v97, v90
	v_mul_f32_e32 v10, 0xbf3504f3, v2
	v_pk_mul_f32 v[32:33], v[102:103], v[130:131] op_sel:[1,1] op_sel_hi:[0,1] neg_lo:[1,0]
	v_pk_mul_f32 v[104:105], v[90:91], v[96:97] op_sel:[1,0]
	v_pk_fma_f32 v[2:3], v[2:3], s[56:57], v[10:11] op_sel:[1,0,0] op_sel_hi:[1,1,0]
	v_pk_add_f32 v[10:11], v[18:19], v[28:29]
	v_pk_add_f32 v[18:19], v[18:19], v[28:29] neg_lo:[0,1] neg_hi:[0,1]
	v_pk_add_f32 v[28:29], v[138:139], v[22:23]
	v_pk_add_f32 v[22:23], v[138:139], v[22:23] neg_lo:[0,1] neg_hi:[0,1]
	v_pk_fma_f32 v[32:33], v[102:103], v[130:131], v[32:33] op_sel_hi:[1,0,1]
	v_pk_mul_f32 v[102:103], v[114:115], v[142:143] op_sel:[1,1] op_sel_hi:[0,1] neg_lo:[1,0]
	v_pk_fma_f32 v[104:105], v[90:91], v[90:91], v[104:105] op_sel_hi:[1,0,1]
	v_xor_b32_e32 v139, 0x80000000, v22
	v_mov_b32_e32 v138, v23
	v_pk_add_f32 v[22:23], v[26:27], v[30:31]
	v_pk_add_f32 v[26:27], v[26:27], v[30:31] neg_lo:[0,1] neg_hi:[0,1]
	v_pk_add_f32 v[30:31], v[4:5], v[16:17]
	v_pk_add_f32 v[4:5], v[4:5], v[16:17] neg_lo:[0,1] neg_hi:[0,1]
	v_pk_fma_f32 v[102:103], v[114:115], v[142:143], v[102:103] op_sel_hi:[1,0,1]
	v_xor_b32_e32 v114, 0x80000000, v105
	v_mov_b32_e32 v115, v104
	v_xor_b32_e32 v17, 0x80000000, v4
	v_mov_b32_e32 v16, v5
	v_pk_add_f32 v[4:5], v[24:25], v[14:15]
	v_pk_add_f32 v[14:15], v[24:25], v[14:15] neg_lo:[0,1] neg_hi:[0,1]
	v_pk_add_f32 v[24:25], v[20:21], v[0:1]
	v_pk_add_f32 v[0:1], v[20:21], v[0:1] neg_lo:[0,1] neg_hi:[0,1]
	v_pk_mul_f32 v[92:93], v[88:89], v[90:91] op_sel:[0,1]
	v_pk_mul_f32 v[116:117], v[104:105], v[114:115] op_sel:[1,0]
	v_xor_b32_e32 v21, 0x80000000, v0
	v_mov_b32_e32 v20, v1
	v_pk_add_f32 v[0:1], v[12:13], v[8:9]
	v_pk_add_f32 v[8:9], v[12:13], v[8:9] neg_lo:[0,1] neg_hi:[0,1]
	v_pk_add_f32 v[12:13], v[6:7], v[2:3]
	v_pk_add_f32 v[2:3], v[6:7], v[2:3] neg_lo:[0,1] neg_hi:[0,1]
	v_pk_fma_f32 v[92:93], v[86:87], v[90:91], v[92:93] op_sel_hi:[1,0,1]
	v_pk_fma_f32 v[116:117], v[104:105], v[104:105], v[116:117] op_sel_hi:[1,0,1]
	v_xor_b32_e32 v7, 0x80000000, v2
	v_mov_b32_e32 v6, v3
	v_pk_add_f32 v[2:3], v[10:11], v[28:29]
	v_pk_add_f32 v[10:11], v[10:11], v[28:29] neg_lo:[0,1] neg_hi:[0,1]
	v_pk_add_f32 v[28:29], v[18:19], v[138:139]
	v_pk_add_f32 v[18:19], v[18:19], v[138:139] neg_lo:[0,1] neg_hi:[0,1]
	v_pk_add_f32 v[138:139], v[22:23], v[30:31]
	v_pk_add_f32 v[22:23], v[22:23], v[30:31] neg_lo:[0,1] neg_hi:[0,1]
	v_pk_add_f32 v[30:31], v[26:27], v[16:17]
	v_pk_add_f32 v[16:17], v[26:27], v[16:17] neg_lo:[0,1] neg_hi:[0,1]
	v_pk_add_f32 v[26:27], v[4:5], v[24:25]
	v_pk_mul_f32 v[98:99], v[108:109], v[136:137] op_sel:[1,1] op_sel_hi:[0,1] neg_lo:[1,0]
	v_pk_mul_f32 v[106:107], v[88:89], v[104:105] op_sel:[0,1]
	v_xor_b32_e32 v110, 0x80000000, v93
	v_mov_b32_e32 v111, v92
	v_pk_mul_f32 v[118:119], v[88:89], v[116:117] op_sel:[0,1]
	v_pk_add_f32 v[4:5], v[4:5], v[24:25] neg_lo:[0,1] neg_hi:[0,1]
	v_pk_add_f32 v[24:25], v[14:15], v[20:21]
	v_pk_add_f32 v[14:15], v[14:15], v[20:21] neg_lo:[0,1] neg_hi:[0,1]
	v_pk_add_f32 v[20:21], v[0:1], v[12:13]
	v_pk_add_f32 v[0:1], v[0:1], v[12:13] neg_lo:[0,1] neg_hi:[0,1]
	v_pk_add_f32 v[12:13], v[8:9], v[6:7]
	v_pk_add_f32 v[6:7], v[8:9], v[6:7] neg_lo:[0,1] neg_hi:[0,1]
	v_pk_mul_f32 v[8:9], v[88:89], v[26:27] op_sel:[0,1]
	v_pk_fma_f32 v[98:99], v[108:109], v[136:137], v[98:99] op_sel_hi:[1,0,1]
	v_pk_fma_f32 v[106:107], v[86:87], v[104:105], v[106:107] op_sel_hi:[1,0,1]
	v_pk_mul_f32 v[108:109], v[96:97], v[104:105] op_sel:[0,1]
	v_pk_fma_f32 v[118:119], v[86:87], v[116:117], v[118:119] op_sel_hi:[1,0,1]
	v_pk_fma_f32 v[8:9], v[86:87], v[26:27], v[8:9] op_sel_hi:[1,0,1]
	v_pk_mul_f32 v[86:87], v[110:111], v[20:21] op_sel:[0,1]
	v_pk_fma_f32 v[108:109], v[90:91], v[104:105], v[108:109] op_sel_hi:[1,0,1]
	v_pk_mul_f32 v[112:113], v[104:105], v[110:111] op_sel:[1,0]
	v_xor_b32_e32 v126, 0x80000000, v107
	v_mov_b32_e32 v127, v106
	v_pk_fma_f32 v[20:21], v[92:93], v[20:21], v[86:87] op_sel_hi:[1,0,1]
	v_pk_mul_f32 v[86:87], v[114:115], v[28:29] op_sel:[0,1]
	v_pk_fma_f32 v[112:113], v[92:93], v[104:105], v[112:113] op_sel_hi:[1,0,1]
	v_xor_b32_e32 v130, 0x80000000, v109
	v_mov_b32_e32 v131, v108
	v_pk_fma_f32 v[28:29], v[104:105], v[28:29], v[86:87] op_sel_hi:[1,0,1]
	v_pk_mul_f32 v[86:87], v[126:127], v[24:25] op_sel:[0,1]
	v_xor_b32_e32 v134, 0x80000000, v113
	v_mov_b32_e32 v135, v112
	v_pk_fma_f32 v[24:25], v[106:107], v[24:25], v[86:87] op_sel_hi:[1,0,1]
	v_pk_mul_f32 v[86:87], v[130:131], v[30:31] op_sel:[0,1]
	v_pk_mul_f32 v[120:121], v[96:97], v[116:117] op_sel:[0,1]
	v_pk_fma_f32 v[30:31], v[108:109], v[30:31], v[86:87] op_sel_hi:[1,0,1]
	v_pk_mul_f32 v[86:87], v[134:135], v[12:13] op_sel:[0,1]
	v_pk_fma_f32 v[120:121], v[90:91], v[116:117], v[120:121] op_sel_hi:[1,0,1]
	v_pk_fma_f32 v[12:13], v[112:113], v[12:13], v[86:87] op_sel_hi:[1,0,1]
	v_pk_mul_f32 v[86:87], v[116:117], v[10:11] op_sel:[1,1] op_sel_hi:[0,1] neg_lo:[1,0]
	v_pk_mul_f32 v[122:123], v[110:111], v[116:117] op_sel:[0,1]
	v_pk_fma_f32 v[10:11], v[116:117], v[10:11], v[86:87] op_sel_hi:[1,0,1]
	v_pk_mul_f32 v[86:87], v[118:119], v[4:5] op_sel:[1,1] op_sel_hi:[0,1] neg_lo:[1,0]
	v_pk_fma_f32 v[122:123], v[92:93], v[116:117], v[122:123] op_sel_hi:[1,0,1]
	v_pk_fma_f32 v[4:5], v[118:119], v[4:5], v[86:87] op_sel_hi:[1,0,1]
	v_pk_mul_f32 v[86:87], v[120:121], v[22:23] op_sel:[1,1] op_sel_hi:[0,1] neg_lo:[1,0]
	v_pk_mul_f32 v[124:125], v[114:115], v[116:117] op_sel:[0,1]
	v_pk_fma_f32 v[22:23], v[120:121], v[22:23], v[86:87] op_sel_hi:[1,0,1]
	v_pk_fma_f32 v[124:125], v[104:105], v[116:117], v[124:125] op_sel_hi:[1,0,1]
	v_pk_mul_f32 v[86:87], v[122:123], v[0:1] op_sel:[1,1] op_sel_hi:[0,1] neg_lo:[1,0]
	v_pk_mul_f32 v[128:129], v[116:117], v[126:127] op_sel:[1,0]
	v_pk_fma_f32 v[0:1], v[122:123], v[0:1], v[86:87] op_sel_hi:[1,0,1]
	v_pk_fma_f32 v[128:129], v[106:107], v[116:117], v[128:129] op_sel_hi:[1,0,1]
	v_pk_mul_f32 v[86:87], v[124:125], v[18:19] op_sel:[1,1] op_sel_hi:[0,1] neg_lo:[1,0]
	v_pk_mul_f32 v[132:133], v[116:117], v[130:131] op_sel:[1,0]
	v_pk_fma_f32 v[18:19], v[124:125], v[18:19], v[86:87] op_sel_hi:[1,0,1]
	v_pk_fma_f32 v[132:133], v[108:109], v[116:117], v[132:133] op_sel_hi:[1,0,1]
	v_pk_mul_f32 v[86:87], v[128:129], v[14:15] op_sel:[1,1] op_sel_hi:[0,1] neg_lo:[1,0]
	v_pk_mul_f32 v[136:137], v[116:117], v[134:135] op_sel:[1,0]
	v_pk_fma_f32 v[14:15], v[128:129], v[14:15], v[86:87] op_sel_hi:[1,0,1]
	v_pk_fma_f32 v[136:137], v[112:113], v[116:117], v[136:137] op_sel_hi:[1,0,1]
	v_pk_mul_f32 v[86:87], v[132:133], v[16:17] op_sel:[1,1] op_sel_hi:[0,1] neg_lo:[1,0]
	v_cmp_lt_i32_e32 vcc, -1, v66
	v_pk_fma_f32 v[16:17], v[132:133], v[16:17], v[86:87] op_sel_hi:[1,0,1]
	v_pk_mul_f32 v[26:27], v[96:97], v[138:139] op_sel:[0,1]
	v_pk_mul_f32 v[86:87], v[136:137], v[6:7] op_sel:[1,1] op_sel_hi:[0,1] neg_lo:[1,0]
	v_add_u32_e32 v66, 0x400, v66
	s_or_b64 s[88:89], vcc, s[88:89]
	v_pk_fma_f32 v[26:27], v[90:91], v[138:139], v[26:27] op_sel_hi:[1,0,1]
	v_pk_fma_f32 v[6:7], v[136:137], v[6:7], v[86:87] op_sel_hi:[1,0,1]
	ds_write_b64 v82, v[34:35]
	ds_write_b64 v84, v[2:3]
	ds_write_b64 v82, v[50:51] offset:8256
	ds_write_b64 v84, v[10:11] offset:8256
	ds_write_b64 v82, v[94:95] offset:4128
	ds_write_b64 v84, v[28:29] offset:4128
	ds_write_b64 v82, v[38:39] offset:12384
	ds_write_b64 v84, v[18:19] offset:12384
	ds_write_b64 v82, v[54:55] offset:2064
	ds_write_b64 v84, v[26:27] offset:2064
	ds_write_b64 v82, v[46:47] offset:10320
	ds_write_b64 v84, v[22:23] offset:10320
	ds_write_b64 v82, v[100:101] offset:6192
	ds_write_b64 v84, v[30:31] offset:6192
	ds_write_b64 v82, v[40:41] offset:14448
	ds_write_b64 v84, v[16:17] offset:14448
	ds_write_b64 v82, v[44:45] offset:1032
	ds_write_b64 v84, v[8:9] offset:1032
	ds_write_b64 v82, v[36:37] offset:9288
	ds_write_b64 v84, v[4:5] offset:9288
	ds_write_b64 v82, v[98:99] offset:5160
	ds_write_b64 v84, v[24:25] offset:5160
	ds_write_b64 v82, v[52:53] offset:13416
	ds_write_b64 v84, v[14:15] offset:13416
	ds_write_b64 v82, v[32:33] offset:3096
	ds_write_b64 v84, v[20:21] offset:3096
	ds_write_b64 v82, v[48:49] offset:11352
	ds_write_b64 v84, v[0:1] offset:11352
	ds_write_b64 v82, v[102:103] offset:7224
	ds_write_b64 v84, v[12:13] offset:7224
	ds_write_b64 v82, v[42:43] offset:15480
	ds_write_b64 v84, v[6:7] offset:15480
	s_andn2_b64 exec, exec, s[88:89]
	s_cbranch_execnz .LBB0_291

.LBB0_294:
	v_ashrrev_i32_e32 v1, 7, v0
	v_mov_b32_e32 v34, v1
	v_add_u32_e32 v2, 0x200, v0
	v_cvt_f32_i32_e32 v34, v34
	v_ashrrev_i32_e32 v2, 7, v2
	v_mov_b32_e32 v66, v2
	v_lshl_add_u32 v1, v1, 3, v196
	v_mul_f32_e32 v35, 0x3c000000, v34
	v_lshl_add_u32 v82, v2, 3, v196
	ds_read_b64 v[2:3], v1
	ds_read_b64 v[4:5], v1 offset:128
	ds_read_b64 v[6:7], v82
	ds_read_b64 v[8:9], v82 offset:128
	ds_read_b64 v[10:11], v1 offset:256
	ds_read_b64 v[12:13], v1 offset:384
	ds_read_b64 v[14:15], v82 offset:256
	ds_read_b64 v[16:17], v82 offset:384
	ds_read_b64 v[18:19], v1 offset:512
	ds_read_b64 v[20:21], v1 offset:640
	ds_read_b64 v[22:23], v82 offset:512
	ds_read_b64 v[24:25], v82 offset:640
	ds_read_b64 v[26:27], v1 offset:768
	ds_read_b64 v[28:29], v1 offset:896
	ds_read_b64 v[30:31], v82 offset:768
	ds_read_b64 v[32:33], v82 offset:896
	v_cos_f32_e32 v34, v35
	v_sin_f32_e32 v36, v35
	s_waitcnt lgkmcnt(6)
	v_pk_add_f32 v[54:55], v[2:3], v[18:19]
	v_pk_add_f32 v[2:3], v[2:3], v[18:19] neg_lo:[0,1] neg_hi:[0,1]
	v_pk_add_f32 v[18:19], v[4:5], v[20:21]
	v_pk_add_f32 v[4:5], v[4:5], v[20:21] neg_lo:[0,1] neg_hi:[0,1]
	v_mov_b32_e32 v37, v34
	v_mul_f32_e32 v20, 0x3f3504f3, v5
	v_pk_fma_f32 v[4:5], v[4:5], s[56:57], v[20:21] op_sel_hi:[0,1,0]
	s_waitcnt lgkmcnt(2)
	v_pk_add_f32 v[20:21], v[10:11], v[26:27]
	v_pk_add_f32 v[10:11], v[10:11], v[26:27] neg_lo:[0,1] neg_hi:[0,1]
	v_xor_b32_e32 v35, 0x80000000, v36
	v_pk_mul_f32 v[38:39], v[36:37], v[36:37] op_sel_hi:[1,0] neg_lo:[0,1] neg_hi:[0,1]
	v_xor_b32_e32 v27, 0x80000000, v10
	v_mov_b32_e32 v26, v11
	v_pk_add_f32 v[10:11], v[12:13], v[28:29]
	v_pk_add_f32 v[12:13], v[12:13], v[28:29] neg_lo:[0,1] neg_hi:[0,1]
	v_pk_fma_f32 v[38:39], v[34:35], v[34:35], v[38:39] op_sel_hi:[1,0,1]
	v_mul_f32_e32 v28, 0xbf3504f3, v12
	v_pk_fma_f32 v[12:13], v[12:13], s[56:57], v[28:29] op_sel:[1,0,0] op_sel_hi:[1,1,0]
	v_pk_add_f32 v[28:29], v[54:55], v[20:21]
	v_pk_add_f32 v[20:21], v[54:55], v[20:21] neg_lo:[0,1] neg_hi:[0,1]
	v_pk_add_f32 v[54:55], v[18:19], v[10:11]
	v_pk_add_f32 v[10:11], v[18:19], v[10:11] neg_lo:[0,1] neg_hi:[0,1]
	v_pk_mul_f32 v[40:41], v[36:37], v[38:39] op_sel:[0,1]
	v_pk_mul_f32 v[44:45], v[38:39], v[38:39] op_sel:[1,1] op_sel_hi:[1,0] neg_lo:[0,1]
	v_xor_b32_e32 v19, 0x80000000, v10
	v_mov_b32_e32 v18, v11
	v_pk_add_f32 v[10:11], v[2:3], v[26:27]
	v_pk_add_f32 v[2:3], v[2:3], v[26:27] neg_lo:[0,1] neg_hi:[0,1]
	v_pk_add_f32 v[26:27], v[4:5], v[12:13]
	v_pk_add_f32 v[4:5], v[4:5], v[12:13] neg_lo:[0,1] neg_hi:[0,1]
	v_pk_fma_f32 v[40:41], v[34:35], v[38:39], v[40:41] op_sel_hi:[1,0,1]
	v_pk_fma_f32 v[44:45], v[38:39], v[38:39], v[44:45] op_sel_hi:[1,0,1]
	v_xor_b32_e32 v13, 0x80000000, v4
	v_mov_b32_e32 v12, v5
	v_pk_add_f32 v[4:5], v[28:29], v[54:55]
	v_pk_add_f32 v[28:29], v[28:29], v[54:55] neg_lo:[0,1] neg_hi:[0,1]
	v_pk_add_f32 v[54:55], v[20:21], v[18:19]
	v_pk_add_f32 v[18:19], v[20:21], v[18:19] neg_lo:[0,1] neg_hi:[0,1]
	v_pk_add_f32 v[20:21], v[10:11], v[26:27]
	v_pk_mul_f32 v[46:47], v[36:37], v[44:45] op_sel:[0,1]
	v_pk_add_f32 v[10:11], v[10:11], v[26:27] neg_lo:[0,1] neg_hi:[0,1]
	v_pk_add_f32 v[26:27], v[2:3], v[12:13]
	v_pk_add_f32 v[2:3], v[2:3], v[12:13] neg_lo:[0,1] neg_hi:[0,1]
	v_pk_mul_f32 v[12:13], v[36:37], v[20:21] op_sel:[0,1]
	v_pk_fma_f32 v[46:47], v[34:35], v[44:45], v[46:47] op_sel_hi:[1,0,1]
	v_pk_fma_f32 v[12:13], v[34:35], v[20:21], v[12:13] op_sel_hi:[1,0,1]
	v_pk_mul_f32 v[34:35], v[40:41], v[26:27] op_sel:[1,1] op_sel_hi:[0,1] neg_lo:[1,0]
	v_pk_mul_f32 v[48:49], v[38:39], v[44:45] op_sel:[1,1] op_sel_hi:[0,1] neg_lo:[1,0]
	v_pk_fma_f32 v[26:27], v[40:41], v[26:27], v[34:35] op_sel_hi:[1,0,1]
	v_pk_mul_f32 v[34:35], v[44:45], v[28:29] op_sel:[1,1] op_sel_hi:[0,1] neg_lo:[1,0]
	v_pk_fma_f32 v[48:49], v[38:39], v[44:45], v[48:49] op_sel_hi:[1,0,1]
	v_pk_fma_f32 v[28:29], v[44:45], v[28:29], v[34:35] op_sel_hi:[1,0,1]
	v_pk_mul_f32 v[34:35], v[46:47], v[10:11] op_sel:[1,1] op_sel_hi:[0,1] neg_lo:[1,0]
	v_pk_mul_f32 v[52:53], v[44:45], v[40:41] op_sel:[1,1] op_sel_hi:[1,0] neg_lo:[0,1]
	v_pk_fma_f32 v[10:11], v[46:47], v[10:11], v[34:35] op_sel_hi:[1,0,1]
	v_pk_fma_f32 v[52:53], v[40:41], v[44:45], v[52:53] op_sel_hi:[1,0,1]
	v_pk_mul_f32 v[34:35], v[48:49], v[18:19] op_sel:[1,1] op_sel_hi:[0,1] neg_lo:[1,0]
	v_pk_mul_f32 v[20:21], v[38:39], v[54:55] op_sel:[1,1] op_sel_hi:[0,1] neg_lo:[1,0]
	v_pk_fma_f32 v[18:19], v[48:49], v[18:19], v[34:35] op_sel_hi:[1,0,1]
	v_pk_mul_f32 v[34:35], v[52:53], v[2:3] op_sel:[1,1] op_sel_hi:[0,1] neg_lo:[1,0]
	v_pk_fma_f32 v[20:21], v[38:39], v[54:55], v[20:21] op_sel_hi:[1,0,1]
	v_pk_fma_f32 v[2:3], v[52:53], v[2:3], v[34:35] op_sel_hi:[1,0,1]
	v_cvt_f32_i32_e32 v34, v66
	v_pk_add_f32 v[54:55], v[6:7], v[22:23]
	v_pk_add_f32 v[6:7], v[6:7], v[22:23] neg_lo:[0,1] neg_hi:[0,1]
	v_pk_add_f32 v[22:23], v[8:9], v[24:25]
	v_mul_f32_e32 v35, 0x3c000000, v34
	v_cos_f32_e32 v34, v35
	v_sin_f32_e32 v36, v35
	v_pk_add_f32 v[8:9], v[8:9], v[24:25] neg_lo:[0,1] neg_hi:[0,1]
	v_cmp_lt_i32_e32 vcc, s28, v0
	v_mul_f32_e32 v24, 0x3f3504f3, v9
	v_mov_b32_e32 v37, v34
	v_pk_fma_f32 v[8:9], v[8:9], s[56:57], v[24:25] op_sel_hi:[0,1,0]
	s_waitcnt lgkmcnt(0)
	v_pk_add_f32 v[24:25], v[14:15], v[30:31]
	v_pk_add_f32 v[14:15], v[14:15], v[30:31] neg_lo:[0,1] neg_hi:[0,1]
	v_xor_b32_e32 v35, 0x80000000, v36
	v_pk_mul_f32 v[38:39], v[36:37], v[36:37] op_sel_hi:[1,0] neg_lo:[0,1] neg_hi:[0,1]
	v_xor_b32_e32 v31, 0x80000000, v14
	v_mov_b32_e32 v30, v15
	v_pk_add_f32 v[14:15], v[16:17], v[32:33]
	v_pk_add_f32 v[16:17], v[16:17], v[32:33] neg_lo:[0,1] neg_hi:[0,1]
	v_pk_fma_f32 v[38:39], v[34:35], v[34:35], v[38:39] op_sel_hi:[1,0,1]
	v_mul_f32_e32 v32, 0xbf3504f3, v16
	v_xor_b32_e32 v42, 0x80000000, v39
	v_mov_b32_e32 v43, v38
	v_pk_fma_f32 v[16:17], v[16:17], s[56:57], v[32:33] op_sel:[1,0,0] op_sel_hi:[1,1,0]
	v_pk_add_f32 v[32:33], v[54:55], v[24:25]
	v_pk_add_f32 v[24:25], v[54:55], v[24:25] neg_lo:[0,1] neg_hi:[0,1]
	v_pk_add_f32 v[54:55], v[22:23], v[14:15]
	v_pk_add_f32 v[14:15], v[22:23], v[14:15] neg_lo:[0,1] neg_hi:[0,1]
	v_pk_mul_f32 v[40:41], v[36:37], v[38:39] op_sel:[0,1]
	v_pk_mul_f32 v[44:45], v[38:39], v[42:43] op_sel:[1,0]
	v_xor_b32_e32 v23, 0x80000000, v14
	v_mov_b32_e32 v22, v15
	v_pk_add_f32 v[14:15], v[6:7], v[30:31]
	v_pk_add_f32 v[6:7], v[6:7], v[30:31] neg_lo:[0,1] neg_hi:[0,1]
	v_pk_add_f32 v[30:31], v[8:9], v[16:17]
	v_pk_add_f32 v[8:9], v[8:9], v[16:17] neg_lo:[0,1] neg_hi:[0,1]
	v_pk_fma_f32 v[40:41], v[34:35], v[38:39], v[40:41] op_sel_hi:[1,0,1]
	v_pk_fma_f32 v[44:45], v[38:39], v[38:39], v[44:45] op_sel_hi:[1,0,1]
	v_xor_b32_e32 v17, 0x80000000, v8
	v_mov_b32_e32 v16, v9
	v_pk_add_f32 v[8:9], v[32:33], v[54:55]
	v_pk_add_f32 v[32:33], v[32:33], v[54:55] neg_lo:[0,1] neg_hi:[0,1]
	v_pk_add_f32 v[54:55], v[24:25], v[22:23]
	v_pk_add_f32 v[22:23], v[24:25], v[22:23] neg_lo:[0,1] neg_hi:[0,1]
	v_pk_add_f32 v[24:25], v[14:15], v[30:31]
	v_pk_mul_f32 v[46:47], v[36:37], v[44:45] op_sel:[0,1]
	v_xor_b32_e32 v50, 0x80000000, v41
	v_mov_b32_e32 v51, v40
	v_pk_add_f32 v[14:15], v[14:15], v[30:31] neg_lo:[0,1] neg_hi:[0,1]
	v_pk_add_f32 v[30:31], v[6:7], v[16:17]
	v_pk_add_f32 v[6:7], v[6:7], v[16:17] neg_lo:[0,1] neg_hi:[0,1]
	v_pk_mul_f32 v[16:17], v[36:37], v[24:25] op_sel:[0,1]
	v_pk_fma_f32 v[46:47], v[34:35], v[44:45], v[46:47] op_sel_hi:[1,0,1]
	v_pk_fma_f32 v[16:17], v[34:35], v[24:25], v[16:17] op_sel_hi:[1,0,1]
	v_pk_mul_f32 v[34:35], v[50:51], v[30:31] op_sel:[0,1]
	v_pk_mul_f32 v[48:49], v[42:43], v[44:45] op_sel:[0,1]
	v_pk_fma_f32 v[30:31], v[40:41], v[30:31], v[34:35] op_sel_hi:[1,0,1]
	v_pk_mul_f32 v[34:35], v[44:45], v[32:33] op_sel:[1,1] op_sel_hi:[0,1] neg_lo:[1,0]
	v_pk_fma_f32 v[48:49], v[38:39], v[44:45], v[48:49] op_sel_hi:[1,0,1]
	v_pk_fma_f32 v[32:33], v[44:45], v[32:33], v[34:35] op_sel_hi:[1,0,1]
	v_pk_mul_f32 v[34:35], v[46:47], v[14:15] op_sel:[1,1] op_sel_hi:[0,1] neg_lo:[1,0]
	v_pk_mul_f32 v[52:53], v[44:45], v[50:51] op_sel:[1,0]
	v_pk_fma_f32 v[14:15], v[46:47], v[14:15], v[34:35] op_sel_hi:[1,0,1]
	v_pk_fma_f32 v[52:53], v[40:41], v[44:45], v[52:53] op_sel_hi:[1,0,1]
	v_pk_mul_f32 v[34:35], v[48:49], v[22:23] op_sel:[1,1] op_sel_hi:[0,1] neg_lo:[1,0]
	v_pk_mul_f32 v[24:25], v[42:43], v[54:55] op_sel:[0,1]
	v_pk_fma_f32 v[22:23], v[48:49], v[22:23], v[34:35] op_sel_hi:[1,0,1]
	v_pk_mul_f32 v[34:35], v[52:53], v[6:7] op_sel:[1,1] op_sel_hi:[0,1] neg_lo:[1,0]
	v_add_u32_e32 v0, 0x400, v0
	s_or_b64 s[88:89], vcc, s[88:89]
	v_pk_fma_f32 v[24:25], v[38:39], v[54:55], v[24:25] op_sel_hi:[1,0,1]
	v_pk_fma_f32 v[6:7], v[52:53], v[6:7], v[34:35] op_sel_hi:[1,0,1]
	ds_write_b64 v1, v[4:5]
	ds_write_b64 v82, v[8:9]
	ds_write_b64 v1, v[28:29] offset:512
	ds_write_b64 v82, v[32:33] offset:512
	ds_write_b64 v1, v[20:21] offset:256
	ds_write_b64 v82, v[24:25] offset:256
	ds_write_b64 v1, v[18:19] offset:768
	ds_write_b64 v82, v[22:23] offset:768
	ds_write_b64 v1, v[12:13] offset:128
	ds_write_b64 v82, v[16:17] offset:128
	ds_write_b64 v1, v[10:11] offset:640
	ds_write_b64 v82, v[14:15] offset:640
	ds_write_b64 v1, v[26:27] offset:384
	ds_write_b64 v82, v[30:31] offset:384
	ds_write_b64 v1, v[2:3] offset:896
	ds_write_b64 v82, v[6:7] offset:896
	s_andn2_b64 exec, exec, s[88:89]
	s_cbranch_execnz .LBB0_294

.LBB0_297:
	v_add_u32_e32 v0, 0x200, v38
	v_and_b32_e32 v1, 0xffffff80, v38
	v_add_u32_e32 v39, v196, v1
	v_and_b32_e32 v0, 0xffffff80, v0
	v_add_u32_e32 v98, v196, v0
	ds_read_b64 v[40:41], v39
	ds_read_b64 v[42:43], v39 offset:8
	ds_read_b64 v[20:21], v98
	ds_read_b64 v[22:23], v98 offset:8
	ds_read_b64 v[44:45], v39 offset:16
	ds_read_b64 v[46:47], v39 offset:24
	ds_read_b64 v[12:13], v98 offset:16
	ds_read_b64 v[14:15], v98 offset:24
	ds_read_b64 v[48:49], v39 offset:32
	ds_read_b64 v[50:51], v39 offset:40
	ds_read_b64 v[4:5], v98 offset:32
	ds_read_b64 v[6:7], v98 offset:40
	ds_read_b64 v[52:53], v39 offset:48
	ds_read_b64 v[54:55], v39 offset:56
	ds_read_b64 v[0:1], v98 offset:48
	ds_read_b64 v[2:3], v98 offset:56
	ds_read_b64 v[82:83], v39 offset:64
	ds_read_b64 v[84:85], v39 offset:72
	ds_read_b64 v[28:29], v98 offset:64
	ds_read_b64 v[30:31], v98 offset:72
	ds_read_b64 v[86:87], v39 offset:80
	ds_read_b64 v[88:89], v39 offset:88
	ds_read_b64 v[24:25], v98 offset:80
	ds_read_b64 v[26:27], v98 offset:88
	ds_read_b64 v[90:91], v39 offset:96
	ds_read_b64 v[92:93], v39 offset:104
	ds_read_b64 v[16:17], v98 offset:96
	ds_read_b64 v[18:19], v98 offset:104
	ds_read_b64 v[94:95], v39 offset:112
	ds_read_b64 v[96:97], v39 offset:120
	ds_read_b64 v[8:9], v98 offset:112
	ds_read_b64 v[10:11], v98 offset:120
	s_waitcnt lgkmcnt(14)
	v_pk_add_f32 v[34:35], v[40:41], v[82:83]
	v_pk_add_f32 v[32:33], v[40:41], v[82:83] neg_lo:[0,1] neg_hi:[0,1]
	s_waitcnt lgkmcnt(10)
	v_pk_add_f32 v[82:83], v[46:47], v[88:89]
	v_pk_add_f32 v[46:47], v[46:47], v[88:89] neg_lo:[0,1] neg_hi:[0,1]
	s_mov_b32 s66, s64
	v_pk_add_f32 v[36:37], v[42:43], v[84:85]
	v_pk_add_f32 v[40:41], v[42:43], v[84:85] neg_lo:[0,1] neg_hi:[0,1]
	v_pk_mul_f32 v[84:85], v[46:47], s[66:67] op_sel_hi:[0,1]
	s_mov_b32 s40, s42
	s_mov_b32 s41, s64
	v_pk_mul_f32 v[42:43], v[40:41], s[42:43] op_sel_hi:[0,1]
	s_mov_b32 s65, s42
	v_pk_fma_f32 v[46:47], v[46:47], s[40:41], v[84:85] op_sel:[1,0,0]
	s_waitcnt lgkmcnt(6)
	v_pk_add_f32 v[84:85], v[48:49], v[90:91]
	v_pk_add_f32 v[48:49], v[48:49], v[90:91] neg_lo:[0,1] neg_hi:[0,1]
	s_waitcnt lgkmcnt(2)
	v_pk_add_f32 v[90:91], v[54:55], v[96:97]
	v_pk_add_f32 v[54:55], v[54:55], v[96:97] neg_lo:[0,1] neg_hi:[0,1]
	s_mov_b32 s58, s67
	s_mov_b32 s59, s43
	v_pk_fma_f32 v[40:41], v[40:41], s[64:65], v[42:43] op_sel:[1,0,0]
	v_pk_add_f32 v[42:43], v[44:45], v[86:87]
	v_pk_add_f32 v[44:45], v[44:45], v[86:87] neg_lo:[0,1] neg_hi:[0,1]
	v_xor_b32_e32 v87, 0x80000000, v48
	v_mov_b32_e32 v86, v49
	v_pk_add_f32 v[48:49], v[50:51], v[92:93]
	v_pk_add_f32 v[50:51], v[50:51], v[92:93] neg_lo:[0,1] neg_hi:[0,1]
	s_mov_b32 s44, s43
	s_mov_b32 s45, s67
	v_pk_mul_f32 v[92:93], v[54:55], s[58:59] op_sel_hi:[0,1]
	v_pk_mul_f32 v[88:89], v[50:51], s[44:45] op_sel_hi:[0,1]
	v_pk_fma_f32 v[54:55], v[54:55], s[66:67], v[92:93] op_sel:[1,0,0]
	v_pk_add_f32 v[92:93], v[34:35], v[84:85]
	v_pk_add_f32 v[34:35], v[34:35], v[84:85] neg_lo:[0,1] neg_hi:[0,1]
	v_pk_add_f32 v[84:85], v[36:37], v[48:49]
	v_pk_add_f32 v[36:37], v[36:37], v[48:49] neg_lo:[0,1] neg_hi:[0,1]
	v_pk_fma_f32 v[50:51], v[50:51], s[42:43], v[88:89] op_sel:[1,0,0]
	v_pk_add_f32 v[88:89], v[52:53], v[94:95]
	v_mul_f32_e32 v48, 0x3f3504f3, v37
	v_mul_f32_e32 v66, 0x3f3504f3, v45
	v_pk_add_f32 v[52:53], v[52:53], v[94:95] neg_lo:[0,1] neg_hi:[0,1]
	v_pk_fma_f32 v[36:37], v[36:37], s[56:57], v[48:49] op_sel_hi:[0,1,0]
	v_pk_add_f32 v[48:49], v[42:43], v[88:89]
	v_pk_add_f32 v[42:43], v[42:43], v[88:89] neg_lo:[0,1] neg_hi:[0,1]
	v_pk_fma_f32 v[44:45], v[44:45], s[56:57], v[66:67] op_sel_hi:[0,1,0]
	v_mul_f32_e32 v66, 0xbf3504f3, v52
	v_xor_b32_e32 v89, 0x80000000, v42
	v_mov_b32_e32 v88, v43
	v_pk_add_f32 v[42:43], v[82:83], v[90:91]
	v_pk_add_f32 v[82:83], v[82:83], v[90:91] neg_lo:[0,1] neg_hi:[0,1]
	v_pk_add_f32 v[90:91], v[32:33], v[86:87]
	v_pk_add_f32 v[32:33], v[32:33], v[86:87] neg_lo:[0,1] neg_hi:[0,1]
	v_pk_add_f32 v[86:87], v[40:41], v[50:51]
	v_pk_add_f32 v[40:41], v[40:41], v[50:51] neg_lo:[0,1] neg_hi:[0,1]
	v_pk_fma_f32 v[52:53], v[52:53], s[56:57], v[66:67] op_sel:[1,0,0] op_sel_hi:[1,1,0]
	v_mul_f32_e32 v50, 0x3f3504f3, v41
	v_pk_fma_f32 v[40:41], v[40:41], s[56:57], v[50:51] op_sel_hi:[0,1,0]
	v_pk_add_f32 v[50:51], v[44:45], v[52:53]
	v_pk_add_f32 v[44:45], v[44:45], v[52:53] neg_lo:[0,1] neg_hi:[0,1]
	v_mul_f32_e32 v66, 0xbf3504f3, v82
	v_xor_b32_e32 v53, 0x80000000, v44
	v_mov_b32_e32 v52, v45
	v_pk_add_f32 v[44:45], v[46:47], v[54:55]
	v_pk_add_f32 v[46:47], v[46:47], v[54:55] neg_lo:[0,1] neg_hi:[0,1]
	v_pk_fma_f32 v[82:83], v[82:83], s[56:57], v[66:67] op_sel:[1,0,0] op_sel_hi:[1,1,0]
	v_mul_f32_e32 v54, 0xbf3504f3, v46
	v_pk_fma_f32 v[46:47], v[46:47], s[56:57], v[54:55] op_sel:[1,0,0] op_sel_hi:[1,1,0]
	v_pk_add_f32 v[54:55], v[92:93], v[48:49]
	v_pk_add_f32 v[48:49], v[92:93], v[48:49] neg_lo:[0,1] neg_hi:[0,1]
	v_pk_add_f32 v[92:93], v[84:85], v[42:43]
	v_pk_add_f32 v[42:43], v[84:85], v[42:43] neg_lo:[0,1] neg_hi:[0,1]
	v_cmp_lt_i32_e32 vcc, -1, v38
	v_xor_b32_e32 v85, 0x80000000, v42
	v_mov_b32_e32 v84, v43
	v_pk_add_f32 v[42:43], v[34:35], v[88:89]
	v_pk_add_f32 v[34:35], v[34:35], v[88:89] neg_lo:[0,1] neg_hi:[0,1]
	v_pk_add_f32 v[88:89], v[36:37], v[82:83]
	v_pk_add_f32 v[36:37], v[36:37], v[82:83] neg_lo:[0,1] neg_hi:[0,1]
	v_add_u32_e32 v38, 0x400, v38
	v_xor_b32_e32 v83, 0x80000000, v36
	v_mov_b32_e32 v82, v37
	v_pk_add_f32 v[36:37], v[90:91], v[50:51]
	v_pk_add_f32 v[50:51], v[90:91], v[50:51] neg_lo:[0,1] neg_hi:[0,1]
	v_pk_add_f32 v[90:91], v[86:87], v[44:45]
	v_pk_add_f32 v[44:45], v[86:87], v[44:45] neg_lo:[0,1] neg_hi:[0,1]
	s_or_b64 s[88:89], vcc, s[88:89]
	v_xor_b32_e32 v87, 0x80000000, v44
	v_mov_b32_e32 v86, v45
	v_pk_add_f32 v[44:45], v[32:33], v[52:53]
	v_pk_add_f32 v[32:33], v[32:33], v[52:53] neg_lo:[0,1] neg_hi:[0,1]
	v_pk_add_f32 v[52:53], v[40:41], v[46:47]
	v_pk_add_f32 v[40:41], v[40:41], v[46:47] neg_lo:[0,1] neg_hi:[0,1]
	s_nop 0
	v_xor_b32_e32 v47, 0x80000000, v40
	v_mov_b32_e32 v46, v41
	v_pk_add_f32 v[40:41], v[54:55], v[92:93]
	v_pk_add_f32 v[54:55], v[54:55], v[92:93] neg_lo:[0,1] neg_hi:[0,1]
	v_pk_add_f32 v[92:93], v[48:49], v[84:85]
	v_pk_add_f32 v[48:49], v[48:49], v[84:85] neg_lo:[0,1] neg_hi:[0,1]
	v_pk_add_f32 v[84:85], v[42:43], v[88:89]
	v_pk_add_f32 v[42:43], v[42:43], v[88:89] neg_lo:[0,1] neg_hi:[0,1]
	v_pk_add_f32 v[88:89], v[34:35], v[82:83]
	v_pk_add_f32 v[34:35], v[34:35], v[82:83] neg_lo:[0,1] neg_hi:[0,1]
	v_pk_add_f32 v[82:83], v[36:37], v[90:91]
	v_pk_add_f32 v[36:37], v[36:37], v[90:91] neg_lo:[0,1] neg_hi:[0,1]
	v_pk_add_f32 v[90:91], v[50:51], v[86:87]
	v_pk_add_f32 v[50:51], v[50:51], v[86:87] neg_lo:[0,1] neg_hi:[0,1]
	v_pk_add_f32 v[86:87], v[44:45], v[52:53]
	v_pk_add_f32 v[44:45], v[44:45], v[52:53] neg_lo:[0,1] neg_hi:[0,1]
	v_pk_add_f32 v[52:53], v[32:33], v[46:47]
	v_pk_add_f32 v[32:33], v[32:33], v[46:47] neg_lo:[0,1] neg_hi:[0,1]
	v_pk_add_f32 v[46:47], v[20:21], v[28:29]
	v_pk_add_f32 v[20:21], v[20:21], v[28:29] neg_lo:[0,1] neg_hi:[0,1]
	v_pk_add_f32 v[28:29], v[22:23], v[30:31]
	v_pk_add_f32 v[22:23], v[22:23], v[30:31] neg_lo:[0,1] neg_hi:[0,1]
	s_nop 0
	v_pk_mul_f32 v[30:31], v[22:23], s[42:43] op_sel_hi:[0,1]
	v_pk_fma_f32 v[22:23], v[22:23], s[64:65], v[30:31] op_sel:[1,0,0]
	v_pk_add_f32 v[30:31], v[12:13], v[24:25]
	v_pk_add_f32 v[12:13], v[12:13], v[24:25] neg_lo:[0,1] neg_hi:[0,1]
	s_nop 0
	v_mul_f32_e32 v24, 0x3f3504f3, v13
	v_pk_fma_f32 v[12:13], v[12:13], s[56:57], v[24:25] op_sel_hi:[0,1,0]
	v_pk_add_f32 v[24:25], v[14:15], v[26:27]
	v_pk_add_f32 v[14:15], v[14:15], v[26:27] neg_lo:[0,1] neg_hi:[0,1]
	s_nop 0
	v_pk_mul_f32 v[26:27], v[14:15], s[66:67] op_sel_hi:[0,1]
	v_pk_fma_f32 v[14:15], v[14:15], s[40:41], v[26:27] op_sel:[1,0,0]
	v_pk_add_f32 v[26:27], v[4:5], v[16:17]
	v_pk_add_f32 v[4:5], v[4:5], v[16:17] neg_lo:[0,1] neg_hi:[0,1]
	s_nop 0
	v_xor_b32_e32 v17, 0x80000000, v4
	v_mov_b32_e32 v16, v5
	v_pk_add_f32 v[4:5], v[6:7], v[18:19]
	v_pk_add_f32 v[6:7], v[6:7], v[18:19] neg_lo:[0,1] neg_hi:[0,1]
	s_nop 0
	v_pk_mul_f32 v[18:19], v[6:7], s[44:45] op_sel_hi:[0,1]
	v_pk_fma_f32 v[6:7], v[6:7], s[42:43], v[18:19] op_sel:[1,0,0]
	s_waitcnt lgkmcnt(0)
	v_pk_add_f32 v[18:19], v[0:1], v[8:9]
	v_pk_add_f32 v[0:1], v[0:1], v[8:9] neg_lo:[0,1] neg_hi:[0,1]
	s_nop 0
	v_mul_f32_e32 v8, 0xbf3504f3, v0
	v_pk_fma_f32 v[0:1], v[0:1], s[56:57], v[8:9] op_sel:[1,0,0] op_sel_hi:[1,1,0]
	v_pk_add_f32 v[8:9], v[2:3], v[10:11]
	v_pk_add_f32 v[2:3], v[2:3], v[10:11] neg_lo:[0,1] neg_hi:[0,1]
	s_nop 0
	v_pk_mul_f32 v[10:11], v[2:3], s[58:59] op_sel_hi:[0,1]
	v_pk_fma_f32 v[2:3], v[2:3], s[66:67], v[10:11] op_sel:[1,0,0]
	v_pk_add_f32 v[10:11], v[46:47], v[26:27]
	v_pk_add_f32 v[26:27], v[46:47], v[26:27] neg_lo:[0,1] neg_hi:[0,1]
	v_pk_add_f32 v[46:47], v[28:29], v[4:5]
	v_pk_add_f32 v[4:5], v[28:29], v[4:5] neg_lo:[0,1] neg_hi:[0,1]
	s_nop 0
	v_mul_f32_e32 v28, 0x3f3504f3, v5
	v_pk_fma_f32 v[4:5], v[4:5], s[56:57], v[28:29] op_sel_hi:[0,1,0]
	v_pk_add_f32 v[28:29], v[30:31], v[18:19]
	v_pk_add_f32 v[18:19], v[30:31], v[18:19] neg_lo:[0,1] neg_hi:[0,1]
	s_nop 0
	v_xor_b32_e32 v31, 0x80000000, v18
	v_mov_b32_e32 v30, v19
	v_pk_add_f32 v[18:19], v[24:25], v[8:9]
	v_pk_add_f32 v[8:9], v[24:25], v[8:9] neg_lo:[0,1] neg_hi:[0,1]
	s_nop 0
	v_mul_f32_e32 v24, 0xbf3504f3, v8
	v_pk_fma_f32 v[8:9], v[8:9], s[56:57], v[24:25] op_sel:[1,0,0] op_sel_hi:[1,1,0]
	v_pk_add_f32 v[24:25], v[20:21], v[16:17]
	v_pk_add_f32 v[16:17], v[20:21], v[16:17] neg_lo:[0,1] neg_hi:[0,1]
	v_pk_add_f32 v[20:21], v[22:23], v[6:7]
	v_pk_add_f32 v[6:7], v[22:23], v[6:7] neg_lo:[0,1] neg_hi:[0,1]
	s_nop 0
	v_mul_f32_e32 v22, 0x3f3504f3, v7
	v_pk_fma_f32 v[6:7], v[6:7], s[56:57], v[22:23] op_sel_hi:[0,1,0]
	v_pk_add_f32 v[22:23], v[12:13], v[0:1]
	v_pk_add_f32 v[0:1], v[12:13], v[0:1] neg_lo:[0,1] neg_hi:[0,1]
	s_nop 0
	v_xor_b32_e32 v13, 0x80000000, v0
	v_mov_b32_e32 v12, v1
	v_pk_add_f32 v[0:1], v[14:15], v[2:3]
	v_pk_add_f32 v[2:3], v[14:15], v[2:3] neg_lo:[0,1] neg_hi:[0,1]
	s_nop 0
	v_mul_f32_e32 v14, 0xbf3504f3, v2
	v_pk_fma_f32 v[2:3], v[2:3], s[56:57], v[14:15] op_sel:[1,0,0] op_sel_hi:[1,1,0]
	v_pk_add_f32 v[14:15], v[10:11], v[28:29]
	v_pk_add_f32 v[10:11], v[10:11], v[28:29] neg_lo:[0,1] neg_hi:[0,1]
	v_pk_add_f32 v[28:29], v[46:47], v[18:19]
	v_pk_add_f32 v[18:19], v[46:47], v[18:19] neg_lo:[0,1] neg_hi:[0,1]
	s_nop 0
	v_xor_b32_e32 v47, 0x80000000, v18
	v_mov_b32_e32 v46, v19
	v_pk_add_f32 v[18:19], v[26:27], v[30:31]
	v_pk_add_f32 v[26:27], v[26:27], v[30:31] neg_lo:[0,1] neg_hi:[0,1]
	v_pk_add_f32 v[30:31], v[4:5], v[8:9]
	v_pk_add_f32 v[4:5], v[4:5], v[8:9] neg_lo:[0,1] neg_hi:[0,1]
	s_nop 0
	v_xor_b32_e32 v9, 0x80000000, v4
	v_mov_b32_e32 v8, v5
	v_pk_add_f32 v[4:5], v[24:25], v[22:23]
	v_pk_add_f32 v[22:23], v[24:25], v[22:23] neg_lo:[0,1] neg_hi:[0,1]
	v_pk_add_f32 v[24:25], v[20:21], v[0:1]
	v_pk_add_f32 v[0:1], v[20:21], v[0:1] neg_lo:[0,1] neg_hi:[0,1]
	s_nop 0
	v_xor_b32_e32 v21, 0x80000000, v0
	v_mov_b32_e32 v20, v1
	v_pk_add_f32 v[0:1], v[16:17], v[12:13]
	v_pk_add_f32 v[12:13], v[16:17], v[12:13] neg_lo:[0,1] neg_hi:[0,1]
	v_pk_add_f32 v[16:17], v[6:7], v[2:3]
	v_pk_add_f32 v[2:3], v[6:7], v[2:3] neg_lo:[0,1] neg_hi:[0,1]
	s_nop 0
	v_xor_b32_e32 v7, 0x80000000, v2
	v_mov_b32_e32 v6, v3
	v_pk_add_f32 v[2:3], v[14:15], v[28:29]
	v_pk_add_f32 v[14:15], v[14:15], v[28:29] neg_lo:[0,1] neg_hi:[0,1]
	v_pk_add_f32 v[28:29], v[10:11], v[46:47]
	v_pk_add_f32 v[10:11], v[10:11], v[46:47] neg_lo:[0,1] neg_hi:[0,1]
	v_pk_add_f32 v[46:47], v[18:19], v[30:31]
	v_pk_add_f32 v[18:19], v[18:19], v[30:31] neg_lo:[0,1] neg_hi:[0,1]
	v_pk_add_f32 v[30:31], v[26:27], v[8:9]
	v_pk_add_f32 v[8:9], v[26:27], v[8:9] neg_lo:[0,1] neg_hi:[0,1]
	v_pk_add_f32 v[26:27], v[4:5], v[24:25]
	v_pk_add_f32 v[4:5], v[4:5], v[24:25] neg_lo:[0,1] neg_hi:[0,1]
	v_pk_add_f32 v[24:25], v[22:23], v[20:21]
	v_pk_add_f32 v[20:21], v[22:23], v[20:21] neg_lo:[0,1] neg_hi:[0,1]
	v_pk_add_f32 v[22:23], v[0:1], v[16:17]
	v_pk_add_f32 v[0:1], v[0:1], v[16:17] neg_lo:[0,1] neg_hi:[0,1]
	v_pk_add_f32 v[16:17], v[12:13], v[6:7]
	v_pk_add_f32 v[6:7], v[12:13], v[6:7] neg_lo:[0,1] neg_hi:[0,1]
	ds_write_b64 v39, v[40:41]
	ds_write_b64 v98, v[2:3]
	ds_write_b64 v39, v[54:55] offset:64
	ds_write_b64 v98, v[14:15] offset:64
	ds_write_b64 v39, v[92:93] offset:32
	ds_write_b64 v98, v[28:29] offset:32
	ds_write_b64 v39, v[48:49] offset:96
	ds_write_b64 v98, v[10:11] offset:96
	ds_write_b64 v39, v[84:85] offset:16
	ds_write_b64 v98, v[46:47] offset:16
	ds_write_b64 v39, v[42:43] offset:80
	ds_write_b64 v98, v[18:19] offset:80
	ds_write_b64 v39, v[88:89] offset:48
	ds_write_b64 v98, v[30:31] offset:48
	ds_write_b64 v39, v[34:35] offset:112
	ds_write_b64 v98, v[8:9] offset:112
	ds_write_b64 v39, v[82:83] offset:8
	ds_write_b64 v98, v[26:27] offset:8
	ds_write_b64 v39, v[36:37] offset:72
	ds_write_b64 v98, v[4:5] offset:72
	ds_write_b64 v39, v[90:91] offset:40
	ds_write_b64 v98, v[24:25] offset:40
	ds_write_b64 v39, v[50:51] offset:104
	ds_write_b64 v98, v[20:21] offset:104
	ds_write_b64 v39, v[86:87] offset:24
	ds_write_b64 v98, v[22:23] offset:24
	ds_write_b64 v39, v[44:45] offset:88
	ds_write_b64 v98, v[0:1] offset:88
	ds_write_b64 v39, v[52:53] offset:56
	ds_write_b64 v98, v[16:17] offset:56
	ds_write_b64 v39, v[32:33] offset:120
	ds_write_b64 v98, v[6:7] offset:120
	s_andn2_b64 exec, exec, s[88:89]
	s_cbranch_execnz .LBB0_297

.LBB0_309:
	v_mul_f32_e32 v252, 0x38800000, v82
	v_mov_b32_e32 v253, v252
	s_lshl_b32 s33, s80, 15
	s_add_u32 s90, s52, s33
	s_addc_u32 s91, s73, 0
	v_lshl_add_u64 v[104:105], v[62:63], 1, s[90:91]
	s_cmp_lg_u32 s80, 0
	s_cbranch_scc1 .Lbp_nobar
	s_barrier
.Lbp_nobar:
	global_load_dwordx4 v[0:3], v[104:105], off
	v_mov_b32_e32 v16, 0
	v_lshl_add_u64 v[110:111], v[68:69], 1, s[90:91]
	v_mov_b32_e32 v17, 0
	v_mov_b32_e32 v244, 0
	s_and_saveexec_b64 s[40:41], s[12:13]
	s_cbranch_execz .LBB0_311
	global_load_ushort v244, v[110:111], off offset:-2
	s_nop 0
	s_nop 0

.LBB0_343:
	v_ashrrev_i32_e32 v1, 7, v0
	v_mov_b32_e32 v22, v0
	v_mad_u64_u32 v[2:3], s[40:41], v1, s25, v[60:61]
	v_cvt_f32_i32_e32 v1, v22
	v_add_u32_e32 v52, 0x200, v0
	v_ashrrev_i32_e32 v4, 7, v52
	v_mul_f32_e32 v1, 0x38800000, v1
	v_cos_f32_e32 v22, v1
	v_sin_f32_e32 v24, v1
	v_mad_u64_u32 v[4:5], s[40:41], v4, s25, v[60:61]
	ds_read_b64 v[6:7], v2
	ds_read_b64 v[8:9], v4
	ds_read_b64 v[10:11], v2 offset:16512
	ds_read_b64 v[12:13], v4 offset:16512
	ds_read_b64 v[14:15], v2 offset:33024
	ds_read_b64 v[16:17], v4 offset:33024
	ds_read_b64 v[18:19], v2 offset:49536
	ds_read_b64 v[20:21], v4 offset:49536
	v_mov_b32_e32 v25, v22
	v_xor_b32_e32 v23, 0x80000000, v24
	v_pk_mul_f32 v[26:27], v[24:25], v[24:25] op_sel_hi:[1,0] neg_lo:[0,1] neg_hi:[0,1]
	s_waitcnt lgkmcnt(5)
	v_mul_f32_e32 v42, 0x3f3504f3, v11
	v_pk_fma_f32 v[26:27], v[22:23], v[22:23], v[26:27] op_sel_hi:[1,0,1]
	s_waitcnt lgkmcnt(1)
	v_mul_f32_e32 v46, 0xbf3504f3, v18
	v_xor_b32_e32 v30, 0x80000000, v27
	v_mov_b32_e32 v31, v26
	v_pk_fma_f32 v[42:43], v[10:11], s[56:57], v[42:43] op_sel_hi:[0,1,0]
	v_xor_b32_e32 v45, 0x80000000, v14
	v_mov_b32_e32 v44, v15
	v_pk_fma_f32 v[46:47], v[18:19], s[56:57], v[46:47] op_sel:[1,0,0] op_sel_hi:[1,1,0]
	v_pk_add_f32 v[50:51], v[10:11], v[18:19]
	v_pk_add_f32 v[10:11], v[10:11], v[18:19] neg_lo:[0,1] neg_hi:[0,1]
	v_pk_mul_f32 v[28:29], v[24:25], v[26:27] op_sel:[0,1]
	v_pk_mul_f32 v[32:33], v[26:27], v[30:31] op_sel:[1,0]
	v_pk_add_f32 v[48:49], v[6:7], v[14:15]
	v_pk_add_f32 v[14:15], v[6:7], v[14:15] neg_lo:[0,1] neg_hi:[0,1]
	v_xor_b32_e32 v19, 0x80000000, v10
	v_mov_b32_e32 v18, v11
	v_pk_add_f32 v[10:11], v[6:7], v[44:45]
	v_pk_add_f32 v[6:7], v[6:7], v[44:45] neg_lo:[0,1] neg_hi:[0,1]
	v_pk_add_f32 v[44:45], v[42:43], v[46:47]
	v_pk_add_f32 v[42:43], v[42:43], v[46:47] neg_lo:[0,1] neg_hi:[0,1]
	v_pk_fma_f32 v[28:29], v[22:23], v[26:27], v[28:29] op_sel_hi:[1,0,1]
	v_pk_fma_f32 v[32:33], v[26:27], v[26:27], v[32:33] op_sel_hi:[1,0,1]
	v_xor_b32_e32 v47, 0x80000000, v42
	v_mov_b32_e32 v46, v43
	v_pk_add_f32 v[42:43], v[48:49], v[50:51]
	v_pk_add_f32 v[48:49], v[48:49], v[50:51] neg_lo:[0,1] neg_hi:[0,1]
	v_pk_add_f32 v[50:51], v[14:15], v[18:19]
	v_pk_add_f32 v[14:15], v[14:15], v[18:19] neg_lo:[0,1] neg_hi:[0,1]
	v_pk_add_f32 v[18:19], v[10:11], v[44:45]
	v_pk_mul_f32 v[34:35], v[24:25], v[32:33] op_sel:[0,1]
	v_pk_add_f32 v[10:11], v[10:11], v[44:45] neg_lo:[0,1] neg_hi:[0,1]
	v_pk_add_f32 v[44:45], v[6:7], v[46:47]
	v_pk_mul_f32 v[24:25], v[24:25], v[18:19] op_sel:[0,1]
	v_pk_fma_f32 v[34:35], v[22:23], v[32:33], v[34:35] op_sel_hi:[1,0,1]
	v_pk_mul_f32 v[40:41], v[32:33], v[28:29] op_sel:[1,1] op_sel_hi:[1,0] neg_lo:[0,1]
	v_pk_fma_f32 v[18:19], v[22:23], v[18:19], v[24:25] op_sel_hi:[1,0,1]
	v_pk_mul_f32 v[24:25], v[28:29], v[44:45] op_sel:[1,1] op_sel_hi:[0,1] neg_lo:[1,0]
	v_pk_mul_f32 v[36:37], v[30:31], v[32:33] op_sel:[0,1]
	v_pk_fma_f32 v[40:41], v[28:29], v[32:33], v[40:41] op_sel_hi:[1,0,1]
	v_pk_fma_f32 v[24:25], v[28:29], v[44:45], v[24:25] op_sel_hi:[1,0,1]
	v_pk_fma_f32 v[36:37], v[26:27], v[32:33], v[36:37] op_sel_hi:[1,0,1]
	v_pk_mul_f32 v[28:29], v[10:11], v[34:35] op_sel:[1,1] op_sel_hi:[1,0] neg_lo:[0,1]
	v_cvt_f32_i32_e32 v1, v52
	v_pk_fma_f32 v[10:11], v[10:11], v[34:35], v[28:29] op_sel_hi:[0,1,1]
	v_pk_mul_f32 v[28:29], v[14:15], v[36:37] op_sel:[1,1] op_sel_hi:[1,0] neg_lo:[0,1]
	v_pk_add_f32 v[6:7], v[6:7], v[46:47] neg_lo:[0,1] neg_hi:[0,1]
	v_pk_fma_f32 v[14:15], v[14:15], v[36:37], v[28:29] op_sel_hi:[0,1,1]
	v_pk_mul_f32 v[28:29], v[6:7], v[40:41] op_sel:[1,1] op_sel_hi:[1,0] neg_lo:[0,1]
	v_mul_f32_e32 v1, 0x38800000, v1
	v_pk_fma_f32 v[6:7], v[40:41], v[6:7], v[28:29] op_sel_hi:[1,0,1]
	v_cos_f32_e32 v28, v1
	v_pk_mul_f32 v[22:23], v[30:31], v[50:51] op_sel:[0,1]
	v_sin_f32_e32 v30, v1
	v_pk_fma_f32 v[22:23], v[26:27], v[50:51], v[22:23] op_sel_hi:[1,0,1]
	v_pk_mul_f32 v[26:27], v[48:49], v[32:33] op_sel:[1,1] op_sel_hi:[1,0] neg_lo:[0,1]
	v_mov_b32_e32 v31, v28
	v_pk_fma_f32 v[26:27], v[48:49], v[32:33], v[26:27] op_sel_hi:[0,1,1]
	v_xor_b32_e32 v29, 0x80000000, v30
	v_pk_mul_f32 v[32:33], v[30:31], v[30:31] op_sel_hi:[1,0] neg_lo:[0,1] neg_hi:[0,1]
	v_mul_f32_e32 v50, 0x3f3504f3, v13
	v_pk_fma_f32 v[32:33], v[28:29], v[28:29], v[32:33] op_sel_hi:[1,0,1]
	s_waitcnt lgkmcnt(0)
	ds_write_b64 v2, v[42:43]
	ds_write_b64 v2, v[22:23] offset:33024
	ds_write_b64 v2, v[18:19] offset:16512
	ds_write_b64 v2, v[24:25] offset:49536
	v_mul_f32_e32 v54, 0xbf3504f3, v20
	v_xor_b32_e32 v36, 0x80000000, v33
	v_mov_b32_e32 v37, v32
	v_pk_fma_f32 v[50:51], v[12:13], s[56:57], v[50:51] op_sel_hi:[0,1,0]
	v_xor_b32_e32 v53, 0x80000000, v16
	v_mov_b32_e32 v52, v17
	v_pk_fma_f32 v[54:55], v[20:21], s[56:57], v[54:55] op_sel:[1,0,0] op_sel_hi:[1,1,0]
	v_pk_add_f32 v[138:139], v[12:13], v[20:21]
	v_pk_add_f32 v[12:13], v[12:13], v[20:21] neg_lo:[0,1] neg_hi:[0,1]
	v_pk_mul_f32 v[34:35], v[30:31], v[32:33] op_sel:[0,1]
	v_pk_mul_f32 v[38:39], v[32:33], v[36:37] op_sel:[1,0]
	v_pk_add_f32 v[136:137], v[8:9], v[16:17]
	v_pk_add_f32 v[16:17], v[8:9], v[16:17] neg_lo:[0,1] neg_hi:[0,1]
	v_xor_b32_e32 v21, 0x80000000, v12
	v_mov_b32_e32 v20, v13
	v_pk_add_f32 v[12:13], v[8:9], v[52:53]
	v_pk_add_f32 v[8:9], v[8:9], v[52:53] neg_lo:[0,1] neg_hi:[0,1]
	v_pk_add_f32 v[52:53], v[50:51], v[54:55]
	v_pk_add_f32 v[50:51], v[50:51], v[54:55] neg_lo:[0,1] neg_hi:[0,1]
	v_pk_fma_f32 v[34:35], v[28:29], v[32:33], v[34:35] op_sel_hi:[1,0,1]
	v_pk_fma_f32 v[38:39], v[32:33], v[32:33], v[38:39] op_sel_hi:[1,0,1]
	v_xor_b32_e32 v55, 0x80000000, v50
	v_mov_b32_e32 v54, v51
	v_pk_add_f32 v[50:51], v[136:137], v[138:139]
	v_pk_add_f32 v[136:137], v[136:137], v[138:139] neg_lo:[0,1] neg_hi:[0,1]
	ds_write_b64 v4, v[50:51]
	v_pk_add_f32 v[138:139], v[16:17], v[20:21]
	v_pk_add_f32 v[16:17], v[16:17], v[20:21] neg_lo:[0,1] neg_hi:[0,1]
	v_pk_add_f32 v[20:21], v[12:13], v[52:53]
	v_pk_mul_f32 v[40:41], v[30:31], v[38:39] op_sel:[0,1]
	v_xor_b32_e32 v46, 0x80000000, v35
	v_mov_b32_e32 v47, v34
	v_pk_add_f32 v[12:13], v[12:13], v[52:53] neg_lo:[0,1] neg_hi:[0,1]
	v_pk_add_f32 v[52:53], v[8:9], v[54:55]
	v_pk_mul_f32 v[30:31], v[30:31], v[20:21] op_sel:[0,1]
	v_pk_fma_f32 v[40:41], v[28:29], v[38:39], v[40:41] op_sel_hi:[1,0,1]
	v_pk_mul_f32 v[44:45], v[36:37], v[38:39] op_sel:[0,1]
	v_pk_mul_f32 v[48:49], v[38:39], v[46:47] op_sel:[1,0]
	v_pk_fma_f32 v[20:21], v[28:29], v[20:21], v[30:31] op_sel_hi:[1,0,1]
	v_pk_mul_f32 v[28:29], v[36:37], v[138:139] op_sel:[0,1]
	ds_write_b64 v4, v[20:21] offset:16512
	v_pk_mul_f32 v[30:31], v[46:47], v[52:53] op_sel:[0,1]
	v_pk_fma_f32 v[44:45], v[32:33], v[38:39], v[44:45] op_sel_hi:[1,0,1]
	v_pk_fma_f32 v[48:49], v[34:35], v[38:39], v[48:49] op_sel_hi:[1,0,1]
	v_pk_fma_f32 v[28:29], v[32:33], v[138:139], v[28:29] op_sel_hi:[1,0,1]
	v_pk_fma_f32 v[30:31], v[34:35], v[52:53], v[30:31] op_sel_hi:[1,0,1]
	ds_write_b64 v4, v[28:29] offset:33024
	v_pk_mul_f32 v[32:33], v[136:137], v[38:39] op_sel:[1,1] op_sel_hi:[1,0] neg_lo:[0,1]
	ds_write_b64 v4, v[30:31] offset:49536
	v_pk_mul_f32 v[34:35], v[12:13], v[40:41] op_sel:[1,1] op_sel_hi:[1,0] neg_lo:[0,1]
	v_add_u32_e32 v1, 0x10200, v2
	v_pk_fma_f32 v[32:33], v[136:137], v[38:39], v[32:33] op_sel_hi:[0,1,1]
	ds_write_b64 v1, v[26:27]
	v_pk_fma_f32 v[12:13], v[12:13], v[40:41], v[34:35] op_sel_hi:[0,1,1]
	v_add_u32_e32 v1, 0x10200, v4
	v_pk_mul_f32 v[34:35], v[16:17], v[44:45] op_sel:[1,1] op_sel_hi:[1,0] neg_lo:[0,1]
	ds_write_b64 v1, v[32:33]
	v_add_u32_e32 v1, 0x18300, v2
	v_pk_fma_f32 v[16:17], v[16:17], v[44:45], v[34:35] op_sel_hi:[0,1,1]
	ds_write_b64 v1, v[14:15]
	v_add_u32_e32 v1, 0x18300, v4
	ds_write_b64 v1, v[16:17]
	v_add_u32_e32 v1, 0x14280, v2
	v_pk_add_f32 v[8:9], v[8:9], v[54:55] neg_lo:[0,1] neg_hi:[0,1]
	ds_write_b64 v1, v[10:11]
	v_add_u32_e32 v1, 0x14280, v4
	v_pk_mul_f32 v[34:35], v[8:9], v[48:49] op_sel:[1,1] op_sel_hi:[1,0] neg_lo:[0,1]
	ds_write_b64 v1, v[12:13]
	v_add_u32_e32 v1, 0x1c380, v2
	v_cmp_lt_i32_e32 vcc, s28, v0
	ds_write_b64 v1, v[6:7]
	v_pk_fma_f32 v[8:9], v[48:49], v[8:9], v[34:35] op_sel_hi:[1,0,1]
	v_add_u32_e32 v1, 0x1c380, v4
	v_add_u32_e32 v0, 0x400, v0
	ds_write_b64 v1, v[8:9]
	s_or_b64 s[92:93], vcc, s[92:93]
	s_andn2_b64 exec, exec, s[92:93]
	s_cbranch_execnz .LBB0_343
	s_or_b64 exec, exec, s[92:93]

.LBB0_347:
	v_lshrrev_b32_e32 v0, 3, v66
	v_add_u32_e32 v1, 0x200, v66
	v_and_b32_e32 v0, 0x1ffffff0, v0
	v_lshrrev_b32_e32 v1, 3, v1
	v_and_b32_e32 v1, 0x1ffffff0, v1
	v_mad_u64_u32 v[136:137], s[40:41], v0, s25, v[60:61]
	v_mov_b32_e32 v140, v65
	v_mov_b32_e32 v216, v65
	v_mad_u64_u32 v[138:139], s[40:41], v1, s25, v[60:61]
	v_add_u32_e32 v16, 0x2000, v136
	ds_read_b64 v[190:191], v136
	ds_read_b64 v[192:193], v136 offset:1032
	ds_read_b64 v[12:13], v138
	ds_read_b64 v[14:15], v138 offset:1032
	ds_read_b64 v[218:219], v16 offset:64
	ds_read_b64 v[220:221], v16 offset:1096
	v_add_u32_e32 v16, 0x2000, v138
	v_add_u32_e32 v0, 0x800, v136
	ds_read_b64 v[28:29], v16 offset:64
	ds_read_b64 v[30:31], v16 offset:1096
	v_add_u32_e32 v16, 0x2800, v136
	ds_read_b64 v[48:49], v0 offset:16
	ds_read_b64 v[50:51], v0 offset:1048
	ds_read_b64 v[52:53], v16 offset:80
	ds_read_b64 v[54:55], v16 offset:1112
	v_add_u32_e32 v0, 0x800, v138
	v_add_u32_e32 v16, 0x2800, v138
	ds_read_b64 v[8:9], v0 offset:16
	ds_read_b64 v[10:11], v0 offset:1048
	v_add_u32_e32 v0, 0x1000, v136
	ds_read_b64 v[24:25], v16 offset:80
	ds_read_b64 v[26:27], v16 offset:1112
	v_add_u32_e32 v16, 0x3000, v136
	s_waitcnt lgkmcnt(10)
	v_pk_add_f32 v[188:189], v[190:191], v[218:219]
	v_pk_add_f32 v[186:187], v[190:191], v[218:219] neg_lo:[0,1] neg_hi:[0,1]
	v_pk_add_f32 v[190:191], v[192:193], v[220:221]
	v_pk_add_f32 v[192:193], v[192:193], v[220:221] neg_lo:[0,1] neg_hi:[0,1]
	ds_read_b64 v[40:41], v0 offset:32
	ds_read_b64 v[42:43], v0 offset:1064
	ds_read_b64 v[44:45], v16 offset:96
	ds_read_b64 v[46:47], v16 offset:1128
	v_pk_mul_f32 v[194:195], v[192:193], s[42:43] op_sel_hi:[0,1]
	s_mov_b32 s65, s42
	v_add_u32_e32 v0, 0x1000, v138
	v_add_u32_e32 v16, 0x3000, v138
	v_pk_fma_f32 v[192:193], v[192:193], s[64:65], v[194:195] op_sel:[1,0,0]
	s_waitcnt lgkmcnt(8)
	v_pk_add_f32 v[194:195], v[48:49], v[52:53]
	v_pk_add_f32 v[48:49], v[48:49], v[52:53] neg_lo:[0,1] neg_hi:[0,1]
	ds_read_b64 v[4:5], v0 offset:32
	ds_read_b64 v[6:7], v0 offset:1064
	v_add_u32_e32 v0, 0x1800, v136
	ds_read_b64 v[20:21], v16 offset:96
	ds_read_b64 v[22:23], v16 offset:1128
	v_add_u32_e32 v16, 0x3800, v136
	v_mul_f32_e32 v52, 0x3f3504f3, v49
	ds_read_b64 v[32:33], v0 offset:48
	ds_read_b64 v[34:35], v0 offset:1080
	ds_read_b64 v[36:37], v16 offset:112
	ds_read_b64 v[38:39], v16 offset:1144
	v_pk_fma_f32 v[48:49], v[48:49], s[56:57], v[52:53] op_sel_hi:[0,1,0]
	v_pk_add_f32 v[52:53], v[50:51], v[54:55]
	v_pk_add_f32 v[50:51], v[50:51], v[54:55] neg_lo:[0,1] neg_hi:[0,1]
	s_mov_b32 s66, s64
	v_pk_mul_f32 v[54:55], v[50:51], s[66:67] op_sel_hi:[0,1]
	s_mov_b32 s44, s42
	s_mov_b32 s45, s64
	v_cvt_f32_i32_e32 v137, v140
	v_pk_fma_f32 v[50:51], v[50:51], s[44:45], v[54:55] op_sel:[1,0,0]
	s_waitcnt lgkmcnt(8)
	v_pk_add_f32 v[54:55], v[40:41], v[44:45]
	v_pk_add_f32 v[40:41], v[40:41], v[44:45] neg_lo:[0,1] neg_hi:[0,1]
	s_mov_b32 s58, s43
	v_xor_b32_e32 v45, 0x80000000, v40
	v_mov_b32_e32 v44, v41
	v_pk_add_f32 v[40:41], v[42:43], v[46:47]
	v_pk_add_f32 v[42:43], v[42:43], v[46:47] neg_lo:[0,1] neg_hi:[0,1]
	s_mov_b32 s59, s67
	v_pk_mul_f32 v[46:47], v[42:43], s[58:59] op_sel_hi:[0,1]
	v_pk_fma_f32 v[42:43], v[42:43], s[42:43], v[46:47] op_sel:[1,0,0]
	s_waitcnt lgkmcnt(0)
	v_pk_add_f32 v[46:47], v[32:33], v[36:37]
	v_pk_add_f32 v[32:33], v[32:33], v[36:37] neg_lo:[0,1] neg_hi:[0,1]
	v_mul_f32_e32 v137, 0x3a000000, v137
	v_mul_f32_e32 v36, 0xbf3504f3, v32
	v_cos_f32_e32 v148, v137
	v_pk_fma_f32 v[32:33], v[32:33], s[56:57], v[36:37] op_sel:[1,0,0] op_sel_hi:[1,1,0]
	v_pk_add_f32 v[36:37], v[34:35], v[38:39]
	v_pk_add_f32 v[34:35], v[34:35], v[38:39] neg_lo:[0,1] neg_hi:[0,1]
	s_mov_b32 s40, s67
	s_mov_b32 s41, s43
	v_sin_f32_e32 v152, v137
	v_pk_mul_f32 v[38:39], v[34:35], s[40:41] op_sel_hi:[0,1]
	v_pk_fma_f32 v[34:35], v[34:35], s[66:67], v[38:39] op_sel:[1,0,0]
	v_pk_add_f32 v[38:39], v[188:189], v[54:55]
	v_pk_add_f32 v[54:55], v[188:189], v[54:55] neg_lo:[0,1] neg_hi:[0,1]
	v_pk_add_f32 v[188:189], v[190:191], v[40:41]
	v_pk_add_f32 v[40:41], v[190:191], v[40:41] neg_lo:[0,1] neg_hi:[0,1]
	v_mov_b32_e32 v153, v148
	v_mul_f32_e32 v190, 0x3f3504f3, v41
	v_pk_fma_f32 v[40:41], v[40:41], s[56:57], v[190:191] op_sel_hi:[0,1,0]
	v_pk_add_f32 v[190:191], v[194:195], v[46:47]
	v_pk_add_f32 v[46:47], v[194:195], v[46:47] neg_lo:[0,1] neg_hi:[0,1]
	v_xor_b32_e32 v149, 0x80000000, v152
	v_pk_mul_f32 v[140:141], v[152:153], v[152:153] op_sel_hi:[1,0] neg_lo:[0,1] neg_hi:[0,1]
	v_xor_b32_e32 v195, 0x80000000, v46
	v_mov_b32_e32 v194, v47
	v_pk_add_f32 v[46:47], v[52:53], v[36:37]
	v_pk_add_f32 v[36:37], v[52:53], v[36:37] neg_lo:[0,1] neg_hi:[0,1]
	v_pk_fma_f32 v[154:155], v[148:149], v[148:149], v[140:141] op_sel_hi:[1,0,1]
	v_mul_f32_e32 v52, 0xbf3504f3, v36
	v_pk_mul_f32 v[140:141], v[152:153], v[154:155] op_sel:[0,1]
	v_pk_fma_f32 v[36:37], v[36:37], s[56:57], v[52:53] op_sel:[1,0,0] op_sel_hi:[1,1,0]
	v_pk_add_f32 v[52:53], v[186:187], v[44:45]
	v_pk_add_f32 v[44:45], v[186:187], v[44:45] neg_lo:[0,1] neg_hi:[0,1]
	v_pk_add_f32 v[186:187], v[192:193], v[42:43]
	v_pk_add_f32 v[42:43], v[192:193], v[42:43] neg_lo:[0,1] neg_hi:[0,1]
	v_pk_fma_f32 v[156:157], v[148:149], v[154:155], v[140:141] op_sel_hi:[1,0,1]
	v_pk_mul_f32 v[140:141], v[154:155], v[154:155] op_sel:[1,1] op_sel_hi:[1,0] neg_lo:[0,1]
	v_mul_f32_e32 v192, 0x3f3504f3, v43
	v_pk_fma_f32 v[160:161], v[154:155], v[154:155], v[140:141] op_sel_hi:[1,0,1]
	v_pk_fma_f32 v[42:43], v[42:43], s[56:57], v[192:193] op_sel_hi:[0,1,0]
	v_pk_add_f32 v[192:193], v[48:49], v[32:33]
	v_pk_add_f32 v[32:33], v[48:49], v[32:33] neg_lo:[0,1] neg_hi:[0,1]
	v_pk_mul_f32 v[140:141], v[152:153], v[160:161] op_sel:[0,1]
	v_xor_b32_e32 v49, 0x80000000, v32
	v_mov_b32_e32 v48, v33
	v_pk_add_f32 v[32:33], v[50:51], v[34:35]
	v_pk_add_f32 v[34:35], v[50:51], v[34:35] neg_lo:[0,1] neg_hi:[0,1]
	v_pk_fma_f32 v[162:163], v[148:149], v[160:161], v[140:141] op_sel_hi:[1,0,1]
	v_pk_mul_f32 v[140:141], v[154:155], v[160:161] op_sel:[1,1] op_sel_hi:[0,1] neg_lo:[1,0]
	v_mul_f32_e32 v50, 0xbf3504f3, v34
	v_pk_fma_f32 v[164:165], v[154:155], v[160:161], v[140:141] op_sel_hi:[1,0,1]
	v_pk_mul_f32 v[140:141], v[160:161], v[156:157] op_sel:[1,1] op_sel_hi:[1,0] neg_lo:[0,1]
	v_pk_fma_f32 v[34:35], v[34:35], s[56:57], v[50:51] op_sel:[1,0,0] op_sel_hi:[1,1,0]
	v_pk_add_f32 v[50:51], v[38:39], v[190:191]
	v_pk_add_f32 v[38:39], v[38:39], v[190:191] neg_lo:[0,1] neg_hi:[0,1]
	v_pk_add_f32 v[190:191], v[188:189], v[46:47]
	v_pk_add_f32 v[46:47], v[188:189], v[46:47] neg_lo:[0,1] neg_hi:[0,1]
	v_pk_fma_f32 v[170:171], v[156:157], v[160:161], v[140:141] op_sel_hi:[1,0,1]
	v_pk_mul_f32 v[140:141], v[160:161], v[160:161] op_sel:[1,1] op_sel_hi:[1,0] neg_lo:[0,1]
	v_xor_b32_e32 v189, 0x80000000, v46
	v_mov_b32_e32 v188, v47
	v_pk_add_f32 v[46:47], v[54:55], v[194:195]
	v_pk_add_f32 v[54:55], v[54:55], v[194:195] neg_lo:[0,1] neg_hi:[0,1]
	v_pk_add_f32 v[194:195], v[40:41], v[36:37]
	v_pk_add_f32 v[36:37], v[40:41], v[36:37] neg_lo:[0,1] neg_hi:[0,1]
	v_pk_fma_f32 v[172:173], v[160:161], v[160:161], v[140:141] op_sel_hi:[1,0,1]
	v_xor_b32_e32 v41, 0x80000000, v36
	v_mov_b32_e32 v40, v37
	v_pk_add_f32 v[36:37], v[52:53], v[192:193]
	v_pk_add_f32 v[52:53], v[52:53], v[192:193] neg_lo:[0,1] neg_hi:[0,1]
	v_pk_add_f32 v[192:193], v[186:187], v[32:33]
	v_pk_add_f32 v[32:33], v[186:187], v[32:33] neg_lo:[0,1] neg_hi:[0,1]
	v_pk_mul_f32 v[140:141], v[152:153], v[172:173] op_sel:[0,1]
	v_xor_b32_e32 v187, 0x80000000, v32
	v_mov_b32_e32 v186, v33
	v_pk_add_f32 v[32:33], v[44:45], v[48:49]
	v_pk_add_f32 v[44:45], v[44:45], v[48:49] neg_lo:[0,1] neg_hi:[0,1]
	v_pk_add_f32 v[48:49], v[42:43], v[34:35]
	v_pk_add_f32 v[34:35], v[42:43], v[34:35] neg_lo:[0,1] neg_hi:[0,1]
	v_pk_fma_f32 v[166:167], v[148:149], v[172:173], v[140:141] op_sel_hi:[1,0,1]
	v_pk_mul_f32 v[140:141], v[154:155], v[172:173] op_sel:[1,1] op_sel_hi:[0,1] neg_lo:[1,0]
	v_xor_b32_e32 v43, 0x80000000, v34
	v_mov_b32_e32 v42, v35
	v_pk_add_f32 v[34:35], v[50:51], v[190:191]
	v_pk_add_f32 v[50:51], v[50:51], v[190:191] neg_lo:[0,1] neg_hi:[0,1]
	v_pk_add_f32 v[190:191], v[38:39], v[188:189]
	v_pk_add_f32 v[38:39], v[38:39], v[188:189] neg_lo:[0,1] neg_hi:[0,1]
	v_pk_add_f32 v[188:189], v[46:47], v[194:195]
	v_pk_add_f32 v[46:47], v[46:47], v[194:195] neg_lo:[0,1] neg_hi:[0,1]
	v_pk_add_f32 v[194:195], v[54:55], v[40:41]
	v_pk_add_f32 v[40:41], v[54:55], v[40:41] neg_lo:[0,1] neg_hi:[0,1]
	v_pk_add_f32 v[54:55], v[36:37], v[192:193]
	v_pk_fma_f32 v[158:159], v[154:155], v[172:173], v[140:141] op_sel_hi:[1,0,1]
	v_pk_mul_f32 v[140:141], v[156:157], v[172:173] op_sel:[1,1] op_sel_hi:[0,1] neg_lo:[1,0]
	v_pk_add_f32 v[36:37], v[36:37], v[192:193] neg_lo:[0,1] neg_hi:[0,1]
	v_pk_add_f32 v[192:193], v[52:53], v[186:187]
	v_pk_add_f32 v[52:53], v[52:53], v[186:187] neg_lo:[0,1] neg_hi:[0,1]
	v_pk_add_f32 v[186:187], v[32:33], v[48:49]
	v_pk_add_f32 v[48:49], v[32:33], v[48:49] neg_lo:[0,1] neg_hi:[0,1]
	v_pk_mul_f32 v[32:33], v[152:153], v[54:55] op_sel:[0,1]
	v_pk_fma_f32 v[150:151], v[156:157], v[172:173], v[140:141] op_sel_hi:[1,0,1]
	v_pk_mul_f32 v[140:141], v[160:161], v[172:173] op_sel:[1,1] op_sel_hi:[0,1] neg_lo:[1,0]
	v_pk_add_f32 v[218:219], v[44:45], v[42:43]
	v_pk_add_f32 v[42:43], v[44:45], v[42:43] neg_lo:[0,1] neg_hi:[0,1]
	v_pk_fma_f32 v[44:45], v[148:149], v[54:55], v[32:33] op_sel_hi:[1,0,1]
	v_pk_mul_f32 v[32:33], v[154:155], v[188:189] op_sel:[1,1] op_sel_hi:[0,1] neg_lo:[1,0]
	v_pk_mul_f32 v[148:149], v[160:161], v[190:191] op_sel:[1,1] op_sel_hi:[0,1] neg_lo:[1,0]
	v_pk_fma_f32 v[140:141], v[160:161], v[172:173], v[140:141] op_sel_hi:[1,0,1]
	v_pk_fma_f32 v[54:55], v[154:155], v[188:189], v[32:33] op_sel_hi:[1,0,1]
	v_pk_fma_f32 v[148:149], v[160:161], v[190:191], v[148:149] op_sel_hi:[1,0,1]
	v_pk_mul_f32 v[154:155], v[164:165], v[194:195] op_sel:[1,1] op_sel_hi:[0,1] neg_lo:[1,0]
	v_pk_fma_f32 v[154:155], v[164:165], v[194:195], v[154:155] op_sel_hi:[1,0,1]
	v_pk_mul_f32 v[160:161], v[172:173], v[50:51] op_sel:[1,1] op_sel_hi:[0,1] neg_lo:[1,0]
	v_pk_add_f32 v[194:195], v[12:13], v[28:29]
	v_pk_add_f32 v[12:13], v[12:13], v[28:29] neg_lo:[0,1] neg_hi:[0,1]
	v_pk_add_f32 v[28:29], v[14:15], v[30:31]
	v_pk_add_f32 v[14:15], v[14:15], v[30:31] neg_lo:[0,1] neg_hi:[0,1]
	v_pk_fma_f32 v[50:51], v[172:173], v[50:51], v[160:161] op_sel_hi:[1,0,1]
	v_pk_mul_f32 v[30:31], v[14:15], s[42:43] op_sel_hi:[0,1]
	v_pk_mul_f32 v[160:161], v[166:167], v[36:37] op_sel:[1,1] op_sel_hi:[0,1] neg_lo:[1,0]
	v_pk_fma_f32 v[14:15], v[14:15], s[64:65], v[30:31] op_sel:[1,0,0]
	v_pk_add_f32 v[30:31], v[8:9], v[24:25]
	v_pk_add_f32 v[8:9], v[8:9], v[24:25] neg_lo:[0,1] neg_hi:[0,1]
	v_add_u32_e32 v0, 0x1800, v138
	v_add_u32_e32 v16, 0x3800, v138
	v_pk_fma_f32 v[36:37], v[166:167], v[36:37], v[160:161] op_sel_hi:[1,0,1]
	v_mul_f32_e32 v24, 0x3f3504f3, v9
	ds_read_b64 v[2:3], v0 offset:1080
	ds_read_b64 v[0:1], v0 offset:48
	ds_read_b64 v[18:19], v16 offset:1144
	ds_read_b64 v[16:17], v16 offset:112
	v_pk_mul_f32 v[160:161], v[158:159], v[46:47] op_sel:[1,1] op_sel_hi:[0,1] neg_lo:[1,0]
	v_pk_fma_f32 v[8:9], v[8:9], s[56:57], v[24:25] op_sel_hi:[0,1,0]
	v_pk_add_f32 v[24:25], v[10:11], v[26:27]
	v_pk_add_f32 v[10:11], v[10:11], v[26:27] neg_lo:[0,1] neg_hi:[0,1]
	v_pk_fma_f32 v[46:47], v[158:159], v[46:47], v[160:161] op_sel_hi:[1,0,1]
	v_pk_mul_f32 v[26:27], v[10:11], s[66:67] op_sel_hi:[0,1]
	v_pk_mul_f32 v[158:159], v[150:151], v[48:49] op_sel:[1,1] op_sel_hi:[0,1] neg_lo:[1,0]
	v_pk_fma_f32 v[10:11], v[10:11], s[44:45], v[26:27] op_sel:[1,0,0]
	v_pk_add_f32 v[26:27], v[4:5], v[20:21]
	v_pk_add_f32 v[4:5], v[4:5], v[20:21] neg_lo:[0,1] neg_hi:[0,1]
	v_pk_mul_f32 v[142:143], v[172:173], v[162:163] op_sel:[1,1] op_sel_hi:[1,0] neg_lo:[0,1]
	v_pk_fma_f32 v[48:49], v[150:151], v[48:49], v[158:159] op_sel_hi:[1,0,1]
	v_xor_b32_e32 v21, 0x80000000, v4
	v_mov_b32_e32 v20, v5
	v_pk_add_f32 v[4:5], v[6:7], v[22:23]
	v_pk_add_f32 v[6:7], v[6:7], v[22:23] neg_lo:[0,1] neg_hi:[0,1]
	v_pk_fma_f32 v[142:143], v[162:163], v[172:173], v[142:143] op_sel_hi:[1,0,1]
	v_pk_mul_f32 v[150:151], v[140:141], v[38:39] op_sel:[1,1] op_sel_hi:[0,1] neg_lo:[1,0]
	v_pk_mul_f32 v[22:23], v[6:7], s[58:59] op_sel_hi:[0,1]
	v_pk_mul_f32 v[144:145], v[172:173], v[164:165] op_sel:[1,1] op_sel_hi:[1,0] neg_lo:[0,1]
	v_pk_fma_f32 v[38:39], v[140:141], v[38:39], v[150:151] op_sel_hi:[1,0,1]
	v_pk_fma_f32 v[6:7], v[6:7], s[42:43], v[22:23] op_sel:[1,0,0]
	s_waitcnt lgkmcnt(0)
	ds_write_b64 v136, v[34:35]
	ds_write_b64 v136, v[50:51] offset:8256
	ds_write_b64 v136, v[148:149] offset:4128
	ds_write_b64 v136, v[38:39] offset:12384
	ds_write_b64 v136, v[54:55] offset:2064
	ds_write_b64 v136, v[46:47] offset:10320
	ds_write_b64 v136, v[154:155] offset:6192
	ds_write_b64 v136, v[44:45] offset:1032
	ds_write_b64 v136, v[36:37] offset:9288
	ds_write_b64 v136, v[48:49] offset:11352
	v_pk_add_f32 v[22:23], v[0:1], v[16:17]
	v_pk_add_f32 v[0:1], v[0:1], v[16:17] neg_lo:[0,1] neg_hi:[0,1]
	v_pk_fma_f32 v[144:145], v[164:165], v[172:173], v[144:145] op_sel_hi:[1,0,1]
	v_pk_mul_f32 v[140:141], v[142:143], v[52:53] op_sel:[1,1] op_sel_hi:[0,1] neg_lo:[1,0]
	v_cvt_f32_i32_e32 v137, v216
	v_mul_f32_e32 v16, 0xbf3504f3, v0
	v_pk_mul_f32 v[146:147], v[172:173], v[170:171] op_sel:[1,1] op_sel_hi:[1,0] neg_lo:[0,1]
	v_pk_fma_f32 v[52:53], v[142:143], v[52:53], v[140:141] op_sel_hi:[1,0,1]
	v_pk_fma_f32 v[0:1], v[0:1], s[56:57], v[16:17] op_sel:[1,0,0] op_sel_hi:[1,1,0]
	ds_write_b64 v136, v[52:53] offset:13416
	v_pk_add_f32 v[16:17], v[2:3], v[18:19]
	v_pk_add_f32 v[2:3], v[2:3], v[18:19] neg_lo:[0,1] neg_hi:[0,1]
	v_pk_fma_f32 v[146:147], v[170:171], v[172:173], v[146:147] op_sel_hi:[1,0,1]
	v_pk_mul_f32 v[140:141], v[144:145], v[40:41] op_sel:[1,1] op_sel_hi:[0,1] neg_lo:[1,0]
	v_pk_mul_f32 v[18:19], v[2:3], s[40:41] op_sel_hi:[0,1]
	v_pk_fma_f32 v[40:41], v[144:145], v[40:41], v[140:141] op_sel_hi:[1,0,1]
	v_pk_fma_f32 v[2:3], v[2:3], s[66:67], v[18:19] op_sel:[1,0,0]
	ds_write_b64 v136, v[40:41] offset:14448
	v_pk_add_f32 v[18:19], v[194:195], v[26:27]
	v_pk_add_f32 v[26:27], v[194:195], v[26:27] neg_lo:[0,1] neg_hi:[0,1]
	v_pk_add_f32 v[194:195], v[28:29], v[4:5]
	v_pk_add_f32 v[4:5], v[28:29], v[4:5] neg_lo:[0,1] neg_hi:[0,1]
	v_pk_mul_f32 v[140:141], v[146:147], v[42:43] op_sel:[1,1] op_sel_hi:[0,1] neg_lo:[1,0]
	v_mul_f32_e32 v137, 0x3a000000, v137
	v_mul_f32_e32 v28, 0x3f3504f3, v5
	v_pk_fma_f32 v[42:43], v[146:147], v[42:43], v[140:141] op_sel_hi:[1,0,1]
	v_cos_f32_e32 v140, v137
	ds_write_b64 v136, v[42:43] offset:15480
	v_pk_fma_f32 v[4:5], v[4:5], s[56:57], v[28:29] op_sel_hi:[0,1,0]
	v_pk_add_f32 v[28:29], v[30:31], v[22:23]
	v_pk_add_f32 v[22:23], v[30:31], v[22:23] neg_lo:[0,1] neg_hi:[0,1]
	v_sin_f32_e32 v142, v137
	v_xor_b32_e32 v31, 0x80000000, v22
	v_mov_b32_e32 v30, v23
	v_pk_add_f32 v[22:23], v[24:25], v[16:17]
	v_pk_add_f32 v[16:17], v[24:25], v[16:17] neg_lo:[0,1] neg_hi:[0,1]
	v_mov_b32_e32 v143, v140
	v_mul_f32_e32 v24, 0xbf3504f3, v16
	v_pk_fma_f32 v[16:17], v[16:17], s[56:57], v[24:25] op_sel:[1,0,0] op_sel_hi:[1,1,0]
	v_pk_add_f32 v[24:25], v[12:13], v[20:21]
	v_pk_add_f32 v[12:13], v[12:13], v[20:21] neg_lo:[0,1] neg_hi:[0,1]
	v_pk_add_f32 v[20:21], v[14:15], v[6:7]
	v_pk_add_f32 v[6:7], v[14:15], v[6:7] neg_lo:[0,1] neg_hi:[0,1]
	v_xor_b32_e32 v141, 0x80000000, v142
	v_mul_f32_e32 v14, 0x3f3504f3, v7
	v_pk_mul_f32 v[144:145], v[142:143], v[142:143] op_sel_hi:[1,0] neg_lo:[0,1] neg_hi:[0,1]
	v_pk_fma_f32 v[6:7], v[6:7], s[56:57], v[14:15] op_sel_hi:[0,1,0]
	v_pk_add_f32 v[14:15], v[8:9], v[0:1]
	v_pk_add_f32 v[0:1], v[8:9], v[0:1] neg_lo:[0,1] neg_hi:[0,1]
	v_pk_fma_f32 v[144:145], v[140:141], v[140:141], v[144:145] op_sel_hi:[1,0,1]
	v_xor_b32_e32 v9, 0x80000000, v0
	v_mov_b32_e32 v8, v1
	v_pk_add_f32 v[0:1], v[10:11], v[2:3]
	v_pk_add_f32 v[2:3], v[10:11], v[2:3] neg_lo:[0,1] neg_hi:[0,1]
	v_xor_b32_e32 v150, 0x80000000, v145
	v_mov_b32_e32 v151, v144
	v_mul_f32_e32 v10, 0xbf3504f3, v2
	v_pk_mul_f32 v[32:33], v[156:157], v[186:187] op_sel:[1,1] op_sel_hi:[0,1] neg_lo:[1,0]
	v_pk_mul_f32 v[158:159], v[144:145], v[150:151] op_sel:[1,0]
	v_pk_fma_f32 v[2:3], v[2:3], s[56:57], v[10:11] op_sel:[1,0,0] op_sel_hi:[1,1,0]
	v_pk_add_f32 v[10:11], v[18:19], v[28:29]
	v_pk_add_f32 v[18:19], v[18:19], v[28:29] neg_lo:[0,1] neg_hi:[0,1]
	v_pk_add_f32 v[28:29], v[194:195], v[22:23]
	v_pk_add_f32 v[22:23], v[194:195], v[22:23] neg_lo:[0,1] neg_hi:[0,1]
	v_pk_fma_f32 v[32:33], v[156:157], v[186:187], v[32:33] op_sel_hi:[1,0,1]
	v_pk_mul_f32 v[156:157], v[170:171], v[218:219] op_sel:[1,1] op_sel_hi:[0,1] neg_lo:[1,0]
	ds_write_b64 v136, v[32:33] offset:3096
	v_pk_fma_f32 v[158:159], v[144:145], v[144:145], v[158:159] op_sel_hi:[1,0,1]
	v_xor_b32_e32 v195, 0x80000000, v22
	v_mov_b32_e32 v194, v23
	v_pk_add_f32 v[22:23], v[26:27], v[30:31]
	v_pk_add_f32 v[26:27], v[26:27], v[30:31] neg_lo:[0,1] neg_hi:[0,1]
	v_pk_add_f32 v[30:31], v[4:5], v[16:17]
	v_pk_add_f32 v[4:5], v[4:5], v[16:17] neg_lo:[0,1] neg_hi:[0,1]
	v_pk_fma_f32 v[156:157], v[170:171], v[218:219], v[156:157] op_sel_hi:[1,0,1]
	v_xor_b32_e32 v170, 0x80000000, v159
	ds_write_b64 v136, v[156:157] offset:7224
	v_mov_b32_e32 v171, v158
	v_xor_b32_e32 v17, 0x80000000, v4
	v_mov_b32_e32 v16, v5
	v_pk_add_f32 v[4:5], v[24:25], v[14:15]
	v_pk_add_f32 v[14:15], v[24:25], v[14:15] neg_lo:[0,1] neg_hi:[0,1]
	v_pk_add_f32 v[24:25], v[20:21], v[0:1]
	v_pk_add_f32 v[0:1], v[20:21], v[0:1] neg_lo:[0,1] neg_hi:[0,1]
	v_pk_mul_f32 v[146:147], v[142:143], v[144:145] op_sel:[0,1]
	v_pk_mul_f32 v[172:173], v[158:159], v[170:171] op_sel:[1,0]
	v_xor_b32_e32 v21, 0x80000000, v0
	v_mov_b32_e32 v20, v1
	v_pk_add_f32 v[0:1], v[12:13], v[8:9]
	v_pk_add_f32 v[8:9], v[12:13], v[8:9] neg_lo:[0,1] neg_hi:[0,1]
	v_pk_add_f32 v[12:13], v[6:7], v[2:3]
	v_pk_add_f32 v[2:3], v[6:7], v[2:3] neg_lo:[0,1] neg_hi:[0,1]
	v_pk_fma_f32 v[146:147], v[140:141], v[144:145], v[146:147] op_sel_hi:[1,0,1]
	v_pk_fma_f32 v[172:173], v[158:159], v[158:159], v[172:173] op_sel_hi:[1,0,1]
	v_xor_b32_e32 v7, 0x80000000, v2
	v_mov_b32_e32 v6, v3
	v_pk_add_f32 v[2:3], v[10:11], v[28:29]
	v_pk_add_f32 v[10:11], v[10:11], v[28:29] neg_lo:[0,1] neg_hi:[0,1]
	ds_write_b64 v138, v[2:3]
	v_pk_add_f32 v[28:29], v[18:19], v[194:195]
	v_pk_add_f32 v[18:19], v[18:19], v[194:195] neg_lo:[0,1] neg_hi:[0,1]
	v_pk_add_f32 v[194:195], v[22:23], v[30:31]
	v_pk_add_f32 v[22:23], v[22:23], v[30:31] neg_lo:[0,1] neg_hi:[0,1]
	v_pk_add_f32 v[30:31], v[26:27], v[16:17]
	v_pk_add_f32 v[16:17], v[26:27], v[16:17] neg_lo:[0,1] neg_hi:[0,1]
	v_pk_add_f32 v[26:27], v[4:5], v[24:25]
	v_pk_mul_f32 v[152:153], v[162:163], v[192:193] op_sel:[1,1] op_sel_hi:[0,1] neg_lo:[1,0]
	v_pk_mul_f32 v[160:161], v[142:143], v[158:159] op_sel:[0,1]
	v_xor_b32_e32 v164, 0x80000000, v147
	v_mov_b32_e32 v165, v146
	v_pk_mul_f32 v[174:175], v[142:143], v[172:173] op_sel:[0,1]
	v_pk_add_f32 v[4:5], v[4:5], v[24:25] neg_lo:[0,1] neg_hi:[0,1]
	v_pk_add_f32 v[24:25], v[14:15], v[20:21]
	v_pk_add_f32 v[14:15], v[14:15], v[20:21] neg_lo:[0,1] neg_hi:[0,1]
	v_pk_add_f32 v[20:21], v[0:1], v[12:13]
	v_pk_add_f32 v[0:1], v[0:1], v[12:13] neg_lo:[0,1] neg_hi:[0,1]
	v_pk_add_f32 v[12:13], v[8:9], v[6:7]
	v_pk_add_f32 v[6:7], v[8:9], v[6:7] neg_lo:[0,1] neg_hi:[0,1]
	v_pk_mul_f32 v[8:9], v[142:143], v[26:27] op_sel:[0,1]
	v_pk_fma_f32 v[152:153], v[162:163], v[192:193], v[152:153] op_sel_hi:[1,0,1]
	v_pk_fma_f32 v[160:161], v[140:141], v[158:159], v[160:161] op_sel_hi:[1,0,1]
	ds_write_b64 v136, v[152:153] offset:5160
	v_pk_mul_f32 v[162:163], v[150:151], v[158:159] op_sel:[0,1]
	v_pk_fma_f32 v[174:175], v[140:141], v[172:173], v[174:175] op_sel_hi:[1,0,1]
	v_pk_fma_f32 v[8:9], v[140:141], v[26:27], v[8:9] op_sel_hi:[1,0,1]
	v_pk_mul_f32 v[140:141], v[164:165], v[20:21] op_sel:[0,1]
	ds_write_b64 v138, v[8:9] offset:1032
	v_pk_fma_f32 v[162:163], v[144:145], v[158:159], v[162:163] op_sel_hi:[1,0,1]
	v_pk_mul_f32 v[166:167], v[158:159], v[164:165] op_sel:[1,0]
	v_xor_b32_e32 v182, 0x80000000, v161
	v_mov_b32_e32 v183, v160
	v_pk_fma_f32 v[20:21], v[146:147], v[20:21], v[140:141] op_sel_hi:[1,0,1]
	v_pk_mul_f32 v[140:141], v[170:171], v[28:29] op_sel:[0,1]
	ds_write_b64 v138, v[20:21] offset:3096
	v_pk_fma_f32 v[166:167], v[146:147], v[158:159], v[166:167] op_sel_hi:[1,0,1]
	v_xor_b32_e32 v186, 0x80000000, v163
	v_mov_b32_e32 v187, v162
	v_pk_fma_f32 v[28:29], v[158:159], v[28:29], v[140:141] op_sel_hi:[1,0,1]
	v_pk_mul_f32 v[140:141], v[182:183], v[24:25] op_sel:[0,1]
	ds_write_b64 v138, v[28:29] offset:4128
	v_xor_b32_e32 v190, 0x80000000, v167
	v_mov_b32_e32 v191, v166
	v_pk_fma_f32 v[24:25], v[160:161], v[24:25], v[140:141] op_sel_hi:[1,0,1]
	v_pk_mul_f32 v[140:141], v[186:187], v[30:31] op_sel:[0,1]
	ds_write_b64 v138, v[24:25] offset:5160
	v_pk_mul_f32 v[176:177], v[150:151], v[172:173] op_sel:[0,1]
	v_pk_fma_f32 v[30:31], v[162:163], v[30:31], v[140:141] op_sel_hi:[1,0,1]
	v_pk_mul_f32 v[140:141], v[190:191], v[12:13] op_sel:[0,1]
	ds_write_b64 v138, v[30:31] offset:6192
	v_pk_fma_f32 v[176:177], v[144:145], v[172:173], v[176:177] op_sel_hi:[1,0,1]
	v_pk_fma_f32 v[12:13], v[166:167], v[12:13], v[140:141] op_sel_hi:[1,0,1]
	v_pk_mul_f32 v[140:141], v[172:173], v[10:11] op_sel:[1,1] op_sel_hi:[0,1] neg_lo:[1,0]
	ds_write_b64 v138, v[12:13] offset:7224
	v_pk_mul_f32 v[178:179], v[164:165], v[172:173] op_sel:[0,1]
	v_pk_fma_f32 v[10:11], v[172:173], v[10:11], v[140:141] op_sel_hi:[1,0,1]
	v_pk_mul_f32 v[140:141], v[174:175], v[4:5] op_sel:[1,1] op_sel_hi:[0,1] neg_lo:[1,0]
	ds_write_b64 v138, v[10:11] offset:8256
	v_pk_fma_f32 v[178:179], v[146:147], v[172:173], v[178:179] op_sel_hi:[1,0,1]
	v_pk_fma_f32 v[4:5], v[174:175], v[4:5], v[140:141] op_sel_hi:[1,0,1]
	v_pk_mul_f32 v[140:141], v[176:177], v[22:23] op_sel:[1,1] op_sel_hi:[0,1] neg_lo:[1,0]
	ds_write_b64 v138, v[4:5] offset:9288
	v_pk_mul_f32 v[180:181], v[170:171], v[172:173] op_sel:[0,1]
	v_pk_fma_f32 v[22:23], v[176:177], v[22:23], v[140:141] op_sel_hi:[1,0,1]
	v_pk_fma_f32 v[180:181], v[158:159], v[172:173], v[180:181] op_sel_hi:[1,0,1]
	ds_write_b64 v138, v[22:23] offset:10320
	v_pk_mul_f32 v[140:141], v[178:179], v[0:1] op_sel:[1,1] op_sel_hi:[0,1] neg_lo:[1,0]
	v_pk_mul_f32 v[184:185], v[172:173], v[182:183] op_sel:[1,0]
	v_pk_fma_f32 v[0:1], v[178:179], v[0:1], v[140:141] op_sel_hi:[1,0,1]
	v_pk_fma_f32 v[184:185], v[160:161], v[172:173], v[184:185] op_sel_hi:[1,0,1]
	ds_write_b64 v138, v[0:1] offset:11352
	v_pk_mul_f32 v[140:141], v[180:181], v[18:19] op_sel:[1,1] op_sel_hi:[0,1] neg_lo:[1,0]
	v_pk_mul_f32 v[188:189], v[172:173], v[186:187] op_sel:[1,0]
	v_pk_fma_f32 v[18:19], v[180:181], v[18:19], v[140:141] op_sel_hi:[1,0,1]
	v_pk_fma_f32 v[188:189], v[162:163], v[172:173], v[188:189] op_sel_hi:[1,0,1]
	ds_write_b64 v138, v[18:19] offset:12384
	v_pk_mul_f32 v[140:141], v[184:185], v[14:15] op_sel:[1,1] op_sel_hi:[0,1] neg_lo:[1,0]
	v_pk_mul_f32 v[192:193], v[172:173], v[190:191] op_sel:[1,0]
	v_pk_fma_f32 v[14:15], v[184:185], v[14:15], v[140:141] op_sel_hi:[1,0,1]
	v_pk_fma_f32 v[192:193], v[166:167], v[172:173], v[192:193] op_sel_hi:[1,0,1]
	ds_write_b64 v138, v[14:15] offset:13416
	v_pk_mul_f32 v[140:141], v[188:189], v[16:17] op_sel:[1,1] op_sel_hi:[0,1] neg_lo:[1,0]
	v_cmp_lt_i32_e32 vcc, -1, v66
	v_pk_fma_f32 v[16:17], v[188:189], v[16:17], v[140:141] op_sel_hi:[1,0,1]
	v_pk_mul_f32 v[26:27], v[150:151], v[194:195] op_sel:[0,1]
	ds_write_b64 v138, v[16:17] offset:14448
	v_pk_mul_f32 v[140:141], v[192:193], v[6:7] op_sel:[1,1] op_sel_hi:[0,1] neg_lo:[1,0]
	v_add_u32_e32 v66, 0x400, v66
	s_or_b64 s[92:93], vcc, s[92:93]
	v_pk_fma_f32 v[26:27], v[144:145], v[194:195], v[26:27] op_sel_hi:[1,0,1]
	v_pk_fma_f32 v[6:7], v[192:193], v[6:7], v[140:141] op_sel_hi:[1,0,1]
	ds_write_b64 v138, v[26:27] offset:2064
	ds_write_b64 v138, v[6:7] offset:15480
	s_andn2_b64 exec, exec, s[92:93]
	s_cbranch_execnz .LBB0_347

.LBB0_350:
	v_ashrrev_i32_e32 v1, 7, v0
	v_mov_b32_e32 v34, v1
	v_add_u32_e32 v2, 0x200, v0
	v_cvt_f32_i32_e32 v34, v34
	v_ashrrev_i32_e32 v2, 7, v2
	v_mov_b32_e32 v66, v2
	v_lshl_add_u32 v1, v1, 3, v196
	v_mul_f32_e32 v35, 0x3c000000, v34
	v_lshl_add_u32 v136, v2, 3, v196
	ds_read_b64 v[2:3], v1
	ds_read_b64 v[4:5], v1 offset:128
	ds_read_b64 v[6:7], v136
	ds_read_b64 v[8:9], v136 offset:128
	ds_read_b64 v[10:11], v1 offset:256
	ds_read_b64 v[12:13], v1 offset:384
	ds_read_b64 v[14:15], v136 offset:256
	ds_read_b64 v[16:17], v136 offset:384
	ds_read_b64 v[18:19], v1 offset:512
	ds_read_b64 v[20:21], v1 offset:640
	ds_read_b64 v[22:23], v136 offset:512
	ds_read_b64 v[24:25], v136 offset:640
	ds_read_b64 v[26:27], v1 offset:768
	ds_read_b64 v[28:29], v1 offset:896
	ds_read_b64 v[30:31], v136 offset:768
	ds_read_b64 v[32:33], v136 offset:896
	v_cos_f32_e32 v34, v35
	v_sin_f32_e32 v36, v35
	s_waitcnt lgkmcnt(6)
	v_pk_add_f32 v[54:55], v[2:3], v[18:19]
	v_pk_add_f32 v[2:3], v[2:3], v[18:19] neg_lo:[0,1] neg_hi:[0,1]
	v_pk_add_f32 v[18:19], v[4:5], v[20:21]
	v_pk_add_f32 v[4:5], v[4:5], v[20:21] neg_lo:[0,1] neg_hi:[0,1]
	v_mov_b32_e32 v37, v34
	v_mul_f32_e32 v20, 0x3f3504f3, v5
	v_pk_fma_f32 v[4:5], v[4:5], s[56:57], v[20:21] op_sel_hi:[0,1,0]
	s_waitcnt lgkmcnt(2)
	v_pk_add_f32 v[20:21], v[10:11], v[26:27]
	v_pk_add_f32 v[10:11], v[10:11], v[26:27] neg_lo:[0,1] neg_hi:[0,1]
	v_xor_b32_e32 v35, 0x80000000, v36
	v_pk_mul_f32 v[38:39], v[36:37], v[36:37] op_sel_hi:[1,0] neg_lo:[0,1] neg_hi:[0,1]
	v_xor_b32_e32 v27, 0x80000000, v10
	v_mov_b32_e32 v26, v11
	v_pk_add_f32 v[10:11], v[12:13], v[28:29]
	v_pk_add_f32 v[12:13], v[12:13], v[28:29] neg_lo:[0,1] neg_hi:[0,1]
	v_pk_fma_f32 v[38:39], v[34:35], v[34:35], v[38:39] op_sel_hi:[1,0,1]
	v_mul_f32_e32 v28, 0xbf3504f3, v12
	v_pk_fma_f32 v[12:13], v[12:13], s[56:57], v[28:29] op_sel:[1,0,0] op_sel_hi:[1,1,0]
	v_pk_add_f32 v[28:29], v[54:55], v[20:21]
	v_pk_add_f32 v[20:21], v[54:55], v[20:21] neg_lo:[0,1] neg_hi:[0,1]
	v_pk_add_f32 v[54:55], v[18:19], v[10:11]
	v_pk_add_f32 v[10:11], v[18:19], v[10:11] neg_lo:[0,1] neg_hi:[0,1]
	v_pk_mul_f32 v[40:41], v[36:37], v[38:39] op_sel:[0,1]
	v_pk_mul_f32 v[44:45], v[38:39], v[38:39] op_sel:[1,1] op_sel_hi:[1,0] neg_lo:[0,1]
	v_xor_b32_e32 v19, 0x80000000, v10
	v_mov_b32_e32 v18, v11
	v_pk_add_f32 v[10:11], v[2:3], v[26:27]
	v_pk_add_f32 v[2:3], v[2:3], v[26:27] neg_lo:[0,1] neg_hi:[0,1]
	v_pk_add_f32 v[26:27], v[4:5], v[12:13]
	v_pk_add_f32 v[4:5], v[4:5], v[12:13] neg_lo:[0,1] neg_hi:[0,1]
	v_pk_fma_f32 v[40:41], v[34:35], v[38:39], v[40:41] op_sel_hi:[1,0,1]
	v_pk_fma_f32 v[44:45], v[38:39], v[38:39], v[44:45] op_sel_hi:[1,0,1]
	v_xor_b32_e32 v13, 0x80000000, v4
	v_mov_b32_e32 v12, v5
	v_pk_add_f32 v[4:5], v[28:29], v[54:55]
	v_pk_add_f32 v[28:29], v[28:29], v[54:55] neg_lo:[0,1] neg_hi:[0,1]
	v_pk_add_f32 v[54:55], v[20:21], v[18:19]
	v_pk_add_f32 v[18:19], v[20:21], v[18:19] neg_lo:[0,1] neg_hi:[0,1]
	v_pk_add_f32 v[20:21], v[10:11], v[26:27]
	v_pk_mul_f32 v[46:47], v[36:37], v[44:45] op_sel:[0,1]
	v_pk_add_f32 v[10:11], v[10:11], v[26:27] neg_lo:[0,1] neg_hi:[0,1]
	v_pk_add_f32 v[26:27], v[2:3], v[12:13]
	v_pk_add_f32 v[2:3], v[2:3], v[12:13] neg_lo:[0,1] neg_hi:[0,1]
	v_pk_mul_f32 v[12:13], v[36:37], v[20:21] op_sel:[0,1]
	v_pk_fma_f32 v[46:47], v[34:35], v[44:45], v[46:47] op_sel_hi:[1,0,1]
	v_pk_fma_f32 v[12:13], v[34:35], v[20:21], v[12:13] op_sel_hi:[1,0,1]
	v_pk_mul_f32 v[34:35], v[40:41], v[26:27] op_sel:[1,1] op_sel_hi:[0,1] neg_lo:[1,0]
	v_pk_mul_f32 v[48:49], v[38:39], v[44:45] op_sel:[1,1] op_sel_hi:[0,1] neg_lo:[1,0]
	v_pk_fma_f32 v[26:27], v[40:41], v[26:27], v[34:35] op_sel_hi:[1,0,1]
	v_pk_mul_f32 v[34:35], v[44:45], v[28:29] op_sel:[1,1] op_sel_hi:[0,1] neg_lo:[1,0]
	v_pk_fma_f32 v[48:49], v[38:39], v[44:45], v[48:49] op_sel_hi:[1,0,1]
	v_pk_fma_f32 v[28:29], v[44:45], v[28:29], v[34:35] op_sel_hi:[1,0,1]
	v_pk_mul_f32 v[34:35], v[46:47], v[10:11] op_sel:[1,1] op_sel_hi:[0,1] neg_lo:[1,0]
	v_pk_mul_f32 v[52:53], v[44:45], v[40:41] op_sel:[1,1] op_sel_hi:[1,0] neg_lo:[0,1]
	v_pk_fma_f32 v[10:11], v[46:47], v[10:11], v[34:35] op_sel_hi:[1,0,1]
	v_pk_fma_f32 v[52:53], v[40:41], v[44:45], v[52:53] op_sel_hi:[1,0,1]
	v_pk_mul_f32 v[34:35], v[48:49], v[18:19] op_sel:[1,1] op_sel_hi:[0,1] neg_lo:[1,0]
	v_pk_mul_f32 v[20:21], v[38:39], v[54:55] op_sel:[1,1] op_sel_hi:[0,1] neg_lo:[1,0]
	v_pk_fma_f32 v[18:19], v[48:49], v[18:19], v[34:35] op_sel_hi:[1,0,1]
	v_pk_mul_f32 v[34:35], v[52:53], v[2:3] op_sel:[1,1] op_sel_hi:[0,1] neg_lo:[1,0]
	v_pk_fma_f32 v[20:21], v[38:39], v[54:55], v[20:21] op_sel_hi:[1,0,1]
	v_pk_fma_f32 v[2:3], v[52:53], v[2:3], v[34:35] op_sel_hi:[1,0,1]
	v_cvt_f32_i32_e32 v34, v66
	v_pk_add_f32 v[54:55], v[6:7], v[22:23]
	v_pk_add_f32 v[6:7], v[6:7], v[22:23] neg_lo:[0,1] neg_hi:[0,1]
	v_pk_add_f32 v[22:23], v[8:9], v[24:25]
	v_mul_f32_e32 v35, 0x3c000000, v34
	v_cos_f32_e32 v34, v35
	v_sin_f32_e32 v36, v35
	v_pk_add_f32 v[8:9], v[8:9], v[24:25] neg_lo:[0,1] neg_hi:[0,1]
	v_cmp_lt_i32_e32 vcc, s28, v0
	v_mul_f32_e32 v24, 0x3f3504f3, v9
	v_mov_b32_e32 v37, v34
	v_pk_fma_f32 v[8:9], v[8:9], s[56:57], v[24:25] op_sel_hi:[0,1,0]
	s_waitcnt lgkmcnt(0)
	ds_write_b64 v1, v[4:5]
	ds_write_b64 v1, v[28:29] offset:512
	ds_write_b64 v1, v[20:21] offset:256
	ds_write_b64 v1, v[18:19] offset:768
	ds_write_b64 v1, v[12:13] offset:128
	ds_write_b64 v1, v[10:11] offset:640
	ds_write_b64 v1, v[26:27] offset:384
	ds_write_b64 v1, v[2:3] offset:896
	v_pk_add_f32 v[24:25], v[14:15], v[30:31]
	v_pk_add_f32 v[14:15], v[14:15], v[30:31] neg_lo:[0,1] neg_hi:[0,1]
	v_xor_b32_e32 v35, 0x80000000, v36
	v_pk_mul_f32 v[38:39], v[36:37], v[36:37] op_sel_hi:[1,0] neg_lo:[0,1] neg_hi:[0,1]
	v_xor_b32_e32 v31, 0x80000000, v14
	v_mov_b32_e32 v30, v15
	v_pk_add_f32 v[14:15], v[16:17], v[32:33]
	v_pk_add_f32 v[16:17], v[16:17], v[32:33] neg_lo:[0,1] neg_hi:[0,1]
	v_pk_fma_f32 v[38:39], v[34:35], v[34:35], v[38:39] op_sel_hi:[1,0,1]
	v_mul_f32_e32 v32, 0xbf3504f3, v16
	v_xor_b32_e32 v42, 0x80000000, v39
	v_mov_b32_e32 v43, v38
	v_pk_fma_f32 v[16:17], v[16:17], s[56:57], v[32:33] op_sel:[1,0,0] op_sel_hi:[1,1,0]
	v_pk_add_f32 v[32:33], v[54:55], v[24:25]
	v_pk_add_f32 v[24:25], v[54:55], v[24:25] neg_lo:[0,1] neg_hi:[0,1]
	v_pk_add_f32 v[54:55], v[22:23], v[14:15]
	v_pk_add_f32 v[14:15], v[22:23], v[14:15] neg_lo:[0,1] neg_hi:[0,1]
	v_pk_mul_f32 v[40:41], v[36:37], v[38:39] op_sel:[0,1]
	v_pk_mul_f32 v[44:45], v[38:39], v[42:43] op_sel:[1,0]
	v_xor_b32_e32 v23, 0x80000000, v14
	v_mov_b32_e32 v22, v15
	v_pk_add_f32 v[14:15], v[6:7], v[30:31]
	v_pk_add_f32 v[6:7], v[6:7], v[30:31] neg_lo:[0,1] neg_hi:[0,1]
	v_pk_add_f32 v[30:31], v[8:9], v[16:17]
	v_pk_add_f32 v[8:9], v[8:9], v[16:17] neg_lo:[0,1] neg_hi:[0,1]
	v_pk_fma_f32 v[40:41], v[34:35], v[38:39], v[40:41] op_sel_hi:[1,0,1]
	v_pk_fma_f32 v[44:45], v[38:39], v[38:39], v[44:45] op_sel_hi:[1,0,1]
	v_xor_b32_e32 v17, 0x80000000, v8
	v_mov_b32_e32 v16, v9
	v_pk_add_f32 v[8:9], v[32:33], v[54:55]
	v_pk_add_f32 v[32:33], v[32:33], v[54:55] neg_lo:[0,1] neg_hi:[0,1]
	ds_write_b64 v136, v[8:9]
	v_pk_add_f32 v[54:55], v[24:25], v[22:23]
	v_pk_add_f32 v[22:23], v[24:25], v[22:23] neg_lo:[0,1] neg_hi:[0,1]
	v_pk_add_f32 v[24:25], v[14:15], v[30:31]
	v_pk_mul_f32 v[46:47], v[36:37], v[44:45] op_sel:[0,1]
	v_xor_b32_e32 v50, 0x80000000, v41
	v_mov_b32_e32 v51, v40
	v_pk_add_f32 v[14:15], v[14:15], v[30:31] neg_lo:[0,1] neg_hi:[0,1]
	v_pk_add_f32 v[30:31], v[6:7], v[16:17]
	v_pk_add_f32 v[6:7], v[6:7], v[16:17] neg_lo:[0,1] neg_hi:[0,1]
	v_pk_mul_f32 v[16:17], v[36:37], v[24:25] op_sel:[0,1]
	v_pk_fma_f32 v[46:47], v[34:35], v[44:45], v[46:47] op_sel_hi:[1,0,1]
	v_pk_fma_f32 v[16:17], v[34:35], v[24:25], v[16:17] op_sel_hi:[1,0,1]
	v_pk_mul_f32 v[34:35], v[50:51], v[30:31] op_sel:[0,1]
	ds_write_b64 v136, v[16:17] offset:128
	v_pk_mul_f32 v[48:49], v[42:43], v[44:45] op_sel:[0,1]
	v_pk_fma_f32 v[30:31], v[40:41], v[30:31], v[34:35] op_sel_hi:[1,0,1]
	v_pk_mul_f32 v[34:35], v[44:45], v[32:33] op_sel:[1,1] op_sel_hi:[0,1] neg_lo:[1,0]
	ds_write_b64 v136, v[30:31] offset:384
	v_pk_fma_f32 v[48:49], v[38:39], v[44:45], v[48:49] op_sel_hi:[1,0,1]
	v_pk_fma_f32 v[32:33], v[44:45], v[32:33], v[34:35] op_sel_hi:[1,0,1]
	v_pk_mul_f32 v[34:35], v[46:47], v[14:15] op_sel:[1,1] op_sel_hi:[0,1] neg_lo:[1,0]
	ds_write_b64 v136, v[32:33] offset:512
	v_pk_mul_f32 v[52:53], v[44:45], v[50:51] op_sel:[1,0]
	v_pk_fma_f32 v[14:15], v[46:47], v[14:15], v[34:35] op_sel_hi:[1,0,1]
	v_pk_fma_f32 v[52:53], v[40:41], v[44:45], v[52:53] op_sel_hi:[1,0,1]
	ds_write_b64 v136, v[14:15] offset:640
	v_pk_mul_f32 v[34:35], v[48:49], v[22:23] op_sel:[1,1] op_sel_hi:[0,1] neg_lo:[1,0]
	v_pk_mul_f32 v[24:25], v[42:43], v[54:55] op_sel:[0,1]
	v_pk_fma_f32 v[22:23], v[48:49], v[22:23], v[34:35] op_sel_hi:[1,0,1]
	v_pk_mul_f32 v[34:35], v[52:53], v[6:7] op_sel:[1,1] op_sel_hi:[0,1] neg_lo:[1,0]
	ds_write_b64 v136, v[22:23] offset:768
	v_add_u32_e32 v0, 0x400, v0
	s_or_b64 s[92:93], vcc, s[92:93]
	v_pk_fma_f32 v[24:25], v[38:39], v[54:55], v[24:25] op_sel_hi:[1,0,1]
	v_pk_fma_f32 v[6:7], v[52:53], v[6:7], v[34:35] op_sel_hi:[1,0,1]
	ds_write_b64 v136, v[24:25] offset:256
	ds_write_b64 v136, v[6:7] offset:896
	s_andn2_b64 exec, exec, s[92:93]
	s_cbranch_execnz .LBB0_350

.LBB0_353:
	v_ashrrev_i32_e32 v0, 3, v42
	v_add_u32_e32 v1, 0x200, v42
	v_and_b32_e32 v0, -16, v0
	v_ashrrev_i32_e32 v1, 3, v1
	v_and_b32_e32 v1, -16, v1
	v_lshl_add_u32 v43, v0, 3, v196
	v_add_u32_e32 v32, v0, v197
	v_add_u32_e32 v34, v1, v197
	v_lshl_add_u32 v44, v1, 3, v196
	ds_read_b64 v[46:47], v43
	ds_read_b64 v[48:49], v43 offset:8
	ds_read_b64 v[20:21], v44
	ds_read_b64 v[22:23], v44 offset:8
	ds_read_b64 v[50:51], v43 offset:16
	ds_read_b64 v[52:53], v43 offset:24
	ds_read_b64 v[12:13], v44 offset:16
	ds_read_b64 v[14:15], v44 offset:24
	ds_read_b64 v[136:137], v43 offset:32
	ds_read_b64 v[138:139], v43 offset:40
	ds_read_b64 v[4:5], v44 offset:32
	ds_read_b64 v[6:7], v44 offset:40
	ds_read_b64 v[140:141], v43 offset:48
	ds_read_b64 v[142:143], v43 offset:56
	ds_read_b64 v[0:1], v44 offset:48
	ds_read_b64 v[2:3], v44 offset:56
	ds_read_b64 v[144:145], v43 offset:64
	ds_read_b64 v[146:147], v43 offset:72
	ds_read_b64 v[28:29], v44 offset:64
	ds_read_b64 v[30:31], v44 offset:72
	ds_read_b64 v[148:149], v43 offset:80
	ds_read_b64 v[150:151], v43 offset:88
	ds_read_b64 v[24:25], v44 offset:80
	ds_read_b64 v[26:27], v44 offset:88
	ds_read_b64 v[152:153], v43 offset:96
	ds_read_b64 v[154:155], v43 offset:104
	ds_read_b64 v[16:17], v44 offset:96
	ds_read_b64 v[18:19], v44 offset:104
	ds_read_b64 v[156:157], v43 offset:112
	ds_read_b64 v[158:159], v43 offset:120
	ds_read_b64 v[8:9], v44 offset:112
	ds_read_b64 v[10:11], v44 offset:120
	s_waitcnt lgkmcnt(14)
	v_pk_add_f32 v[38:39], v[46:47], v[144:145]
	v_pk_add_f32 v[36:37], v[46:47], v[144:145] neg_lo:[0,1] neg_hi:[0,1]
	v_pk_add_f32 v[46:47], v[48:49], v[146:147] neg_lo:[0,1] neg_hi:[0,1]
	v_pk_add_f32 v[40:41], v[48:49], v[146:147]
	v_pk_mul_f32 v[48:49], v[46:47], s[42:43] op_sel_hi:[0,1]
	s_mov_b32 s65, s42
	v_pk_fma_f32 v[46:47], v[46:47], s[64:65], v[48:49] op_sel:[1,0,0]
	s_waitcnt lgkmcnt(10)
	v_pk_add_f32 v[48:49], v[50:51], v[148:149]
	v_pk_add_f32 v[50:51], v[50:51], v[148:149] neg_lo:[0,1] neg_hi:[0,1]
	s_mov_b32 s66, s64
	v_mul_f32_e32 v54, 0x3f3504f3, v51
	v_pk_fma_f32 v[50:51], v[50:51], s[56:57], v[54:55] op_sel_hi:[0,1,0]
	v_pk_add_f32 v[54:55], v[52:53], v[150:151]
	v_pk_add_f32 v[52:53], v[52:53], v[150:151] neg_lo:[0,1] neg_hi:[0,1]
	s_mov_b32 s40, s42
	v_pk_mul_f32 v[144:145], v[52:53], s[66:67] op_sel_hi:[0,1]
	s_mov_b32 s41, s64
	v_pk_fma_f32 v[52:53], v[52:53], s[40:41], v[144:145] op_sel:[1,0,0]
	s_waitcnt lgkmcnt(6)
	v_pk_add_f32 v[144:145], v[136:137], v[152:153]
	v_pk_add_f32 v[136:137], v[136:137], v[152:153] neg_lo:[0,1] neg_hi:[0,1]
	s_mov_b32 s44, s43
	v_xor_b32_e32 v147, 0x80000000, v136
	v_mov_b32_e32 v146, v137
	v_pk_add_f32 v[136:137], v[138:139], v[154:155]
	v_pk_add_f32 v[138:139], v[138:139], v[154:155] neg_lo:[0,1] neg_hi:[0,1]
	s_mov_b32 s45, s67
	v_pk_mul_f32 v[148:149], v[138:139], s[44:45] op_sel_hi:[0,1]
	s_waitcnt lgkmcnt(2)
	v_pk_add_f32 v[150:151], v[142:143], v[158:159]
	v_pk_add_f32 v[142:143], v[142:143], v[158:159] neg_lo:[0,1] neg_hi:[0,1]
	s_mov_b32 s58, s67
	s_mov_b32 s59, s43
	v_pk_fma_f32 v[138:139], v[138:139], s[42:43], v[148:149] op_sel:[1,0,0]
	v_pk_add_f32 v[148:149], v[140:141], v[156:157]
	v_pk_add_f32 v[140:141], v[140:141], v[156:157] neg_lo:[0,1] neg_hi:[0,1]
	v_pk_mul_f32 v[152:153], v[142:143], s[58:59] op_sel_hi:[0,1]
	v_mul_f32_e32 v66, 0xbf3504f3, v140
	v_pk_fma_f32 v[142:143], v[142:143], s[66:67], v[152:153] op_sel:[1,0,0]
	v_pk_add_f32 v[152:153], v[38:39], v[144:145]
	v_pk_add_f32 v[38:39], v[38:39], v[144:145] neg_lo:[0,1] neg_hi:[0,1]
	v_pk_add_f32 v[144:145], v[40:41], v[136:137]
	v_pk_add_f32 v[40:41], v[40:41], v[136:137] neg_lo:[0,1] neg_hi:[0,1]
	v_pk_add_f32 v[136:137], v[48:49], v[148:149]
	v_pk_add_f32 v[48:49], v[48:49], v[148:149] neg_lo:[0,1] neg_hi:[0,1]
	v_pk_fma_f32 v[140:141], v[140:141], s[56:57], v[66:67] op_sel:[1,0,0] op_sel_hi:[1,1,0]
	v_mul_f32_e32 v66, 0x3f3504f3, v41
	v_xor_b32_e32 v149, 0x80000000, v48
	v_mov_b32_e32 v148, v49
	v_pk_add_f32 v[48:49], v[54:55], v[150:151]
	v_pk_add_f32 v[54:55], v[54:55], v[150:151] neg_lo:[0,1] neg_hi:[0,1]
	v_pk_fma_f32 v[40:41], v[40:41], s[56:57], v[66:67] op_sel_hi:[0,1,0]
	v_mul_f32_e32 v66, 0xbf3504f3, v54
	v_pk_add_f32 v[150:151], v[36:37], v[146:147]
	v_pk_add_f32 v[36:37], v[36:37], v[146:147] neg_lo:[0,1] neg_hi:[0,1]
	v_pk_add_f32 v[146:147], v[46:47], v[138:139]
	v_pk_add_f32 v[46:47], v[46:47], v[138:139] neg_lo:[0,1] neg_hi:[0,1]
	v_pk_add_f32 v[138:139], v[50:51], v[140:141]
	v_pk_add_f32 v[50:51], v[50:51], v[140:141] neg_lo:[0,1] neg_hi:[0,1]
	v_pk_fma_f32 v[54:55], v[54:55], s[56:57], v[66:67] op_sel:[1,0,0] op_sel_hi:[1,1,0]
	v_xor_b32_e32 v141, 0x80000000, v50
	v_mov_b32_e32 v140, v51
	v_pk_add_f32 v[50:51], v[52:53], v[142:143]
	v_pk_add_f32 v[52:53], v[52:53], v[142:143] neg_lo:[0,1] neg_hi:[0,1]
	v_pk_add_f32 v[142:143], v[152:153], v[136:137]
	v_pk_add_f32 v[136:137], v[152:153], v[136:137] neg_lo:[0,1] neg_hi:[0,1]
	v_pk_add_f32 v[152:153], v[144:145], v[48:49]
	v_pk_add_f32 v[48:49], v[144:145], v[48:49] neg_lo:[0,1] neg_hi:[0,1]
	v_mul_f32_e32 v66, 0x3f3504f3, v47
	v_xor_b32_e32 v145, 0x80000000, v48
	v_mov_b32_e32 v144, v49
	v_pk_add_f32 v[48:49], v[38:39], v[148:149]
	v_pk_add_f32 v[38:39], v[38:39], v[148:149] neg_lo:[0,1] neg_hi:[0,1]
	v_pk_add_f32 v[148:149], v[40:41], v[54:55]
	v_pk_fma_f32 v[46:47], v[46:47], s[56:57], v[66:67] op_sel_hi:[0,1,0]
	v_pk_add_f32 v[160:161], v[48:49], v[148:149]
	v_pk_add_f32 v[162:163], v[48:49], v[148:149] neg_lo:[0,1] neg_hi:[0,1]
	v_pk_add_f32 v[48:49], v[20:21], v[28:29]
	v_pk_add_f32 v[20:21], v[20:21], v[28:29] neg_lo:[0,1] neg_hi:[0,1]
	v_pk_add_f32 v[28:29], v[22:23], v[30:31]
	v_pk_add_f32 v[22:23], v[22:23], v[30:31] neg_lo:[0,1] neg_hi:[0,1]
	v_mul_f32_e32 v66, 0xbf3504f3, v52
	v_pk_mul_f32 v[30:31], v[22:23], s[42:43] op_sel_hi:[0,1]
	v_pk_fma_f32 v[22:23], v[22:23], s[64:65], v[30:31] op_sel:[1,0,0]
	v_pk_add_f32 v[30:31], v[12:13], v[24:25]
	v_pk_add_f32 v[12:13], v[12:13], v[24:25] neg_lo:[0,1] neg_hi:[0,1]
	v_pk_add_f32 v[40:41], v[40:41], v[54:55] neg_lo:[0,1] neg_hi:[0,1]
	v_mul_f32_e32 v24, 0x3f3504f3, v13
	v_pk_fma_f32 v[12:13], v[12:13], s[56:57], v[24:25] op_sel_hi:[0,1,0]
	v_pk_add_f32 v[24:25], v[14:15], v[26:27]
	v_pk_add_f32 v[14:15], v[14:15], v[26:27] neg_lo:[0,1] neg_hi:[0,1]
	v_pk_fma_f32 v[52:53], v[52:53], s[56:57], v[66:67] op_sel:[1,0,0] op_sel_hi:[1,1,0]
	v_pk_mul_f32 v[26:27], v[14:15], s[66:67] op_sel_hi:[0,1]
	v_pk_fma_f32 v[14:15], v[14:15], s[40:41], v[26:27] op_sel:[1,0,0]
	v_pk_add_f32 v[26:27], v[4:5], v[16:17]
	v_pk_add_f32 v[4:5], v[4:5], v[16:17] neg_lo:[0,1] neg_hi:[0,1]
	v_xor_b32_e32 v55, 0x80000000, v40
	v_xor_b32_e32 v17, 0x80000000, v4
	v_mov_b32_e32 v16, v5
	v_pk_add_f32 v[4:5], v[6:7], v[18:19]
	v_pk_add_f32 v[6:7], v[6:7], v[18:19] neg_lo:[0,1] neg_hi:[0,1]
	v_mov_b32_e32 v54, v41
	v_pk_mul_f32 v[18:19], v[6:7], s[44:45] op_sel_hi:[0,1]
	v_pk_fma_f32 v[6:7], v[6:7], s[42:43], v[18:19] op_sel:[1,0,0]
	s_waitcnt lgkmcnt(0)
	v_pk_add_f32 v[18:19], v[0:1], v[8:9]
	v_pk_add_f32 v[0:1], v[0:1], v[8:9] neg_lo:[0,1] neg_hi:[0,1]
	v_pk_add_f32 v[40:41], v[150:151], v[138:139]
	v_mul_f32_e32 v8, 0xbf3504f3, v0
	v_pk_fma_f32 v[0:1], v[0:1], s[56:57], v[8:9] op_sel:[1,0,0] op_sel_hi:[1,1,0]
	v_pk_add_f32 v[8:9], v[2:3], v[10:11]
	v_pk_add_f32 v[2:3], v[2:3], v[10:11] neg_lo:[0,1] neg_hi:[0,1]
	v_pk_add_f32 v[138:139], v[150:151], v[138:139] neg_lo:[0,1] neg_hi:[0,1]
	v_pk_mul_f32 v[10:11], v[2:3], s[58:59] op_sel_hi:[0,1]
	v_pk_fma_f32 v[2:3], v[2:3], s[66:67], v[10:11] op_sel:[1,0,0]
	v_pk_add_f32 v[10:11], v[48:49], v[26:27]
	v_pk_add_f32 v[26:27], v[48:49], v[26:27] neg_lo:[0,1] neg_hi:[0,1]
	v_pk_add_f32 v[48:49], v[28:29], v[4:5]
	v_pk_add_f32 v[4:5], v[28:29], v[4:5] neg_lo:[0,1] neg_hi:[0,1]
	v_pk_add_f32 v[150:151], v[146:147], v[50:51]
	v_mul_f32_e32 v28, 0x3f3504f3, v5
	v_pk_fma_f32 v[4:5], v[4:5], s[56:57], v[28:29] op_sel_hi:[0,1,0]
	v_pk_add_f32 v[28:29], v[30:31], v[18:19]
	v_pk_add_f32 v[18:19], v[30:31], v[18:19] neg_lo:[0,1] neg_hi:[0,1]
	v_pk_add_f32 v[50:51], v[146:147], v[50:51] neg_lo:[0,1] neg_hi:[0,1]
	v_xor_b32_e32 v31, 0x80000000, v18
	v_mov_b32_e32 v30, v19
	v_pk_add_f32 v[18:19], v[24:25], v[8:9]
	v_pk_add_f32 v[8:9], v[24:25], v[8:9] neg_lo:[0,1] neg_hi:[0,1]
	v_ashrrev_i32_e32 v33, 31, v32
	v_mul_f32_e32 v24, 0xbf3504f3, v8
	v_pk_fma_f32 v[8:9], v[8:9], s[56:57], v[24:25] op_sel:[1,0,0] op_sel_hi:[1,1,0]
	v_pk_add_f32 v[24:25], v[20:21], v[16:17]
	v_pk_add_f32 v[16:17], v[20:21], v[16:17] neg_lo:[0,1] neg_hi:[0,1]
	v_pk_add_f32 v[20:21], v[22:23], v[6:7]
	v_pk_add_f32 v[6:7], v[22:23], v[6:7] neg_lo:[0,1] neg_hi:[0,1]
	v_xor_b32_e32 v147, 0x80000000, v50
	v_mul_f32_e32 v22, 0x3f3504f3, v7
	v_pk_fma_f32 v[6:7], v[6:7], s[56:57], v[22:23] op_sel_hi:[0,1,0]
	v_pk_add_f32 v[22:23], v[12:13], v[0:1]
	v_pk_add_f32 v[0:1], v[12:13], v[0:1] neg_lo:[0,1] neg_hi:[0,1]
	v_mov_b32_e32 v146, v51
	v_xor_b32_e32 v13, 0x80000000, v0
	v_mov_b32_e32 v12, v1
	v_pk_add_f32 v[0:1], v[14:15], v[2:3]
	v_pk_add_f32 v[2:3], v[14:15], v[2:3] neg_lo:[0,1] neg_hi:[0,1]
	v_pk_add_f32 v[50:51], v[36:37], v[140:141]
	v_mul_f32_e32 v14, 0xbf3504f3, v2
	v_pk_fma_f32 v[2:3], v[2:3], s[56:57], v[14:15] op_sel:[1,0,0] op_sel_hi:[1,1,0]
	v_pk_add_f32 v[14:15], v[10:11], v[28:29]
	v_pk_add_f32 v[10:11], v[10:11], v[28:29] neg_lo:[0,1] neg_hi:[0,1]
	v_pk_add_f32 v[28:29], v[48:49], v[18:19]
	v_pk_add_f32 v[18:19], v[48:49], v[18:19] neg_lo:[0,1] neg_hi:[0,1]
	v_pk_add_f32 v[36:37], v[36:37], v[140:141] neg_lo:[0,1] neg_hi:[0,1]
	v_xor_b32_e32 v49, 0x80000000, v18
	v_mov_b32_e32 v48, v19
	v_pk_add_f32 v[18:19], v[26:27], v[30:31]
	v_pk_add_f32 v[26:27], v[26:27], v[30:31] neg_lo:[0,1] neg_hi:[0,1]
	v_pk_add_f32 v[30:31], v[4:5], v[8:9]
	v_pk_add_f32 v[4:5], v[4:5], v[8:9] neg_lo:[0,1] neg_hi:[0,1]
	v_pk_add_f32 v[140:141], v[46:47], v[52:53]
	v_xor_b32_e32 v9, 0x80000000, v4
	v_mov_b32_e32 v8, v5
	v_pk_add_f32 v[4:5], v[24:25], v[22:23]
	v_pk_add_f32 v[22:23], v[24:25], v[22:23] neg_lo:[0,1] neg_hi:[0,1]
	v_pk_add_f32 v[24:25], v[20:21], v[0:1]
	v_pk_add_f32 v[0:1], v[20:21], v[0:1] neg_lo:[0,1] neg_hi:[0,1]
	v_pk_add_f32 v[156:157], v[136:137], v[144:145]
	v_xor_b32_e32 v21, 0x80000000, v0
	v_mov_b32_e32 v20, v1
	v_pk_add_f32 v[0:1], v[16:17], v[12:13]
	v_pk_add_f32 v[12:13], v[16:17], v[12:13] neg_lo:[0,1] neg_hi:[0,1]
	v_pk_add_f32 v[16:17], v[6:7], v[2:3]
	v_pk_add_f32 v[2:3], v[6:7], v[2:3] neg_lo:[0,1] neg_hi:[0,1]
	v_pk_add_f32 v[158:159], v[136:137], v[144:145] neg_lo:[0,1] neg_hi:[0,1]
	v_lshl_add_u64 v[136:137], v[32:33], 3, s[86:87]
	v_pk_add_f32 v[174:175], v[50:51], v[140:141]
	v_pk_add_f32 v[176:177], v[50:51], v[140:141] neg_lo:[0,1] neg_hi:[0,1]
	v_pk_add_f32 v[50:51], v[14:15], v[28:29]
	v_pk_add_f32 v[178:179], v[14:15], v[28:29] neg_lo:[0,1] neg_hi:[0,1]
	v_pk_add_f32 v[180:181], v[10:11], v[48:49]
	v_pk_add_f32 v[182:183], v[10:11], v[48:49] neg_lo:[0,1] neg_hi:[0,1]
	v_pk_add_f32 v[188:189], v[26:27], v[8:9]
	v_pk_add_f32 v[190:191], v[26:27], v[8:9] neg_lo:[0,1] neg_hi:[0,1]
	v_pk_add_f32 v[192:193], v[4:5], v[24:25]
	v_pk_add_f32 v[194:195], v[4:5], v[24:25] neg_lo:[0,1] neg_hi:[0,1]
	v_pk_add_f32 v[220:221], v[0:1], v[16:17]
	v_pk_add_f32 v[222:223], v[0:1], v[16:17] neg_lo:[0,1] neg_hi:[0,1]
	v_pk_add_f32 v[224:225], v[12:13], v[2:3] op_sel:[0,1] op_sel_hi:[1,0] neg_hi:[0,1]
	v_pk_add_f32 v[226:227], v[12:13], v[2:3] op_sel:[0,1] op_sel_hi:[1,0] neg_lo:[0,1]
	s_waitcnt vmcnt(0)
	v_mov_b32_e32 v0, v104
	v_mov_b32_e32 v1, v105
	v_mov_b32_e32 v2, v106
	v_mov_b32_e32 v3, v107
	v_mov_b32_e32 v4, v108
	v_mov_b32_e32 v5, v109
	v_mov_b32_e32 v6, v110
	v_mov_b32_e32 v7, v111
	v_mov_b32_e32 v8, v112
	v_mov_b32_e32 v9, v113
	v_mov_b32_e32 v10, v114
	v_mov_b32_e32 v11, v115
	v_mov_b32_e32 v12, v116
	v_mov_b32_e32 v13, v117
	v_mov_b32_e32 v14, v118
	v_mov_b32_e32 v15, v119
	global_load_dwordx4 v[104:107], v[254:255], off offset:112
	global_load_dwordx4 v[108:111], v[254:255], off offset:96
	global_load_dwordx4 v[112:115], v[254:255], off offset:80
	global_load_dwordx4 v[116:119], v[254:255], off offset:64
	v_pk_add_f32 v[46:47], v[46:47], v[52:53] neg_lo:[0,1] neg_hi:[0,1]
	v_ashrrev_i32_e32 v35, 31, v34
	v_xor_b32_e32 v53, 0x80000000, v46
	v_mov_b32_e32 v52, v47
	v_pk_add_f32 v[46:47], v[142:143], v[152:153]
	v_pk_add_f32 v[142:143], v[142:143], v[152:153] neg_lo:[0,1] neg_hi:[0,1]
	v_lshl_add_u64 v[152:153], v[34:35], 3, s[86:87]
	v_pk_add_f32 v[184:185], v[18:19], v[30:31]
	v_pk_add_f32 v[186:187], v[18:19], v[30:31] neg_lo:[0,1] neg_hi:[0,1]
	v_pk_add_f32 v[216:217], v[22:23], v[20:21]
	v_pk_add_f32 v[218:219], v[22:23], v[20:21] neg_lo:[0,1] neg_hi:[0,1]
	v_pk_add_f32 v[164:165], v[38:39], v[54:55]
	v_pk_add_f32 v[54:55], v[38:39], v[54:55] neg_lo:[0,1] neg_hi:[0,1]
	v_pk_add_f32 v[170:171], v[138:139], v[146:147]
	v_pk_add_f32 v[172:173], v[138:139], v[146:147] neg_lo:[0,1] neg_hi:[0,1]
	v_pk_add_f32 v[38:39], v[36:37], v[52:53]
	v_pk_add_f32 v[36:37], v[36:37], v[52:53] neg_lo:[0,1] neg_hi:[0,1]
	v_pk_add_f32 v[166:167], v[40:41], v[150:151]
	v_pk_add_f32 v[40:41], v[40:41], v[150:151] neg_lo:[0,1] neg_hi:[0,1]
	v_cmp_lt_i32_e32 vcc, -1, v42
	v_add_u32_e32 v42, 0x400, v42
	s_or_b64 s[92:93], vcc, s[92:93]
	s_waitcnt vmcnt(4)
	v_pk_mul_f32 v[16:17], v[46:47], v[12:13] op_sel:[1,1] op_sel_hi:[1,0] neg_lo:[0,1]
	s_nop 0
	v_pk_fma_f32 v[12:13], v[12:13], v[46:47], v[16:17] op_sel_hi:[1,0,1]
	v_pk_fma_f32 v[12:13], v[46:47], v[252:253], v[12:13]
	v_mov_b32_e32 v16, v120
	v_mov_b32_e32 v17, v121
	v_mov_b32_e32 v18, v122
	v_mov_b32_e32 v19, v123
	v_mov_b32_e32 v20, v124
	v_mov_b32_e32 v21, v125
	v_mov_b32_e32 v22, v126
	v_mov_b32_e32 v23, v127
	v_mov_b32_e32 v24, v128
	v_mov_b32_e32 v25, v129
	v_mov_b32_e32 v26, v130
	v_mov_b32_e32 v27, v131
	v_mov_b32_e32 v28, v132
	v_mov_b32_e32 v29, v133
	v_mov_b32_e32 v30, v134
	v_mov_b32_e32 v31, v135
	s_waitcnt vmcnt(4)
	v_pk_mul_f32 v[32:33], v[50:51], v[28:29] op_sel:[1,1] op_sel_hi:[1,0] neg_lo:[0,1]
	s_nop 0
	v_pk_fma_f32 v[28:29], v[28:29], v[50:51], v[32:33] op_sel_hi:[1,0,1]
	v_pk_fma_f32 v[28:29], v[50:51], v[252:253], v[28:29]
	ds_write_b64 v43, v[12:13]
	ds_write_b64 v44, v[28:29]
	v_mov_b32_e32 v32, v228
	v_mov_b32_e32 v33, v229
	v_mov_b32_e32 v34, v230
	v_mov_b32_e32 v35, v231
	v_mov_b32_e32 v46, v232
	v_mov_b32_e32 v47, v233
	v_mov_b32_e32 v48, v234
	v_mov_b32_e32 v49, v235
	v_mov_b32_e32 v50, v236
	v_mov_b32_e32 v51, v237
	v_mov_b32_e32 v52, v238
	v_mov_b32_e32 v53, v239
	s_nop 0
	v_mov_b32_e32 v136, v246
	v_mov_b32_e32 v137, v247
	v_mov_b32_e32 v138, v248
	v_mov_b32_e32 v139, v249
	s_waitcnt vmcnt(4)
	v_pk_mul_f32 v[12:13], v[142:143], v[136:137] op_sel:[1,1] op_sel_hi:[1,0] neg_lo:[0,1]
	s_nop 0
	v_pk_fma_f32 v[12:13], v[142:143], v[136:137], v[12:13] op_sel_hi:[0,1,1]
	v_pk_fma_f32 v[12:13], v[142:143], v[252:253], v[12:13]
	s_nop 0
	s_waitcnt vmcnt(0)
	v_mov_b32_e32 v140, v104
	v_mov_b32_e32 v141, v105
	v_mov_b32_e32 v142, v106
	v_mov_b32_e32 v143, v107
	v_mov_b32_e32 v144, v108
	v_mov_b32_e32 v145, v109
	v_mov_b32_e32 v146, v110
	v_mov_b32_e32 v147, v111
	v_mov_b32_e32 v148, v112
	v_mov_b32_e32 v149, v113
	v_mov_b32_e32 v150, v114
	v_mov_b32_e32 v151, v115
	v_mov_b32_e32 v152, v116
	v_mov_b32_e32 v153, v117
	v_mov_b32_e32 v154, v118
	v_mov_b32_e32 v155, v119
	v_pk_mul_f32 v[28:29], v[178:179], v[152:153] op_sel:[1,1] op_sel_hi:[1,0] neg_lo:[0,1]
	s_nop 0
	v_pk_fma_f32 v[28:29], v[178:179], v[152:153], v[28:29] op_sel_hi:[0,1,1]
	v_pk_fma_f32 v[28:29], v[178:179], v[252:253], v[28:29]
	ds_write_b64 v43, v[12:13] offset:64
	ds_write_b64 v44, v[28:29] offset:64
	v_pk_mul_f32 v[12:13], v[156:157], v[4:5] op_sel:[1,1] op_sel_hi:[1,0] neg_lo:[0,1]
	s_nop 0
	v_pk_fma_f32 v[4:5], v[156:157], v[4:5], v[12:13] op_sel_hi:[0,1,1]
	v_pk_fma_f32 v[4:5], v[156:157], v[252:253], v[4:5]
	v_pk_mul_f32 v[12:13], v[180:181], v[20:21] op_sel:[1,1] op_sel_hi:[1,0] neg_lo:[0,1]
	s_nop 0
	v_pk_fma_f32 v[12:13], v[180:181], v[20:21], v[12:13] op_sel_hi:[0,1,1]
	v_pk_fma_f32 v[12:13], v[180:181], v[252:253], v[12:13]
	ds_write_b64 v43, v[4:5] offset:32
	ds_write_b64 v44, v[12:13] offset:32
	v_pk_mul_f32 v[4:5], v[158:159], v[46:47] op_sel:[1,1] op_sel_hi:[1,0] neg_lo:[0,1]
	v_pk_fma_f32 v[4:5], v[158:159], v[46:47], v[4:5] op_sel_hi:[0,1,1]
	v_pk_fma_f32 v[4:5], v[158:159], v[252:253], v[4:5]
	v_pk_mul_f32 v[12:13], v[182:183], v[144:145] op_sel:[1,1] op_sel_hi:[1,0] neg_lo:[0,1]
	s_nop 0
	v_pk_fma_f32 v[12:13], v[182:183], v[144:145], v[12:13] op_sel_hi:[0,1,1]
	v_pk_fma_f32 v[12:13], v[182:183], v[252:253], v[12:13]
	ds_write_b64 v43, v[4:5] offset:96
	ds_write_b64 v44, v[12:13] offset:96
	v_pk_mul_f32 v[4:5], v[160:161], v[8:9] op_sel:[1,1] op_sel_hi:[1,0] neg_lo:[0,1]
	s_nop 0
	v_pk_fma_f32 v[4:5], v[160:161], v[8:9], v[4:5] op_sel_hi:[0,1,1]
	v_pk_fma_f32 v[4:5], v[160:161], v[252:253], v[4:5]
	v_pk_mul_f32 v[8:9], v[184:185], v[24:25] op_sel:[1,1] op_sel_hi:[1,0] neg_lo:[0,1]
	s_nop 0
	v_pk_fma_f32 v[8:9], v[184:185], v[24:25], v[8:9] op_sel_hi:[0,1,1]
	v_pk_fma_f32 v[8:9], v[184:185], v[252:253], v[8:9]
	ds_write_b64 v43, v[4:5] offset:16
	ds_write_b64 v44, v[8:9] offset:16
	v_pk_mul_f32 v[4:5], v[162:163], v[50:51] op_sel:[1,1] op_sel_hi:[1,0] neg_lo:[0,1]
	v_pk_fma_f32 v[4:5], v[162:163], v[50:51], v[4:5] op_sel_hi:[0,1,1]
	v_pk_fma_f32 v[4:5], v[162:163], v[252:253], v[4:5]
	v_pk_mul_f32 v[8:9], v[186:187], v[148:149] op_sel:[1,1] op_sel_hi:[1,0] neg_lo:[0,1]
	s_nop 0
	v_pk_fma_f32 v[8:9], v[186:187], v[148:149], v[8:9] op_sel_hi:[0,1,1]
	v_pk_fma_f32 v[8:9], v[186:187], v[252:253], v[8:9]
	ds_write_b64 v43, v[4:5] offset:80
	ds_write_b64 v44, v[8:9] offset:80
	v_pk_mul_f32 v[4:5], v[164:165], v[0:1] op_sel:[1,1] op_sel_hi:[1,0] neg_lo:[0,1]
	s_nop 0
	v_pk_fma_f32 v[0:1], v[164:165], v[0:1], v[4:5] op_sel_hi:[0,1,1]
	v_pk_fma_f32 v[0:1], v[164:165], v[252:253], v[0:1]
	v_pk_mul_f32 v[4:5], v[188:189], v[16:17] op_sel:[1,1] op_sel_hi:[1,0] neg_lo:[0,1]
	s_nop 0
	v_pk_fma_f32 v[4:5], v[188:189], v[16:17], v[4:5] op_sel_hi:[0,1,1]
	v_pk_fma_f32 v[4:5], v[188:189], v[252:253], v[4:5]
	ds_write_b64 v43, v[0:1] offset:48
	ds_write_b64 v44, v[4:5] offset:48
	v_pk_mul_f32 v[0:1], v[54:55], v[32:33] op_sel:[1,1] op_sel_hi:[1,0] neg_lo:[0,1]
	v_pk_fma_f32 v[0:1], v[54:55], v[32:33], v[0:1] op_sel_hi:[0,1,1]
	v_pk_fma_f32 v[0:1], v[54:55], v[252:253], v[0:1]
	v_pk_mul_f32 v[4:5], v[190:191], v[140:141] op_sel:[1,1] op_sel_hi:[1,0] neg_lo:[0,1]
	s_nop 0
	v_pk_fma_f32 v[4:5], v[190:191], v[140:141], v[4:5] op_sel_hi:[0,1,1]
	v_pk_fma_f32 v[4:5], v[190:191], v[252:253], v[4:5]
	ds_write_b64 v43, v[0:1] offset:112
	ds_write_b64 v44, v[4:5] offset:112
	v_pk_mul_f32 v[0:1], v[166:167], v[14:15] op_sel:[1,1] op_sel_hi:[1,0] neg_lo:[0,1]
	v_pk_fma_f32 v[0:1], v[166:167], v[14:15], v[0:1] op_sel_hi:[0,1,1]
	v_pk_fma_f32 v[0:1], v[166:167], v[252:253], v[0:1]
	v_pk_mul_f32 v[4:5], v[192:193], v[30:31] op_sel:[1,1] op_sel_hi:[1,0] neg_lo:[0,1]
	s_nop 0
	v_pk_fma_f32 v[4:5], v[192:193], v[30:31], v[4:5] op_sel_hi:[0,1,1]
	v_pk_fma_f32 v[4:5], v[192:193], v[252:253], v[4:5]
	ds_write_b64 v43, v[0:1] offset:8
	ds_write_b64 v44, v[4:5] offset:8
	v_pk_mul_f32 v[0:1], v[40:41], v[138:139] op_sel:[1,1] op_sel_hi:[1,0] neg_lo:[0,1]
	v_pk_fma_f32 v[0:1], v[40:41], v[138:139], v[0:1] op_sel_hi:[0,1,1]
	v_pk_fma_f32 v[0:1], v[40:41], v[252:253], v[0:1]
	v_pk_mul_f32 v[4:5], v[194:195], v[154:155] op_sel:[1,1] op_sel_hi:[1,0] neg_lo:[0,1]
	s_nop 0
	v_pk_fma_f32 v[4:5], v[194:195], v[154:155], v[4:5] op_sel_hi:[0,1,1]
	v_pk_fma_f32 v[4:5], v[194:195], v[252:253], v[4:5]
	ds_write_b64 v43, v[0:1] offset:72
	ds_write_b64 v44, v[4:5] offset:72
	v_pk_mul_f32 v[0:1], v[170:171], v[6:7] op_sel:[1,1] op_sel_hi:[1,0] neg_lo:[0,1]
	v_pk_fma_f32 v[0:1], v[170:171], v[6:7], v[0:1] op_sel_hi:[0,1,1]
	v_pk_fma_f32 v[0:1], v[170:171], v[252:253], v[0:1]
	v_pk_mul_f32 v[4:5], v[216:217], v[22:23] op_sel:[1,1] op_sel_hi:[1,0] neg_lo:[0,1]
	s_nop 0
	v_pk_fma_f32 v[4:5], v[216:217], v[22:23], v[4:5] op_sel_hi:[0,1,1]
	v_pk_fma_f32 v[4:5], v[216:217], v[252:253], v[4:5]
	ds_write_b64 v43, v[0:1] offset:40
	ds_write_b64 v44, v[4:5] offset:40
	v_pk_mul_f32 v[0:1], v[172:173], v[48:49] op_sel:[1,1] op_sel_hi:[1,0] neg_lo:[0,1]
	v_pk_fma_f32 v[0:1], v[172:173], v[48:49], v[0:1] op_sel_hi:[0,1,1]
	v_pk_fma_f32 v[0:1], v[172:173], v[252:253], v[0:1]
	v_pk_mul_f32 v[4:5], v[218:219], v[146:147] op_sel:[1,1] op_sel_hi:[1,0] neg_lo:[0,1]
	s_nop 0
	v_pk_fma_f32 v[4:5], v[218:219], v[146:147], v[4:5] op_sel_hi:[0,1,1]
	v_pk_fma_f32 v[4:5], v[218:219], v[252:253], v[4:5]
	ds_write_b64 v43, v[0:1] offset:104
	ds_write_b64 v44, v[4:5] offset:104
	v_pk_mul_f32 v[0:1], v[174:175], v[10:11] op_sel:[1,1] op_sel_hi:[1,0] neg_lo:[0,1]
	v_pk_fma_f32 v[0:1], v[174:175], v[10:11], v[0:1] op_sel_hi:[0,1,1]
	v_pk_fma_f32 v[0:1], v[174:175], v[252:253], v[0:1]
	v_pk_mul_f32 v[4:5], v[220:221], v[26:27] op_sel:[1,1] op_sel_hi:[1,0] neg_lo:[0,1]
	s_nop 0
	v_pk_fma_f32 v[4:5], v[220:221], v[26:27], v[4:5] op_sel_hi:[0,1,1]
	v_pk_fma_f32 v[4:5], v[220:221], v[252:253], v[4:5]
	ds_write_b64 v43, v[0:1] offset:24
	ds_write_b64 v44, v[4:5] offset:24
	v_pk_mul_f32 v[0:1], v[176:177], v[52:53] op_sel:[1,1] op_sel_hi:[1,0] neg_lo:[0,1]
	v_pk_fma_f32 v[0:1], v[176:177], v[52:53], v[0:1] op_sel_hi:[0,1,1]
	v_pk_fma_f32 v[0:1], v[176:177], v[252:253], v[0:1]
	v_pk_mul_f32 v[4:5], v[222:223], v[150:151] op_sel:[1,1] op_sel_hi:[1,0] neg_lo:[0,1]
	s_nop 0
	v_pk_fma_f32 v[4:5], v[222:223], v[150:151], v[4:5] op_sel_hi:[0,1,1]
	v_pk_fma_f32 v[4:5], v[222:223], v[252:253], v[4:5]
	ds_write_b64 v43, v[0:1] offset:88
	ds_write_b64 v44, v[4:5] offset:88
	v_pk_mul_f32 v[0:1], v[38:39], v[2:3] op_sel:[1,1] op_sel_hi:[1,0] neg_lo:[0,1]
	s_nop 0
	v_pk_fma_f32 v[0:1], v[38:39], v[2:3], v[0:1] op_sel_hi:[0,1,1]
	v_pk_fma_f32 v[0:1], v[38:39], v[252:253], v[0:1]
	v_pk_mul_f32 v[2:3], v[224:225], v[18:19] op_sel:[1,1] op_sel_hi:[1,0] neg_lo:[0,1]
	s_nop 0
	v_pk_fma_f32 v[2:3], v[224:225], v[18:19], v[2:3] op_sel_hi:[0,1,1]
	v_pk_fma_f32 v[2:3], v[224:225], v[252:253], v[2:3]
	ds_write_b64 v43, v[0:1] offset:56
	ds_write_b64 v44, v[2:3] offset:56
	v_pk_mul_f32 v[0:1], v[36:37], v[34:35] op_sel:[1,1] op_sel_hi:[1,0] neg_lo:[0,1]
	v_pk_fma_f32 v[0:1], v[36:37], v[34:35], v[0:1] op_sel_hi:[0,1,1]
	v_pk_fma_f32 v[0:1], v[36:37], v[252:253], v[0:1]
	v_pk_mul_f32 v[2:3], v[226:227], v[142:143] op_sel:[1,1] op_sel_hi:[1,0] neg_lo:[0,1]
	s_nop 0
	v_pk_fma_f32 v[2:3], v[226:227], v[142:143], v[2:3] op_sel_hi:[0,1,1]
	v_pk_fma_f32 v[2:3], v[226:227], v[252:253], v[2:3]
	ds_write_b64 v43, v[0:1] offset:120
	ds_write_b64 v44, v[2:3] offset:120
	s_andn2_b64 exec, exec, s[92:93]
	s_cbranch_execnz .LBB0_353

.LBB0_356:
	v_add_u32_e32 v0, 0x200, v38
	v_and_b32_e32 v1, 0xffffff80, v38
	v_add_u32_e32 v39, v196, v1
	v_and_b32_e32 v0, 0xffffff80, v0
	v_add_u32_e32 v152, v196, v0
	ds_read_b64 v[40:41], v39
	ds_read_b64 v[42:43], v39 offset:8
	ds_read_b64 v[20:21], v152
	ds_read_b64 v[22:23], v152 offset:8
	ds_read_b64 v[44:45], v39 offset:16
	ds_read_b64 v[46:47], v39 offset:24
	ds_read_b64 v[12:13], v152 offset:16
	ds_read_b64 v[14:15], v152 offset:24
	ds_read_b64 v[48:49], v39 offset:32
	ds_read_b64 v[50:51], v39 offset:40
	ds_read_b64 v[4:5], v152 offset:32
	ds_read_b64 v[6:7], v152 offset:40
	ds_read_b64 v[52:53], v39 offset:48
	ds_read_b64 v[54:55], v39 offset:56
	ds_read_b64 v[0:1], v152 offset:48
	ds_read_b64 v[2:3], v152 offset:56
	ds_read_b64 v[136:137], v39 offset:64
	ds_read_b64 v[138:139], v39 offset:72
	ds_read_b64 v[28:29], v152 offset:64
	ds_read_b64 v[30:31], v152 offset:72
	ds_read_b64 v[140:141], v39 offset:80
	ds_read_b64 v[142:143], v39 offset:88
	ds_read_b64 v[24:25], v152 offset:80
	ds_read_b64 v[26:27], v152 offset:88
	ds_read_b64 v[144:145], v39 offset:96
	ds_read_b64 v[146:147], v39 offset:104
	ds_read_b64 v[16:17], v152 offset:96
	ds_read_b64 v[18:19], v152 offset:104
	ds_read_b64 v[148:149], v39 offset:112
	ds_read_b64 v[150:151], v39 offset:120
	ds_read_b64 v[8:9], v152 offset:112
	ds_read_b64 v[10:11], v152 offset:120
	s_waitcnt lgkmcnt(14)
	v_pk_add_f32 v[34:35], v[40:41], v[136:137]
	v_pk_add_f32 v[32:33], v[40:41], v[136:137] neg_lo:[0,1] neg_hi:[0,1]
	s_waitcnt lgkmcnt(10)
	v_pk_add_f32 v[136:137], v[46:47], v[142:143]
	v_pk_add_f32 v[46:47], v[46:47], v[142:143] neg_lo:[0,1] neg_hi:[0,1]
	s_mov_b32 s94, s67
	s_mov_b32 s95, s64
	v_pk_add_f32 v[36:37], v[42:43], v[138:139]
	v_pk_add_f32 v[40:41], v[42:43], v[138:139] neg_lo:[0,1] neg_hi:[0,1]
	s_mov_b32 s40, s43
	s_mov_b32 s41, s42
	s_mov_b32 s65, s42
	v_pk_mul_f32 v[138:139], v[46:47], s[94:95] op_sel:[1,0]
	s_mov_b32 s58, s42
	s_mov_b32 s59, s64
	v_pk_mul_f32 v[42:43], v[40:41], s[40:41] op_sel:[1,0]
	v_pk_fma_f32 v[46:47], v[46:47], s[64:65], v[138:139] op_sel_hi:[0,1,1]
	s_waitcnt lgkmcnt(6)
	v_pk_add_f32 v[138:139], v[48:49], v[144:145]
	v_pk_add_f32 v[48:49], v[48:49], v[144:145] neg_lo:[0,1] neg_hi:[0,1]
	s_waitcnt lgkmcnt(2)
	v_pk_add_f32 v[144:145], v[54:55], v[150:151]
	v_pk_add_f32 v[54:55], v[54:55], v[150:151] neg_lo:[0,1] neg_hi:[0,1]
	s_mov_b32 s66, s43
	v_pk_fma_f32 v[40:41], v[40:41], s[58:59], v[42:43] op_sel_hi:[0,1,1]
	v_pk_add_f32 v[42:43], v[44:45], v[140:141]
	v_pk_add_f32 v[44:45], v[44:45], v[140:141] neg_lo:[0,1] neg_hi:[0,1]
	v_xor_b32_e32 v140, 0x80000000, v49
	v_mov_b32_e32 v141, v48
	v_pk_add_f32 v[48:49], v[50:51], v[146:147]
	v_pk_add_f32 v[50:51], v[50:51], v[146:147] neg_lo:[0,1] neg_hi:[0,1]
	s_mov_b32 s96, s67
	s_mov_b32 s97, s43
	v_pk_mul_f32 v[146:147], v[54:55], s[66:67] op_sel:[1,0]
	v_pk_mul_f32 v[142:143], v[50:51], s[96:97] op_sel:[1,0]
	v_pk_fma_f32 v[54:55], v[54:55], s[94:95], v[146:147] op_sel_hi:[0,1,1]
	v_pk_add_f32 v[146:147], v[34:35], v[138:139]
	v_pk_add_f32 v[34:35], v[34:35], v[138:139] neg_lo:[0,1] neg_hi:[0,1]
	v_pk_add_f32 v[138:139], v[36:37], v[48:49]
	v_pk_add_f32 v[36:37], v[36:37], v[48:49] neg_lo:[0,1] neg_hi:[0,1]
	s_mov_b32 s44, s57
	s_mov_b32 s45, s56
	v_pk_fma_f32 v[50:51], v[50:51], s[40:41], v[142:143] op_sel_hi:[0,1,1]
	v_pk_add_f32 v[142:143], v[52:53], v[148:149]
	v_mul_f32_e32 v48, 0x3f3504f3, v36
	v_mul_f32_e32 v66, 0x3f3504f3, v44
	v_pk_add_f32 v[52:53], v[52:53], v[148:149] neg_lo:[0,1] neg_hi:[0,1]
	v_pk_fma_f32 v[36:37], v[36:37], s[44:45], v[48:49] op_sel:[1,0,0] op_sel_hi:[1,1,0]
	v_pk_add_f32 v[48:49], v[42:43], v[142:143]
	v_pk_add_f32 v[42:43], v[42:43], v[142:143] neg_lo:[0,1] neg_hi:[0,1]
	v_pk_fma_f32 v[44:45], v[44:45], s[44:45], v[66:67] op_sel:[1,0,0] op_sel_hi:[1,1,0]
	v_mul_f32_e32 v66, 0xbf3504f3, v53
	v_xor_b32_e32 v142, 0x80000000, v43
	v_mov_b32_e32 v143, v42
	v_pk_add_f32 v[42:43], v[136:137], v[144:145]
	v_pk_add_f32 v[136:137], v[136:137], v[144:145] neg_lo:[0,1] neg_hi:[0,1]
	v_pk_add_f32 v[144:145], v[32:33], v[140:141]
	v_pk_add_f32 v[32:33], v[32:33], v[140:141] neg_lo:[0,1] neg_hi:[0,1]
	v_pk_add_f32 v[140:141], v[40:41], v[50:51]
	v_pk_add_f32 v[40:41], v[40:41], v[50:51] neg_lo:[0,1] neg_hi:[0,1]
	v_pk_fma_f32 v[52:53], v[52:53], s[44:45], v[66:67] op_sel_hi:[0,1,0]
	v_mul_f32_e32 v50, 0x3f3504f3, v40
	v_pk_fma_f32 v[40:41], v[40:41], s[44:45], v[50:51] op_sel:[1,0,0] op_sel_hi:[1,1,0]
	v_pk_add_f32 v[50:51], v[44:45], v[52:53]
	v_pk_add_f32 v[44:45], v[44:45], v[52:53] neg_lo:[0,1] neg_hi:[0,1]
	v_mul_f32_e32 v66, 0xbf3504f3, v137
	v_xor_b32_e32 v52, 0x80000000, v45
	v_mov_b32_e32 v53, v44
	v_pk_add_f32 v[44:45], v[46:47], v[54:55]
	v_pk_add_f32 v[46:47], v[46:47], v[54:55] neg_lo:[0,1] neg_hi:[0,1]
	v_pk_fma_f32 v[136:137], v[136:137], s[44:45], v[66:67] op_sel_hi:[0,1,0]
	v_mul_f32_e32 v54, 0xbf3504f3, v47
	v_pk_fma_f32 v[46:47], v[46:47], s[44:45], v[54:55] op_sel_hi:[0,1,0]
	v_pk_add_f32 v[54:55], v[146:147], v[48:49]
	v_pk_add_f32 v[48:49], v[146:147], v[48:49] neg_lo:[0,1] neg_hi:[0,1]
	v_pk_add_f32 v[146:147], v[138:139], v[42:43]
	v_pk_add_f32 v[42:43], v[138:139], v[42:43] neg_lo:[0,1] neg_hi:[0,1]
	v_cmp_lt_i32_e32 vcc, -1, v38
	v_xor_b32_e32 v138, 0x80000000, v43
	v_mov_b32_e32 v139, v42
	v_pk_add_f32 v[42:43], v[34:35], v[142:143]
	v_pk_add_f32 v[34:35], v[34:35], v[142:143] neg_lo:[0,1] neg_hi:[0,1]
	v_pk_add_f32 v[142:143], v[36:37], v[136:137]
	v_pk_add_f32 v[36:37], v[36:37], v[136:137] neg_lo:[0,1] neg_hi:[0,1]
	v_add_u32_e32 v38, 0x400, v38
	v_xor_b32_e32 v136, 0x80000000, v37
	v_mov_b32_e32 v137, v36
	v_pk_add_f32 v[36:37], v[144:145], v[50:51]
	v_pk_add_f32 v[50:51], v[144:145], v[50:51] neg_lo:[0,1] neg_hi:[0,1]
	v_pk_add_f32 v[144:145], v[140:141], v[44:45]
	v_pk_add_f32 v[44:45], v[140:141], v[44:45] neg_lo:[0,1] neg_hi:[0,1]
	s_or_b64 s[92:93], vcc, s[92:93]
	v_xor_b32_e32 v140, 0x80000000, v45
	v_mov_b32_e32 v141, v44
	v_pk_add_f32 v[44:45], v[32:33], v[52:53]
	v_pk_add_f32 v[32:33], v[32:33], v[52:53] neg_lo:[0,1] neg_hi:[0,1]
	v_pk_add_f32 v[52:53], v[40:41], v[46:47]
	v_pk_add_f32 v[40:41], v[40:41], v[46:47] neg_lo:[0,1] neg_hi:[0,1]
	s_nop 0
	v_xor_b32_e32 v46, 0x80000000, v41
	v_mov_b32_e32 v47, v40
	v_pk_add_f32 v[40:41], v[54:55], v[146:147]
	v_pk_add_f32 v[54:55], v[54:55], v[146:147] neg_lo:[0,1] neg_hi:[0,1]
	v_pk_add_f32 v[146:147], v[48:49], v[138:139]
	v_pk_add_f32 v[48:49], v[48:49], v[138:139] neg_lo:[0,1] neg_hi:[0,1]
	v_pk_add_f32 v[138:139], v[42:43], v[142:143]
	v_pk_add_f32 v[42:43], v[42:43], v[142:143] neg_lo:[0,1] neg_hi:[0,1]
	v_pk_add_f32 v[142:143], v[34:35], v[136:137]
	v_pk_add_f32 v[34:35], v[34:35], v[136:137] neg_lo:[0,1] neg_hi:[0,1]
	v_pk_add_f32 v[136:137], v[36:37], v[144:145]
	v_pk_add_f32 v[36:37], v[36:37], v[144:145] neg_lo:[0,1] neg_hi:[0,1]
	v_pk_add_f32 v[144:145], v[50:51], v[140:141]
	v_pk_add_f32 v[50:51], v[50:51], v[140:141] neg_lo:[0,1] neg_hi:[0,1]
	v_pk_add_f32 v[140:141], v[44:45], v[52:53]
	v_pk_add_f32 v[44:45], v[44:45], v[52:53] neg_lo:[0,1] neg_hi:[0,1]
	v_pk_add_f32 v[52:53], v[32:33], v[46:47]
	v_pk_add_f32 v[32:33], v[32:33], v[46:47] neg_lo:[0,1] neg_hi:[0,1]
	v_pk_add_f32 v[46:47], v[20:21], v[28:29]
	v_pk_add_f32 v[20:21], v[20:21], v[28:29] neg_lo:[0,1] neg_hi:[0,1]
	v_pk_add_f32 v[28:29], v[22:23], v[30:31]
	v_pk_add_f32 v[22:23], v[22:23], v[30:31] neg_lo:[0,1] neg_hi:[0,1]
	s_nop 0
	v_pk_mul_f32 v[30:31], v[22:23], s[40:41] op_sel:[1,0]
	s_nop 0
	v_pk_fma_f32 v[22:23], v[22:23], s[58:59], v[30:31] op_sel_hi:[0,1,1]
	v_pk_add_f32 v[30:31], v[12:13], v[24:25]
	v_pk_add_f32 v[12:13], v[12:13], v[24:25] neg_lo:[0,1] neg_hi:[0,1]
	s_nop 0
	v_mul_f32_e32 v24, 0x3f3504f3, v12
	v_pk_fma_f32 v[12:13], v[12:13], s[44:45], v[24:25] op_sel:[1,0,0] op_sel_hi:[1,1,0]
	v_pk_add_f32 v[24:25], v[14:15], v[26:27]
	v_pk_add_f32 v[14:15], v[14:15], v[26:27] neg_lo:[0,1] neg_hi:[0,1]
	s_nop 0
	v_pk_mul_f32 v[26:27], v[14:15], s[94:95] op_sel:[1,0]
	s_nop 0
	v_pk_fma_f32 v[14:15], v[14:15], s[64:65], v[26:27] op_sel_hi:[0,1,1]
	v_pk_add_f32 v[26:27], v[4:5], v[16:17]
	v_pk_add_f32 v[4:5], v[4:5], v[16:17] neg_lo:[0,1] neg_hi:[0,1]
	s_nop 0
	v_xor_b32_e32 v16, 0x80000000, v5
	v_mov_b32_e32 v17, v4
	v_pk_add_f32 v[4:5], v[6:7], v[18:19]
	v_pk_add_f32 v[6:7], v[6:7], v[18:19] neg_lo:[0,1] neg_hi:[0,1]
	s_nop 0
	v_pk_mul_f32 v[18:19], v[6:7], s[96:97] op_sel:[1,0]
	s_nop 0
	v_pk_fma_f32 v[6:7], v[6:7], s[40:41], v[18:19] op_sel_hi:[0,1,1]
	s_waitcnt lgkmcnt(0)
	ds_write_b64 v39, v[40:41]
	ds_write_b64 v39, v[54:55] offset:64
	ds_write_b64 v39, v[146:147] offset:32
	ds_write_b64 v39, v[48:49] offset:96
	ds_write_b64 v39, v[138:139] offset:16
	ds_write_b64 v39, v[42:43] offset:80
	ds_write_b64 v39, v[142:143] offset:48
	ds_write_b64 v39, v[34:35] offset:112
	ds_write_b64 v39, v[136:137] offset:8
	ds_write_b64 v39, v[36:37] offset:72
	ds_write_b64 v39, v[144:145] offset:40
	ds_write_b64 v39, v[50:51] offset:104
	ds_write_b64 v39, v[140:141] offset:24
	ds_write_b64 v39, v[44:45] offset:88
	ds_write_b64 v39, v[52:53] offset:56
	ds_write_b64 v39, v[32:33] offset:120
	v_pk_add_f32 v[18:19], v[0:1], v[8:9]
	v_pk_add_f32 v[0:1], v[0:1], v[8:9] neg_lo:[0,1] neg_hi:[0,1]
	s_nop 0
	v_mul_f32_e32 v8, 0xbf3504f3, v1
	v_pk_fma_f32 v[0:1], v[0:1], s[44:45], v[8:9] op_sel_hi:[0,1,0]
	v_pk_add_f32 v[8:9], v[2:3], v[10:11]
	v_pk_add_f32 v[2:3], v[2:3], v[10:11] neg_lo:[0,1] neg_hi:[0,1]
	s_nop 0
	v_pk_mul_f32 v[10:11], v[2:3], s[66:67] op_sel:[1,0]
	s_nop 0
	v_pk_fma_f32 v[2:3], v[2:3], s[94:95], v[10:11] op_sel_hi:[0,1,1]
	v_pk_add_f32 v[10:11], v[46:47], v[26:27]
	v_pk_add_f32 v[26:27], v[46:47], v[26:27] neg_lo:[0,1] neg_hi:[0,1]
	v_pk_add_f32 v[46:47], v[28:29], v[4:5]
	v_pk_add_f32 v[4:5], v[28:29], v[4:5] neg_lo:[0,1] neg_hi:[0,1]
	s_nop 0
	v_mul_f32_e32 v28, 0x3f3504f3, v4
	v_pk_fma_f32 v[4:5], v[4:5], s[44:45], v[28:29] op_sel:[1,0,0] op_sel_hi:[1,1,0]
	v_pk_add_f32 v[28:29], v[30:31], v[18:19]
	v_pk_add_f32 v[18:19], v[30:31], v[18:19] neg_lo:[0,1] neg_hi:[0,1]
	s_nop 0
	v_xor_b32_e32 v30, 0x80000000, v19
	v_mov_b32_e32 v31, v18
	v_pk_add_f32 v[18:19], v[24:25], v[8:9]
	v_pk_add_f32 v[8:9], v[24:25], v[8:9] neg_lo:[0,1] neg_hi:[0,1]
	s_nop 0
	v_mul_f32_e32 v24, 0xbf3504f3, v9
	v_pk_fma_f32 v[8:9], v[8:9], s[44:45], v[24:25] op_sel_hi:[0,1,0]
	v_pk_add_f32 v[24:25], v[20:21], v[16:17]
	v_pk_add_f32 v[16:17], v[20:21], v[16:17] neg_lo:[0,1] neg_hi:[0,1]
	v_pk_add_f32 v[20:21], v[22:23], v[6:7]
	v_pk_add_f32 v[6:7], v[22:23], v[6:7] neg_lo:[0,1] neg_hi:[0,1]
	s_nop 0
	v_mul_f32_e32 v22, 0x3f3504f3, v6
	v_pk_fma_f32 v[6:7], v[6:7], s[44:45], v[22:23] op_sel:[1,0,0] op_sel_hi:[1,1,0]
	v_pk_add_f32 v[22:23], v[12:13], v[0:1]
	v_pk_add_f32 v[0:1], v[12:13], v[0:1] neg_lo:[0,1] neg_hi:[0,1]
	s_nop 0
	v_xor_b32_e32 v12, 0x80000000, v1
	v_mov_b32_e32 v13, v0
	v_pk_add_f32 v[0:1], v[14:15], v[2:3]
	v_pk_add_f32 v[2:3], v[14:15], v[2:3] neg_lo:[0,1] neg_hi:[0,1]
	s_nop 0
	v_mul_f32_e32 v14, 0xbf3504f3, v3
	v_pk_fma_f32 v[2:3], v[2:3], s[44:45], v[14:15] op_sel_hi:[0,1,0]
	v_pk_add_f32 v[14:15], v[10:11], v[28:29]
	v_pk_add_f32 v[10:11], v[10:11], v[28:29] neg_lo:[0,1] neg_hi:[0,1]
	v_pk_add_f32 v[28:29], v[46:47], v[18:19]
	v_pk_add_f32 v[18:19], v[46:47], v[18:19] neg_lo:[0,1] neg_hi:[0,1]
	s_nop 0
	v_xor_b32_e32 v46, 0x80000000, v19
	v_mov_b32_e32 v47, v18
	v_pk_add_f32 v[18:19], v[26:27], v[30:31]
	v_pk_add_f32 v[26:27], v[26:27], v[30:31] neg_lo:[0,1] neg_hi:[0,1]
	v_pk_add_f32 v[30:31], v[4:5], v[8:9]
	v_pk_add_f32 v[4:5], v[4:5], v[8:9] neg_lo:[0,1] neg_hi:[0,1]
	s_nop 0
	v_xor_b32_e32 v8, 0x80000000, v5
	v_mov_b32_e32 v9, v4
	v_pk_add_f32 v[4:5], v[24:25], v[22:23]
	v_pk_add_f32 v[22:23], v[24:25], v[22:23] neg_lo:[0,1] neg_hi:[0,1]
	v_pk_add_f32 v[24:25], v[20:21], v[0:1]
	v_pk_add_f32 v[0:1], v[20:21], v[0:1] neg_lo:[0,1] neg_hi:[0,1]
	s_nop 0
	v_xor_b32_e32 v20, 0x80000000, v1
	v_mov_b32_e32 v21, v0
	v_pk_add_f32 v[0:1], v[16:17], v[12:13]
	v_pk_add_f32 v[12:13], v[16:17], v[12:13] neg_lo:[0,1] neg_hi:[0,1]
	v_pk_add_f32 v[16:17], v[6:7], v[2:3]
	v_pk_add_f32 v[2:3], v[6:7], v[2:3] neg_lo:[0,1] neg_hi:[0,1]
	s_nop 0
	v_xor_b32_e32 v6, 0x80000000, v3
	v_mov_b32_e32 v7, v2
	v_pk_add_f32 v[2:3], v[14:15], v[28:29]
	v_pk_add_f32 v[14:15], v[14:15], v[28:29] neg_lo:[0,1] neg_hi:[0,1]
	ds_write_b64 v152, v[2:3]
	v_pk_add_f32 v[28:29], v[10:11], v[46:47]
	ds_write_b64 v152, v[14:15] offset:64
	v_pk_add_f32 v[10:11], v[10:11], v[46:47] neg_lo:[0,1] neg_hi:[0,1]
	ds_write_b64 v152, v[28:29] offset:32
	v_pk_add_f32 v[46:47], v[18:19], v[30:31]
	ds_write_b64 v152, v[10:11] offset:96
	v_pk_add_f32 v[18:19], v[18:19], v[30:31] neg_lo:[0,1] neg_hi:[0,1]
	ds_write_b64 v152, v[46:47] offset:16
	v_pk_add_f32 v[30:31], v[26:27], v[8:9]
	ds_write_b64 v152, v[18:19] offset:80
	v_pk_add_f32 v[8:9], v[26:27], v[8:9] neg_lo:[0,1] neg_hi:[0,1]
	ds_write_b64 v152, v[30:31] offset:48
	v_pk_add_f32 v[26:27], v[4:5], v[24:25]
	ds_write_b64 v152, v[8:9] offset:112
	v_pk_add_f32 v[4:5], v[4:5], v[24:25] neg_lo:[0,1] neg_hi:[0,1]
	ds_write_b64 v152, v[26:27] offset:8
	v_pk_add_f32 v[24:25], v[22:23], v[20:21]
	ds_write_b64 v152, v[4:5] offset:72
	v_pk_add_f32 v[20:21], v[22:23], v[20:21] neg_lo:[0,1] neg_hi:[0,1]
	ds_write_b64 v152, v[24:25] offset:40
	v_pk_add_f32 v[22:23], v[0:1], v[16:17]
	ds_write_b64 v152, v[20:21] offset:104
	v_pk_add_f32 v[0:1], v[0:1], v[16:17] neg_lo:[0,1] neg_hi:[0,1]
	ds_write_b64 v152, v[22:23] offset:24
	v_pk_add_f32 v[16:17], v[12:13], v[6:7]
	ds_write_b64 v152, v[0:1] offset:88
	v_pk_add_f32 v[6:7], v[12:13], v[6:7] neg_lo:[0,1] neg_hi:[0,1]
	ds_write_b64 v152, v[16:17] offset:56
	ds_write_b64 v152, v[6:7] offset:120
	s_andn2_b64 exec, exec, s[92:93]
	s_cbranch_execnz .LBB0_356

.LBB0_359:
	v_ashrrev_i32_e32 v0, 7, v33
	v_mov_b32_e32 v16, v0
	v_add_u32_e32 v1, 0x200, v33
	v_cvt_f32_i32_e32 v16, v16
	v_ashrrev_i32_e32 v1, 7, v1
	v_mov_b32_e32 v54, v1
	v_lshl_add_u32 v55, v0, 3, v196
	v_mul_f32_e32 v17, 0x3c000000, v16
	v_cos_f32_e32 v16, v17
	v_sin_f32_e32 v17, v17
	v_lshl_add_u32 v66, v1, 3, v196
	v_mov_b32_e32 v39, v16
	v_mov_b32_e32 v18, v17
	v_xor_b32_e32 v38, 0x80000000, v17
	v_pk_mul_f32 v[18:19], v[38:39], v[18:19] op_sel_hi:[1,0]
	ds_read_b64 v[20:21], v55
	ds_read_b64 v[22:23], v55 offset:128
	ds_read_b64 v[0:1], v66
	ds_read_b64 v[2:3], v66 offset:128
	ds_read_b64 v[24:25], v55 offset:256
	ds_read_b64 v[26:27], v55 offset:384
	ds_read_b64 v[12:13], v66 offset:256
	ds_read_b64 v[14:15], v66 offset:384
	ds_read_b64 v[28:29], v55 offset:512
	ds_read_b64 v[30:31], v55 offset:640
	ds_read_b64 v[8:9], v66 offset:512
	ds_read_b64 v[10:11], v66 offset:640
	ds_read_b64 v[34:35], v55 offset:768
	ds_read_b64 v[36:37], v55 offset:896
	ds_read_b64 v[4:5], v66 offset:768
	ds_read_b64 v[6:7], v66 offset:896
	v_pk_fma_f32 v[18:19], v[16:17], v[16:17], v[18:19] op_sel_hi:[1,0,1]
	s_mov_b32 s40, s57
	v_pk_mul_f32 v[44:45], v[18:19], v[18:19] op_sel:[1,1] op_sel_hi:[1,0] neg_lo:[0,1]
	v_pk_mul_f32 v[40:41], v[38:39], v[18:19] op_sel:[0,1]
	v_pk_fma_f32 v[44:45], v[18:19], v[18:19], v[44:45] op_sel_hi:[1,0,1]
	v_pk_fma_f32 v[40:41], v[16:17], v[18:19], v[40:41] op_sel_hi:[1,0,1]
	v_pk_mul_f32 v[46:47], v[38:39], v[44:45] op_sel:[0,1]
	s_waitcnt lgkmcnt(14)
	v_pk_mul_f32 v[38:39], v[38:39], v[22:23] op_sel:[0,1]
	v_pk_fma_f32 v[46:47], v[16:17], v[44:45], v[46:47] op_sel_hi:[1,0,1]
	v_pk_fma_f32 v[38:39], v[16:17], v[22:23], v[38:39] op_sel_hi:[1,0,1]
	v_pk_mul_f32 v[48:49], v[18:19], v[44:45] op_sel:[1,1] op_sel_hi:[0,1] neg_lo:[1,0]
	s_waitcnt lgkmcnt(10)
	v_pk_mul_f32 v[16:17], v[24:25], v[18:19] op_sel:[1,1] op_sel_hi:[1,0] neg_lo:[0,1]
	s_waitcnt lgkmcnt(6)
	v_pk_mul_f32 v[22:23], v[28:29], v[44:45] op_sel:[1,1] op_sel_hi:[1,0] neg_lo:[0,1]
	v_pk_fma_f32 v[48:49], v[18:19], v[44:45], v[48:49] op_sel_hi:[1,0,1]
	v_pk_fma_f32 v[18:19], v[24:25], v[18:19], v[16:17] op_sel_hi:[0,1,1]
	v_pk_fma_f32 v[24:25], v[28:29], v[44:45], v[22:23] op_sel_hi:[0,1,1]
	v_pk_mul_f32 v[22:23], v[30:31], v[46:47] op_sel:[1,1] op_sel_hi:[1,0] neg_lo:[0,1]
	v_pk_mul_f32 v[52:53], v[44:45], v[40:41] op_sel:[1,1] op_sel_hi:[1,0] neg_lo:[0,1]
	v_pk_fma_f32 v[30:31], v[30:31], v[46:47], v[22:23] op_sel_hi:[0,1,1]
	v_pk_fma_f32 v[52:53], v[40:41], v[44:45], v[52:53] op_sel_hi:[1,0,1]
	v_pk_mul_f32 v[16:17], v[26:27], v[40:41] op_sel:[1,1] op_sel_hi:[1,0] neg_lo:[0,1]
	s_waitcnt lgkmcnt(2)
	v_pk_mul_f32 v[22:23], v[34:35], v[48:49] op_sel:[1,1] op_sel_hi:[1,0] neg_lo:[0,1]
	v_pk_fma_f32 v[16:17], v[26:27], v[40:41], v[16:17] op_sel_hi:[0,1,1]
	v_pk_fma_f32 v[26:27], v[34:35], v[48:49], v[22:23] op_sel_hi:[0,1,1]
	v_pk_mul_f32 v[22:23], v[36:37], v[52:53] op_sel:[1,1] op_sel_hi:[1,0] neg_lo:[0,1]
	v_pk_add_f32 v[34:35], v[18:19], v[26:27]
	v_pk_fma_f32 v[28:29], v[52:53], v[36:37], v[22:23] op_sel_hi:[1,0,1]
	v_pk_add_f32 v[18:19], v[18:19], v[26:27] neg_lo:[0,1] neg_hi:[0,1]
	v_pk_add_f32 v[22:23], v[20:21], v[24:25]
	v_pk_add_f32 v[20:21], v[20:21], v[24:25] neg_lo:[0,1] neg_hi:[0,1]
	v_pk_add_f32 v[24:25], v[38:39], v[30:31]
	v_pk_add_f32 v[30:31], v[38:39], v[30:31] neg_lo:[0,1] neg_hi:[0,1]
	v_xor_b32_e32 v26, 0x80000000, v19
	v_mov_b32_e32 v27, v18
	v_pk_add_f32 v[18:19], v[16:17], v[28:29]
	v_pk_add_f32 v[16:17], v[16:17], v[28:29] neg_lo:[0,1] neg_hi:[0,1]
	v_mul_f32_e32 v32, 0x3f3504f3, v30
	s_mov_b32 s41, s56
	v_mul_f32_e32 v28, 0xbf3504f3, v17
	v_pk_fma_f32 v[30:31], v[30:31], s[40:41], v[32:33] op_sel:[1,0,0] op_sel_hi:[1,1,0]
	v_pk_fma_f32 v[16:17], v[16:17], s[40:41], v[28:29] op_sel_hi:[0,1,0]
	v_pk_add_f32 v[28:29], v[22:23], v[34:35]
	v_pk_add_f32 v[22:23], v[22:23], v[34:35] neg_lo:[0,1] neg_hi:[0,1]
	v_pk_add_f32 v[34:35], v[24:25], v[18:19]
	v_pk_add_f32 v[18:19], v[24:25], v[18:19] neg_lo:[0,1] neg_hi:[0,1]
	v_cmp_lt_i32_e32 vcc, s28, v33
	v_xor_b32_e32 v24, 0x80000000, v19
	v_mov_b32_e32 v25, v18
	v_pk_add_f32 v[18:19], v[20:21], v[26:27]
	v_pk_add_f32 v[20:21], v[20:21], v[26:27] neg_lo:[0,1] neg_hi:[0,1]
	v_pk_add_f32 v[26:27], v[30:31], v[16:17]
	v_pk_add_f32 v[16:17], v[30:31], v[16:17] neg_lo:[0,1] neg_hi:[0,1]
	s_or_b64 s[92:93], vcc, s[92:93]
	v_xor_b32_e32 v30, 0x80000000, v17
	v_mov_b32_e32 v31, v16
	v_pk_add_f32 v[16:17], v[28:29], v[34:35]
	v_pk_add_f32 v[28:29], v[28:29], v[34:35] neg_lo:[0,1] neg_hi:[0,1]
	v_pk_add_f32 v[34:35], v[22:23], v[24:25]
	v_pk_add_f32 v[22:23], v[22:23], v[24:25] neg_lo:[0,1] neg_hi:[0,1]
	v_pk_add_f32 v[24:25], v[18:19], v[26:27]
	v_pk_add_f32 v[18:19], v[18:19], v[26:27] neg_lo:[0,1] neg_hi:[0,1]
	v_pk_add_f32 v[26:27], v[20:21], v[30:31]
	v_pk_add_f32 v[20:21], v[20:21], v[30:31] neg_lo:[0,1] neg_hi:[0,1]
	v_cvt_f32_i32_e32 v30, v54
	v_mul_f32_e32 v31, 0x3c000000, v30
	v_cos_f32_e32 v30, v31
	v_sin_f32_e32 v31, v31
	v_mov_b32_e32 v37, v30
	v_mov_b32_e32 v32, v31
	v_xor_b32_e32 v36, 0x80000000, v31
	v_pk_mul_f32 v[38:39], v[36:37], v[32:33] op_sel_hi:[1,0]
	v_add_u32_e32 v33, 0x400, v33
	v_pk_fma_f32 v[38:39], v[30:31], v[30:31], v[38:39] op_sel_hi:[1,0,1]
	s_nop 0
	v_xor_b32_e32 v42, 0x80000000, v39
	v_mov_b32_e32 v43, v38
	v_pk_mul_f32 v[44:45], v[38:39], v[42:43] op_sel:[1,0]
	v_pk_mul_f32 v[40:41], v[36:37], v[38:39] op_sel:[0,1]
	v_pk_fma_f32 v[44:45], v[38:39], v[38:39], v[44:45] op_sel_hi:[1,0,1]
	v_pk_fma_f32 v[40:41], v[30:31], v[38:39], v[40:41] op_sel_hi:[1,0,1]
	v_pk_mul_f32 v[46:47], v[36:37], v[44:45] op_sel:[0,1]
	v_pk_mul_f32 v[36:37], v[36:37], v[2:3] op_sel:[0,1]
	v_pk_fma_f32 v[46:47], v[30:31], v[44:45], v[46:47] op_sel_hi:[1,0,1]
	v_xor_b32_e32 v50, 0x80000000, v41
	v_mov_b32_e32 v51, v40
	v_pk_fma_f32 v[2:3], v[30:31], v[2:3], v[36:37] op_sel_hi:[1,0,1]
	v_pk_mul_f32 v[30:31], v[12:13], v[42:43] op_sel:[1,0]
	v_pk_mul_f32 v[48:49], v[42:43], v[44:45] op_sel:[0,1]
	v_pk_fma_f32 v[12:13], v[12:13], v[38:39], v[30:31] op_sel_hi:[0,1,1]
	v_pk_mul_f32 v[30:31], v[14:15], v[50:51] op_sel:[1,0]
	v_pk_fma_f32 v[48:49], v[38:39], v[44:45], v[48:49] op_sel_hi:[1,0,1]
	v_pk_fma_f32 v[14:15], v[14:15], v[40:41], v[30:31] op_sel_hi:[0,1,1]
	v_pk_mul_f32 v[30:31], v[8:9], v[44:45] op_sel:[1,1] op_sel_hi:[1,0] neg_lo:[0,1]
	v_pk_mul_f32 v[52:53], v[44:45], v[50:51] op_sel:[1,0]
	v_pk_fma_f32 v[8:9], v[8:9], v[44:45], v[30:31] op_sel_hi:[0,1,1]
	v_pk_mul_f32 v[30:31], v[10:11], v[46:47] op_sel:[1,1] op_sel_hi:[1,0] neg_lo:[0,1]
	v_pk_fma_f32 v[52:53], v[40:41], v[44:45], v[52:53] op_sel_hi:[1,0,1]
	v_pk_fma_f32 v[10:11], v[10:11], v[46:47], v[30:31] op_sel_hi:[0,1,1]
	s_waitcnt lgkmcnt(0)
	ds_write_b64 v55, v[16:17]
	ds_write_b64 v55, v[28:29] offset:512
	ds_write_b64 v55, v[34:35] offset:256
	ds_write_b64 v55, v[22:23] offset:768
	ds_write_b64 v55, v[24:25] offset:128
	ds_write_b64 v55, v[18:19] offset:640
	ds_write_b64 v55, v[26:27] offset:384
	ds_write_b64 v55, v[20:21] offset:896
	v_pk_mul_f32 v[30:31], v[4:5], v[48:49] op_sel:[1,1] op_sel_hi:[1,0] neg_lo:[0,1]
	s_nop 0
	v_pk_fma_f32 v[4:5], v[4:5], v[48:49], v[30:31] op_sel_hi:[0,1,1]
	v_pk_mul_f32 v[30:31], v[6:7], v[52:53] op_sel:[1,1] op_sel_hi:[1,0] neg_lo:[0,1]
	s_nop 0
	v_pk_fma_f32 v[6:7], v[52:53], v[6:7], v[30:31] op_sel_hi:[1,0,1]
	v_pk_add_f32 v[30:31], v[0:1], v[8:9]
	v_pk_add_f32 v[0:1], v[0:1], v[8:9] neg_lo:[0,1] neg_hi:[0,1]
	v_pk_add_f32 v[8:9], v[2:3], v[10:11]
	v_pk_add_f32 v[2:3], v[2:3], v[10:11] neg_lo:[0,1] neg_hi:[0,1]
	s_nop 0
	v_mul_f32_e32 v10, 0x3f3504f3, v2
	v_pk_fma_f32 v[2:3], v[2:3], s[40:41], v[10:11] op_sel:[1,0,0] op_sel_hi:[1,1,0]
	v_pk_add_f32 v[10:11], v[12:13], v[4:5]
	v_pk_add_f32 v[4:5], v[12:13], v[4:5] neg_lo:[0,1] neg_hi:[0,1]
	s_nop 0
	v_xor_b32_e32 v12, 0x80000000, v5
	v_mov_b32_e32 v13, v4
	v_pk_add_f32 v[4:5], v[14:15], v[6:7]
	v_pk_add_f32 v[6:7], v[14:15], v[6:7] neg_lo:[0,1] neg_hi:[0,1]
	s_nop 0
	v_mul_f32_e32 v14, 0xbf3504f3, v7
	v_pk_fma_f32 v[6:7], v[6:7], s[40:41], v[14:15] op_sel_hi:[0,1,0]
	v_pk_add_f32 v[14:15], v[30:31], v[10:11]
	v_pk_add_f32 v[10:11], v[30:31], v[10:11] neg_lo:[0,1] neg_hi:[0,1]
	v_pk_add_f32 v[30:31], v[8:9], v[4:5]
	v_pk_add_f32 v[4:5], v[8:9], v[4:5] neg_lo:[0,1] neg_hi:[0,1]
	s_nop 0
	v_xor_b32_e32 v8, 0x80000000, v5
	v_mov_b32_e32 v9, v4
	v_pk_add_f32 v[4:5], v[0:1], v[12:13]
	v_pk_add_f32 v[0:1], v[0:1], v[12:13] neg_lo:[0,1] neg_hi:[0,1]
	v_pk_add_f32 v[12:13], v[2:3], v[6:7]
	v_pk_add_f32 v[2:3], v[2:3], v[6:7] neg_lo:[0,1] neg_hi:[0,1]
	s_nop 0
	v_xor_b32_e32 v6, 0x80000000, v3
	v_mov_b32_e32 v7, v2
	v_pk_add_f32 v[2:3], v[14:15], v[30:31]
	v_pk_add_f32 v[14:15], v[14:15], v[30:31] neg_lo:[0,1] neg_hi:[0,1]
	ds_write_b64 v66, v[2:3]
	v_pk_add_f32 v[30:31], v[10:11], v[8:9]
	ds_write_b64 v66, v[14:15] offset:512
	v_pk_add_f32 v[8:9], v[10:11], v[8:9] neg_lo:[0,1] neg_hi:[0,1]
	ds_write_b64 v66, v[30:31] offset:256
	v_pk_add_f32 v[10:11], v[4:5], v[12:13]
	ds_write_b64 v66, v[8:9] offset:768
	v_pk_add_f32 v[4:5], v[4:5], v[12:13] neg_lo:[0,1] neg_hi:[0,1]
	ds_write_b64 v66, v[10:11] offset:128
	v_pk_add_f32 v[12:13], v[0:1], v[6:7]
	ds_write_b64 v66, v[4:5] offset:640
	v_pk_add_f32 v[0:1], v[0:1], v[6:7] neg_lo:[0,1] neg_hi:[0,1]
	ds_write_b64 v66, v[12:13] offset:384
	ds_write_b64 v66, v[0:1] offset:896
	s_andn2_b64 exec, exec, s[92:93]
	s_cbranch_execnz .LBB0_359

.LBB0_362:
	v_lshrrev_b32_e32 v0, 3, v66
	v_and_b32_e32 v0, 0x1ffffff0, v0
	v_mov_b32_e32 v48, v65
	v_mad_u64_u32 v[32:33], s[40:41], v0, s25, v[60:61]
	v_add_u32_e32 v1, 0x200, v66
	v_cvt_f32_i32_e32 v33, v48
	v_lshrrev_b32_e32 v1, 3, v1
	v_and_b32_e32 v1, 0x1ffffff0, v1
	v_mov_b32_e32 v148, v65
	v_mul_f32_e32 v33, 0x3a000000, v33
	v_cos_f32_e32 v48, v33
	v_sin_f32_e32 v49, v33
	v_mad_u64_u32 v[34:35], s[40:41], v1, s25, v[60:61]
	v_mov_b32_e32 v53, v48
	v_mov_b32_e32 v50, v49
	v_xor_b32_e32 v52, 0x80000000, v49
	v_pk_mul_f32 v[50:51], v[52:53], v[50:51] op_sel_hi:[1,0]
	v_add_u32_e32 v4, 0x800, v32
	v_pk_fma_f32 v[50:51], v[48:49], v[48:49], v[50:51] op_sel_hi:[1,0,1]
	ds_read_b64 v[36:37], v32
	ds_read_b64 v[38:39], v32 offset:1032
	ds_read_b64 v[0:1], v34
	ds_read_b64 v[2:3], v34 offset:1032
	v_pk_mul_f32 v[142:143], v[50:51], v[50:51] op_sel:[1,1] op_sel_hi:[1,0] neg_lo:[0,1]
	v_pk_mul_f32 v[54:55], v[52:53], v[50:51] op_sel:[0,1]
	v_pk_fma_f32 v[162:163], v[50:51], v[50:51], v[142:143] op_sel_hi:[1,0,1]
	v_pk_fma_f32 v[54:55], v[48:49], v[50:51], v[54:55] op_sel_hi:[1,0,1]
	v_pk_mul_f32 v[142:143], v[52:53], v[162:163] op_sel:[0,1]
	v_pk_fma_f32 v[164:165], v[48:49], v[162:163], v[142:143] op_sel_hi:[1,0,1]
	v_pk_mul_f32 v[142:143], v[50:51], v[162:163] op_sel:[1,1] op_sel_hi:[0,1] neg_lo:[1,0]
	v_pk_fma_f32 v[166:167], v[50:51], v[162:163], v[142:143] op_sel_hi:[1,0,1]
	v_pk_mul_f32 v[142:143], v[162:163], v[54:55] op_sel:[1,1] op_sel_hi:[1,0] neg_lo:[0,1]
	v_pk_fma_f32 v[172:173], v[54:55], v[162:163], v[142:143] op_sel_hi:[1,0,1]
	v_pk_mul_f32 v[142:143], v[162:163], v[162:163] op_sel:[1,1] op_sel_hi:[1,0] neg_lo:[0,1]
	ds_read_b64 v[40:41], v4 offset:16
	ds_read_b64 v[42:43], v4 offset:1048
	v_pk_fma_f32 v[176:177], v[162:163], v[162:163], v[142:143] op_sel_hi:[1,0,1]
	v_add_u32_e32 v4, 0x800, v34
	v_pk_mul_f32 v[142:143], v[52:53], v[176:177] op_sel:[0,1]
	ds_read_b64 v[20:21], v4 offset:16
	ds_read_b64 v[22:23], v4 offset:1048
	v_pk_fma_f32 v[178:179], v[48:49], v[176:177], v[142:143] op_sel_hi:[1,0,1]
	v_pk_mul_f32 v[142:143], v[50:51], v[176:177] op_sel:[1,1] op_sel_hi:[0,1] neg_lo:[1,0]
	v_add_u32_e32 v4, 0x1000, v32
	v_pk_fma_f32 v[180:181], v[50:51], v[176:177], v[142:143] op_sel_hi:[1,0,1]
	v_pk_mul_f32 v[142:143], v[54:55], v[176:177] op_sel:[1,1] op_sel_hi:[0,1] neg_lo:[1,0]
	ds_read_b64 v[44:45], v4 offset:32
	ds_read_b64 v[46:47], v4 offset:1064
	v_add_u32_e32 v4, 0x1000, v34
	v_pk_fma_f32 v[182:183], v[54:55], v[176:177], v[142:143] op_sel_hi:[1,0,1]
	v_pk_mul_f32 v[142:143], v[162:163], v[176:177] op_sel:[1,1] op_sel_hi:[0,1] neg_lo:[1,0]
	ds_read_b64 v[24:25], v4 offset:32
	ds_read_b64 v[26:27], v4 offset:1064
	v_add_u32_e32 v4, 0x1800, v32
	v_pk_fma_f32 v[184:185], v[162:163], v[176:177], v[142:143] op_sel_hi:[1,0,1]
	v_pk_mul_f32 v[142:143], v[176:177], v[164:165] op_sel:[1,1] op_sel_hi:[1,0] neg_lo:[0,1]
	ds_read_b64 v[136:137], v4 offset:48
	ds_read_b64 v[138:139], v4 offset:1080
	v_pk_fma_f32 v[188:189], v[164:165], v[176:177], v[142:143] op_sel_hi:[1,0,1]
	v_pk_mul_f32 v[142:143], v[176:177], v[166:167] op_sel:[1,1] op_sel_hi:[1,0] neg_lo:[0,1]
	v_xor_b32_e32 v194, 0x80000000, v173
	v_mov_b32_e32 v195, v172
	s_waitcnt lgkmcnt(12)
	v_pk_mul_f32 v[52:53], v[52:53], v[38:39] op_sel:[0,1]
	v_add_u32_e32 v4, 0x1800, v34
	v_pk_fma_f32 v[192:193], v[166:167], v[176:177], v[142:143] op_sel_hi:[1,0,1]
	v_pk_mul_f32 v[142:143], v[176:177], v[194:195] op_sel:[1,0]
	v_pk_fma_f32 v[218:219], v[48:49], v[38:39], v[52:53] op_sel_hi:[1,0,1]
	s_waitcnt lgkmcnt(8)
	v_pk_mul_f32 v[38:39], v[40:41], v[50:51] op_sel:[1,1] op_sel_hi:[1,0] neg_lo:[0,1]
	ds_read_b64 v[28:29], v4 offset:48
	ds_read_b64 v[30:31], v4 offset:1080
	v_add_u32_e32 v4, 0x2000, v32
	v_pk_fma_f32 v[216:217], v[172:173], v[176:177], v[142:143] op_sel_hi:[1,0,1]
	v_pk_fma_f32 v[142:143], v[40:41], v[50:51], v[38:39] op_sel_hi:[0,1,1]
	v_pk_mul_f32 v[38:39], v[42:43], v[54:55] op_sel:[1,1] op_sel_hi:[1,0] neg_lo:[0,1]
	ds_read_b64 v[144:145], v4 offset:64
	ds_read_b64 v[146:147], v4 offset:1096
	v_pk_fma_f32 v[54:55], v[42:43], v[54:55], v[38:39] op_sel_hi:[0,1,1]
	s_waitcnt lgkmcnt(8)
	v_pk_mul_f32 v[38:39], v[44:45], v[162:163] op_sel:[1,1] op_sel_hi:[1,0] neg_lo:[0,1]
	v_add_u32_e32 v4, 0x2000, v34
	v_pk_fma_f32 v[52:53], v[44:45], v[162:163], v[38:39] op_sel_hi:[0,1,1]
	v_pk_mul_f32 v[38:39], v[46:47], v[164:165] op_sel:[1,1] op_sel_hi:[1,0] neg_lo:[0,1]
	ds_read_b64 v[16:17], v4 offset:64
	ds_read_b64 v[18:19], v4 offset:1096
	v_pk_fma_f32 v[50:51], v[46:47], v[164:165], v[38:39] op_sel_hi:[0,1,1]
	s_waitcnt lgkmcnt(6)
	v_pk_mul_f32 v[38:39], v[136:137], v[166:167] op_sel:[1,1] op_sel_hi:[1,0] neg_lo:[0,1]
	v_add_u32_e32 v4, 0x2800, v32
	v_pk_fma_f32 v[44:45], v[136:137], v[166:167], v[38:39] op_sel_hi:[0,1,1]
	v_pk_mul_f32 v[38:39], v[138:139], v[194:195] op_sel:[1,0]
	ds_read_b64 v[150:151], v4 offset:80
	ds_read_b64 v[152:153], v4 offset:1112
	v_pk_fma_f32 v[42:43], v[172:173], v[138:139], v[38:39] op_sel_hi:[1,0,1]
	s_waitcnt lgkmcnt(4)
	v_pk_mul_f32 v[38:39], v[144:145], v[176:177] op_sel:[1,1] op_sel_hi:[1,0] neg_lo:[0,1]
	v_add_u32_e32 v4, 0x2800, v34
	v_pk_fma_f32 v[40:41], v[176:177], v[144:145], v[38:39] op_sel_hi:[1,0,1]
	ds_read_b64 v[12:13], v4 offset:80
	ds_read_b64 v[14:15], v4 offset:1112
	v_add_u32_e32 v4, 0x3000, v32
	v_pk_mul_f32 v[38:39], v[146:147], v[178:179] op_sel:[1,1] op_sel_hi:[1,0] neg_lo:[0,1]
	ds_read_b64 v[154:155], v4 offset:96
	ds_read_b64 v[156:157], v4 offset:1128
	v_pk_fma_f32 v[146:147], v[178:179], v[146:147], v[38:39] op_sel_hi:[1,0,1]
	s_waitcnt lgkmcnt(4)
	v_pk_mul_f32 v[38:39], v[150:151], v[180:181] op_sel:[1,1] op_sel_hi:[1,0] neg_lo:[0,1]
	v_add_u32_e32 v4, 0x3000, v34
	v_pk_fma_f32 v[144:145], v[180:181], v[150:151], v[38:39] op_sel_hi:[1,0,1]
	ds_read_b64 v[8:9], v4 offset:96
	ds_read_b64 v[10:11], v4 offset:1128
	v_add_u32_e32 v4, 0x3800, v32
	v_pk_mul_f32 v[38:39], v[182:183], v[152:153] op_sel:[1,1] op_sel_hi:[0,1] neg_lo:[1,0]
	ds_read_b64 v[158:159], v4 offset:112
	ds_read_b64 v[160:161], v4 offset:1144
	v_pk_fma_f32 v[140:141], v[182:183], v[152:153], v[38:39] op_sel_hi:[1,0,1]
	s_waitcnt lgkmcnt(4)
	v_pk_mul_f32 v[38:39], v[184:185], v[154:155] op_sel:[1,1] op_sel_hi:[0,1] neg_lo:[1,0]
	s_mov_b32 s96, s43
	v_pk_fma_f32 v[136:137], v[184:185], v[154:155], v[38:39] op_sel_hi:[1,0,1]
	v_pk_mul_f32 v[38:39], v[188:189], v[156:157] op_sel:[1,1] op_sel_hi:[0,1] neg_lo:[1,0]
	s_mov_b32 s97, s42
	v_pk_fma_f32 v[138:139], v[188:189], v[156:157], v[38:39] op_sel_hi:[1,0,1]
	s_waitcnt lgkmcnt(0)
	v_pk_mul_f32 v[38:39], v[192:193], v[158:159] op_sel:[1,1] op_sel_hi:[0,1] neg_lo:[1,0]
	s_mov_b32 s58, s42
	v_pk_fma_f32 v[46:47], v[192:193], v[158:159], v[38:39] op_sel_hi:[1,0,1]
	v_pk_mul_f32 v[38:39], v[216:217], v[160:161] op_sel:[1,1] op_sel_hi:[0,1] neg_lo:[1,0]
	s_mov_b32 s59, s64
	v_pk_fma_f32 v[48:49], v[216:217], v[160:161], v[38:39] op_sel_hi:[1,0,1]
	v_pk_add_f32 v[38:39], v[36:37], v[40:41]
	v_pk_add_f32 v[36:37], v[36:37], v[40:41] neg_lo:[0,1] neg_hi:[0,1]
	v_pk_add_f32 v[40:41], v[218:219], v[146:147]
	v_pk_add_f32 v[146:147], v[218:219], v[146:147] neg_lo:[0,1] neg_hi:[0,1]
	s_mov_b32 s94, s57
	v_pk_mul_f32 v[150:151], v[146:147], s[96:97] op_sel:[1,0]
	s_mov_b32 s95, s56
	v_pk_fma_f32 v[146:147], v[146:147], s[58:59], v[150:151] op_sel_hi:[0,1,1]
	v_pk_add_f32 v[150:151], v[142:143], v[144:145]
	v_pk_add_f32 v[142:143], v[142:143], v[144:145] neg_lo:[0,1] neg_hi:[0,1]
	s_mov_b32 s44, s67
	v_mul_f32_e32 v144, 0x3f3504f3, v142
	v_pk_fma_f32 v[142:143], v[142:143], s[94:95], v[144:145] op_sel:[1,0,0] op_sel_hi:[1,1,0]
	v_pk_add_f32 v[144:145], v[54:55], v[140:141]
	v_pk_add_f32 v[54:55], v[54:55], v[140:141] neg_lo:[0,1] neg_hi:[0,1]
	s_mov_b32 s45, s64
	s_mov_b32 s65, s42
	v_pk_mul_f32 v[140:141], v[54:55], s[44:45] op_sel:[1,0]
	s_mov_b32 s40, s67
	v_pk_fma_f32 v[54:55], v[54:55], s[64:65], v[140:141] op_sel_hi:[0,1,1]
	v_pk_add_f32 v[140:141], v[52:53], v[136:137]
	v_pk_add_f32 v[52:53], v[52:53], v[136:137] neg_lo:[0,1] neg_hi:[0,1]
	s_mov_b32 s41, s43
	v_xor_b32_e32 v136, 0x80000000, v53
	v_mov_b32_e32 v137, v52
	v_pk_add_f32 v[52:53], v[50:51], v[138:139]
	v_pk_add_f32 v[50:51], v[50:51], v[138:139] neg_lo:[0,1] neg_hi:[0,1]
	s_mov_b32 s66, s43
	v_pk_mul_f32 v[138:139], v[50:51], s[40:41] op_sel:[1,0]
	v_cvt_f32_i32_e32 v33, v148
	v_pk_fma_f32 v[50:51], v[50:51], s[96:97], v[138:139] op_sel_hi:[0,1,1]
	v_pk_add_f32 v[138:139], v[44:45], v[46:47]
	v_pk_add_f32 v[44:45], v[44:45], v[46:47] neg_lo:[0,1] neg_hi:[0,1]
	v_mul_f32_e32 v33, 0x3a000000, v33
	v_mul_f32_e32 v46, 0xbf3504f3, v45
	v_pk_fma_f32 v[44:45], v[44:45], s[94:95], v[46:47] op_sel_hi:[0,1,0]
	v_pk_add_f32 v[46:47], v[42:43], v[48:49]
	v_pk_add_f32 v[42:43], v[42:43], v[48:49] neg_lo:[0,1] neg_hi:[0,1]
	v_add_u32_e32 v4, 0x3800, v34
	v_pk_mul_f32 v[48:49], v[42:43], s[66:67] op_sel:[1,0]
	ds_read_b64 v[6:7], v4 offset:1144
	ds_read_b64 v[4:5], v4 offset:112
	v_pk_fma_f32 v[42:43], v[42:43], s[44:45], v[48:49] op_sel_hi:[0,1,1]
	v_pk_add_f32 v[48:49], v[38:39], v[140:141]
	v_pk_add_f32 v[38:39], v[38:39], v[140:141] neg_lo:[0,1] neg_hi:[0,1]
	v_pk_add_f32 v[140:141], v[40:41], v[52:53]
	v_pk_add_f32 v[40:41], v[40:41], v[52:53] neg_lo:[0,1] neg_hi:[0,1]
	v_cmp_lt_i32_e32 vcc, -1, v66
	v_mul_f32_e32 v52, 0x3f3504f3, v40
	v_pk_fma_f32 v[40:41], v[40:41], s[94:95], v[52:53] op_sel:[1,0,0] op_sel_hi:[1,1,0]
	v_pk_add_f32 v[52:53], v[150:151], v[138:139]
	v_pk_add_f32 v[138:139], v[150:151], v[138:139] neg_lo:[0,1] neg_hi:[0,1]
	v_add_u32_e32 v66, 0x400, v66
	v_xor_b32_e32 v150, 0x80000000, v139
	v_mov_b32_e32 v151, v138
	v_pk_add_f32 v[138:139], v[144:145], v[46:47]
	v_pk_add_f32 v[46:47], v[144:145], v[46:47] neg_lo:[0,1] neg_hi:[0,1]
	s_or_b64 s[92:93], vcc, s[92:93]
	v_mul_f32_e32 v144, 0xbf3504f3, v47
	v_pk_fma_f32 v[46:47], v[46:47], s[94:95], v[144:145] op_sel_hi:[0,1,0]
	v_pk_add_f32 v[144:145], v[36:37], v[136:137]
	v_pk_add_f32 v[36:37], v[36:37], v[136:137] neg_lo:[0,1] neg_hi:[0,1]
	v_pk_add_f32 v[136:137], v[146:147], v[50:51]
	v_pk_add_f32 v[50:51], v[146:147], v[50:51] neg_lo:[0,1] neg_hi:[0,1]
	s_nop 0
	v_mul_f32_e32 v146, 0x3f3504f3, v50
	v_pk_fma_f32 v[50:51], v[50:51], s[94:95], v[146:147] op_sel:[1,0,0] op_sel_hi:[1,1,0]
	v_pk_add_f32 v[146:147], v[142:143], v[44:45]
	v_pk_add_f32 v[44:45], v[142:143], v[44:45] neg_lo:[0,1] neg_hi:[0,1]
	s_nop 0
	v_xor_b32_e32 v142, 0x80000000, v45
	v_mov_b32_e32 v143, v44
	v_pk_add_f32 v[44:45], v[54:55], v[42:43]
	v_pk_add_f32 v[42:43], v[54:55], v[42:43] neg_lo:[0,1] neg_hi:[0,1]
	s_nop 0
	v_mul_f32_e32 v54, 0xbf3504f3, v43
	v_pk_fma_f32 v[42:43], v[42:43], s[94:95], v[54:55] op_sel_hi:[0,1,0]
	v_pk_add_f32 v[54:55], v[48:49], v[52:53]
	v_pk_add_f32 v[48:49], v[48:49], v[52:53] neg_lo:[0,1] neg_hi:[0,1]
	v_pk_add_f32 v[52:53], v[140:141], v[138:139]
	v_pk_add_f32 v[138:139], v[140:141], v[138:139] neg_lo:[0,1] neg_hi:[0,1]
	s_nop 0
	v_xor_b32_e32 v140, 0x80000000, v139
	v_mov_b32_e32 v141, v138
	v_pk_add_f32 v[138:139], v[38:39], v[150:151]
	v_pk_add_f32 v[38:39], v[38:39], v[150:151] neg_lo:[0,1] neg_hi:[0,1]
	v_pk_add_f32 v[150:151], v[40:41], v[46:47]
	v_pk_add_f32 v[40:41], v[40:41], v[46:47] neg_lo:[0,1] neg_hi:[0,1]
	s_nop 0
	v_xor_b32_e32 v46, 0x80000000, v41
	v_mov_b32_e32 v47, v40
	v_pk_add_f32 v[40:41], v[144:145], v[146:147]
	v_pk_add_f32 v[144:145], v[144:145], v[146:147] neg_lo:[0,1] neg_hi:[0,1]
	v_pk_add_f32 v[146:147], v[136:137], v[44:45]
	v_pk_add_f32 v[44:45], v[136:137], v[44:45] neg_lo:[0,1] neg_hi:[0,1]
	s_nop 0
	v_xor_b32_e32 v136, 0x80000000, v45
	v_mov_b32_e32 v137, v44
	v_pk_add_f32 v[44:45], v[36:37], v[142:143]
	v_pk_add_f32 v[36:37], v[36:37], v[142:143] neg_lo:[0,1] neg_hi:[0,1]
	v_pk_add_f32 v[142:143], v[50:51], v[42:43]
	v_pk_add_f32 v[42:43], v[50:51], v[42:43] neg_lo:[0,1] neg_hi:[0,1]
	s_nop 0
	v_xor_b32_e32 v50, 0x80000000, v43
	v_mov_b32_e32 v51, v42
	v_pk_add_f32 v[42:43], v[54:55], v[52:53]
	v_pk_add_f32 v[52:53], v[54:55], v[52:53] neg_lo:[0,1] neg_hi:[0,1]
	v_pk_add_f32 v[54:55], v[48:49], v[140:141]
	v_pk_add_f32 v[48:49], v[48:49], v[140:141] neg_lo:[0,1] neg_hi:[0,1]
	v_pk_add_f32 v[140:141], v[138:139], v[150:151]
	v_pk_add_f32 v[138:139], v[138:139], v[150:151] neg_lo:[0,1] neg_hi:[0,1]
	v_pk_add_f32 v[150:151], v[38:39], v[46:47]
	v_pk_add_f32 v[38:39], v[38:39], v[46:47] neg_lo:[0,1] neg_hi:[0,1]
	v_pk_add_f32 v[46:47], v[40:41], v[146:147]
	v_pk_add_f32 v[40:41], v[40:41], v[146:147] neg_lo:[0,1] neg_hi:[0,1]
	v_pk_add_f32 v[146:147], v[144:145], v[136:137]
	v_pk_add_f32 v[136:137], v[144:145], v[136:137] neg_lo:[0,1] neg_hi:[0,1]
	v_pk_add_f32 v[144:145], v[44:45], v[142:143]
	v_pk_add_f32 v[44:45], v[44:45], v[142:143] neg_lo:[0,1] neg_hi:[0,1]
	v_pk_add_f32 v[142:143], v[36:37], v[50:51]
	v_pk_add_f32 v[36:37], v[36:37], v[50:51] neg_lo:[0,1] neg_hi:[0,1]
	v_cos_f32_e32 v50, v33
	v_sin_f32_e32 v51, v33
	v_mov_b32_e32 v153, v50
	v_mov_b32_e32 v148, v51
	v_xor_b32_e32 v152, 0x80000000, v51
	v_pk_mul_f32 v[148:149], v[152:153], v[148:149] op_sel_hi:[1,0]
	s_nop 0
	v_pk_fma_f32 v[148:149], v[50:51], v[50:51], v[148:149] op_sel_hi:[1,0,1]
	s_nop 0
	v_xor_b32_e32 v156, 0x80000000, v149
	v_mov_b32_e32 v157, v148
	v_pk_mul_f32 v[158:159], v[148:149], v[156:157] op_sel:[1,0]
	v_pk_mul_f32 v[154:155], v[152:153], v[148:149] op_sel:[0,1]
	v_pk_fma_f32 v[158:159], v[148:149], v[148:149], v[158:159] op_sel_hi:[1,0,1]
	v_pk_fma_f32 v[154:155], v[50:51], v[148:149], v[154:155] op_sel_hi:[1,0,1]
	v_xor_b32_e32 v170, 0x80000000, v159
	v_mov_b32_e32 v171, v158
	v_pk_mul_f32 v[172:173], v[158:159], v[170:171] op_sel:[1,0]
	v_pk_mul_f32 v[160:161], v[152:153], v[158:159] op_sel:[0,1]
	v_pk_fma_f32 v[172:173], v[158:159], v[158:159], v[172:173] op_sel_hi:[1,0,1]
	v_pk_fma_f32 v[160:161], v[50:51], v[158:159], v[160:161] op_sel_hi:[1,0,1]
	v_pk_mul_f32 v[174:175], v[152:153], v[172:173] op_sel:[0,1]
	v_pk_mul_f32 v[152:153], v[152:153], v[2:3] op_sel:[0,1]
	v_xor_b32_e32 v164, 0x80000000, v155
	v_mov_b32_e32 v165, v154
	v_pk_fma_f32 v[174:175], v[50:51], v[172:173], v[174:175] op_sel_hi:[1,0,1]
	v_pk_fma_f32 v[2:3], v[50:51], v[2:3], v[152:153] op_sel_hi:[1,0,1]
	v_pk_mul_f32 v[50:51], v[20:21], v[156:157] op_sel:[1,0]
	v_pk_mul_f32 v[162:163], v[156:157], v[158:159] op_sel:[0,1]
	v_pk_fma_f32 v[20:21], v[20:21], v[148:149], v[50:51] op_sel_hi:[0,1,1]
	v_pk_mul_f32 v[50:51], v[22:23], v[164:165] op_sel:[1,0]
	v_pk_fma_f32 v[162:163], v[148:149], v[158:159], v[162:163] op_sel_hi:[1,0,1]
	v_pk_mul_f32 v[166:167], v[158:159], v[164:165] op_sel:[1,0]
	v_xor_b32_e32 v182, 0x80000000, v161
	v_mov_b32_e32 v183, v160
	v_pk_fma_f32 v[22:23], v[22:23], v[154:155], v[50:51] op_sel_hi:[0,1,1]
	v_pk_mul_f32 v[50:51], v[24:25], v[170:171] op_sel:[1,0]
	v_pk_fma_f32 v[166:167], v[154:155], v[158:159], v[166:167] op_sel_hi:[1,0,1]
	v_xor_b32_e32 v186, 0x80000000, v163
	v_mov_b32_e32 v187, v162
	v_pk_fma_f32 v[24:25], v[24:25], v[158:159], v[50:51] op_sel_hi:[0,1,1]
	v_pk_mul_f32 v[50:51], v[26:27], v[182:183] op_sel:[1,0]
	v_xor_b32_e32 v190, 0x80000000, v167
	v_mov_b32_e32 v191, v166
	v_pk_fma_f32 v[26:27], v[26:27], v[160:161], v[50:51] op_sel_hi:[0,1,1]
	v_pk_mul_f32 v[50:51], v[28:29], v[186:187] op_sel:[1,0]
	v_pk_mul_f32 v[176:177], v[156:157], v[172:173] op_sel:[0,1]
	v_pk_fma_f32 v[28:29], v[28:29], v[162:163], v[50:51] op_sel_hi:[0,1,1]
	v_pk_mul_f32 v[50:51], v[30:31], v[190:191] op_sel:[1,0]
	v_pk_fma_f32 v[176:177], v[148:149], v[172:173], v[176:177] op_sel_hi:[1,0,1]
	v_pk_fma_f32 v[30:31], v[166:167], v[30:31], v[50:51] op_sel_hi:[1,0,1]
	v_pk_mul_f32 v[50:51], v[16:17], v[172:173] op_sel:[1,1] op_sel_hi:[1,0] neg_lo:[0,1]
	v_pk_mul_f32 v[178:179], v[164:165], v[172:173] op_sel:[0,1]
	v_pk_fma_f32 v[16:17], v[172:173], v[16:17], v[50:51] op_sel_hi:[1,0,1]
	v_pk_mul_f32 v[50:51], v[18:19], v[174:175] op_sel:[1,1] op_sel_hi:[1,0] neg_lo:[0,1]
	v_pk_fma_f32 v[178:179], v[154:155], v[172:173], v[178:179] op_sel_hi:[1,0,1]
	v_pk_fma_f32 v[18:19], v[174:175], v[18:19], v[50:51] op_sel_hi:[1,0,1]
	v_pk_mul_f32 v[50:51], v[12:13], v[176:177] op_sel:[1,1] op_sel_hi:[1,0] neg_lo:[0,1]
	v_pk_mul_f32 v[180:181], v[170:171], v[172:173] op_sel:[0,1]
	v_pk_fma_f32 v[12:13], v[176:177], v[12:13], v[50:51] op_sel_hi:[1,0,1]
	v_pk_fma_f32 v[180:181], v[158:159], v[172:173], v[180:181] op_sel_hi:[1,0,1]
	v_pk_mul_f32 v[50:51], v[178:179], v[14:15] op_sel:[1,1] op_sel_hi:[0,1] neg_lo:[1,0]
	v_pk_mul_f32 v[184:185], v[172:173], v[182:183] op_sel:[1,0]
	v_pk_fma_f32 v[14:15], v[178:179], v[14:15], v[50:51] op_sel_hi:[1,0,1]
	v_pk_fma_f32 v[184:185], v[160:161], v[172:173], v[184:185] op_sel_hi:[1,0,1]
	v_pk_mul_f32 v[50:51], v[180:181], v[8:9] op_sel:[1,1] op_sel_hi:[0,1] neg_lo:[1,0]
	v_pk_mul_f32 v[188:189], v[172:173], v[186:187] op_sel:[1,0]
	v_pk_fma_f32 v[8:9], v[180:181], v[8:9], v[50:51] op_sel_hi:[1,0,1]
	v_pk_fma_f32 v[188:189], v[162:163], v[172:173], v[188:189] op_sel_hi:[1,0,1]
	v_pk_mul_f32 v[50:51], v[184:185], v[10:11] op_sel:[1,1] op_sel_hi:[0,1] neg_lo:[1,0]
	v_pk_mul_f32 v[192:193], v[172:173], v[190:191] op_sel:[1,0]
	v_pk_fma_f32 v[10:11], v[184:185], v[10:11], v[50:51] op_sel_hi:[1,0,1]
	v_pk_fma_f32 v[192:193], v[166:167], v[172:173], v[192:193] op_sel_hi:[1,0,1]
	s_waitcnt lgkmcnt(0)
	ds_write_b64 v32, v[42:43]
	ds_write_b64 v32, v[52:53] offset:8256
	ds_write_b64 v32, v[54:55] offset:4128
	ds_write_b64 v32, v[48:49] offset:12384
	ds_write_b64 v32, v[140:141] offset:2064
	ds_write_b64 v32, v[138:139] offset:10320
	ds_write_b64 v32, v[150:151] offset:6192
	ds_write_b64 v32, v[38:39] offset:14448
	ds_write_b64 v32, v[46:47] offset:1032
	ds_write_b64 v32, v[40:41] offset:9288
	ds_write_b64 v32, v[146:147] offset:5160
	ds_write_b64 v32, v[136:137] offset:13416
	ds_write_b64 v32, v[144:145] offset:3096
	ds_write_b64 v32, v[44:45] offset:11352
	ds_write_b64 v32, v[142:143] offset:7224
	ds_write_b64 v32, v[36:37] offset:15480
	v_pk_mul_f32 v[50:51], v[188:189], v[4:5] op_sel:[1,1] op_sel_hi:[0,1] neg_lo:[1,0]
	s_nop 0
	v_pk_fma_f32 v[4:5], v[188:189], v[4:5], v[50:51] op_sel_hi:[1,0,1]
	v_pk_mul_f32 v[50:51], v[192:193], v[6:7] op_sel:[1,1] op_sel_hi:[0,1] neg_lo:[1,0]
	s_nop 0
	v_pk_fma_f32 v[6:7], v[192:193], v[6:7], v[50:51] op_sel_hi:[1,0,1]
	v_pk_add_f32 v[50:51], v[0:1], v[16:17]
	v_pk_add_f32 v[0:1], v[0:1], v[16:17] neg_lo:[0,1] neg_hi:[0,1]
	v_pk_add_f32 v[16:17], v[2:3], v[18:19]
	v_pk_add_f32 v[2:3], v[2:3], v[18:19] neg_lo:[0,1] neg_hi:[0,1]
	s_nop 0
	v_pk_mul_f32 v[18:19], v[2:3], s[96:97] op_sel:[1,0]
	s_nop 0
	v_pk_fma_f32 v[2:3], v[2:3], s[58:59], v[18:19] op_sel_hi:[0,1,1]
	v_pk_add_f32 v[18:19], v[20:21], v[12:13]
	v_pk_add_f32 v[12:13], v[20:21], v[12:13] neg_lo:[0,1] neg_hi:[0,1]
	s_nop 0
	v_mul_f32_e32 v20, 0x3f3504f3, v12
	v_pk_fma_f32 v[12:13], v[12:13], s[94:95], v[20:21] op_sel:[1,0,0] op_sel_hi:[1,1,0]
	v_pk_add_f32 v[20:21], v[22:23], v[14:15]
	v_pk_add_f32 v[14:15], v[22:23], v[14:15] neg_lo:[0,1] neg_hi:[0,1]
	s_nop 0
	v_pk_mul_f32 v[22:23], v[14:15], s[44:45] op_sel:[1,0]
	s_nop 0
	v_pk_fma_f32 v[14:15], v[14:15], s[64:65], v[22:23] op_sel_hi:[0,1,1]
	v_pk_add_f32 v[22:23], v[24:25], v[8:9]
	v_pk_add_f32 v[8:9], v[24:25], v[8:9] neg_lo:[0,1] neg_hi:[0,1]
	s_nop 0
	v_xor_b32_e32 v24, 0x80000000, v9
	v_mov_b32_e32 v25, v8
	v_pk_add_f32 v[8:9], v[26:27], v[10:11]
	v_pk_add_f32 v[10:11], v[26:27], v[10:11] neg_lo:[0,1] neg_hi:[0,1]
	s_nop 0
	v_pk_mul_f32 v[26:27], v[10:11], s[40:41] op_sel:[1,0]
	s_nop 0
	v_pk_fma_f32 v[10:11], v[10:11], s[96:97], v[26:27] op_sel_hi:[0,1,1]
	v_pk_add_f32 v[26:27], v[28:29], v[4:5]
	v_pk_add_f32 v[4:5], v[28:29], v[4:5] neg_lo:[0,1] neg_hi:[0,1]
	s_nop 0
	v_mul_f32_e32 v28, 0xbf3504f3, v5
	v_pk_fma_f32 v[4:5], v[4:5], s[94:95], v[28:29] op_sel_hi:[0,1,0]
	v_pk_add_f32 v[28:29], v[30:31], v[6:7]
	v_pk_add_f32 v[6:7], v[30:31], v[6:7] neg_lo:[0,1] neg_hi:[0,1]
	s_nop 0
	v_pk_mul_f32 v[30:31], v[6:7], s[66:67] op_sel:[1,0]
	s_nop 0
	v_pk_fma_f32 v[6:7], v[6:7], s[44:45], v[30:31] op_sel_hi:[0,1,1]
	v_pk_add_f32 v[30:31], v[50:51], v[22:23]
	v_pk_add_f32 v[22:23], v[50:51], v[22:23] neg_lo:[0,1] neg_hi:[0,1]
	v_pk_add_f32 v[50:51], v[16:17], v[8:9]
	v_pk_add_f32 v[8:9], v[16:17], v[8:9] neg_lo:[0,1] neg_hi:[0,1]
	s_nop 0
	v_mul_f32_e32 v16, 0x3f3504f3, v8
	v_pk_fma_f32 v[8:9], v[8:9], s[94:95], v[16:17] op_sel:[1,0,0] op_sel_hi:[1,1,0]
	v_pk_add_f32 v[16:17], v[18:19], v[26:27]
	v_pk_add_f32 v[18:19], v[18:19], v[26:27] neg_lo:[0,1] neg_hi:[0,1]
	s_nop 0
	v_xor_b32_e32 v26, 0x80000000, v19
	v_mov_b32_e32 v27, v18
	v_pk_add_f32 v[18:19], v[20:21], v[28:29]
	v_pk_add_f32 v[20:21], v[20:21], v[28:29] neg_lo:[0,1] neg_hi:[0,1]
	s_nop 0
	v_mul_f32_e32 v28, 0xbf3504f3, v21
	v_pk_fma_f32 v[20:21], v[20:21], s[94:95], v[28:29] op_sel_hi:[0,1,0]
	v_pk_add_f32 v[28:29], v[0:1], v[24:25]
	v_pk_add_f32 v[0:1], v[0:1], v[24:25] neg_lo:[0,1] neg_hi:[0,1]
	v_pk_add_f32 v[24:25], v[2:3], v[10:11]
	v_pk_add_f32 v[2:3], v[2:3], v[10:11] neg_lo:[0,1] neg_hi:[0,1]
	s_nop 0
	v_mul_f32_e32 v10, 0x3f3504f3, v2
	v_pk_fma_f32 v[2:3], v[2:3], s[94:95], v[10:11] op_sel:[1,0,0] op_sel_hi:[1,1,0]
	v_pk_add_f32 v[10:11], v[12:13], v[4:5]
	v_pk_add_f32 v[4:5], v[12:13], v[4:5] neg_lo:[0,1] neg_hi:[0,1]
	s_nop 0
	v_xor_b32_e32 v12, 0x80000000, v5
	v_mov_b32_e32 v13, v4
	v_pk_add_f32 v[4:5], v[14:15], v[6:7]
	v_pk_add_f32 v[6:7], v[14:15], v[6:7] neg_lo:[0,1] neg_hi:[0,1]
	s_nop 0
	v_mul_f32_e32 v14, 0xbf3504f3, v7
	v_pk_fma_f32 v[6:7], v[6:7], s[94:95], v[14:15] op_sel_hi:[0,1,0]
	v_pk_add_f32 v[14:15], v[30:31], v[16:17]
	v_pk_add_f32 v[16:17], v[30:31], v[16:17] neg_lo:[0,1] neg_hi:[0,1]
	v_pk_add_f32 v[30:31], v[50:51], v[18:19]
	v_pk_add_f32 v[18:19], v[50:51], v[18:19] neg_lo:[0,1] neg_hi:[0,1]
	s_nop 0
	v_xor_b32_e32 v50, 0x80000000, v19
	v_mov_b32_e32 v51, v18
	v_pk_add_f32 v[18:19], v[22:23], v[26:27]
	v_pk_add_f32 v[22:23], v[22:23], v[26:27] neg_lo:[0,1] neg_hi:[0,1]
	v_pk_add_f32 v[26:27], v[8:9], v[20:21]
	v_pk_add_f32 v[8:9], v[8:9], v[20:21] neg_lo:[0,1] neg_hi:[0,1]
	s_nop 0
	v_xor_b32_e32 v20, 0x80000000, v9
	v_mov_b32_e32 v21, v8
	v_pk_add_f32 v[8:9], v[28:29], v[10:11]
	v_pk_add_f32 v[10:11], v[28:29], v[10:11] neg_lo:[0,1] neg_hi:[0,1]
	v_pk_add_f32 v[28:29], v[24:25], v[4:5]
	v_pk_add_f32 v[4:5], v[24:25], v[4:5] neg_lo:[0,1] neg_hi:[0,1]
	s_nop 0
	v_xor_b32_e32 v24, 0x80000000, v5
	v_mov_b32_e32 v25, v4
	v_pk_add_f32 v[4:5], v[0:1], v[12:13]
	v_pk_add_f32 v[0:1], v[0:1], v[12:13] neg_lo:[0,1] neg_hi:[0,1]
	v_pk_add_f32 v[12:13], v[2:3], v[6:7]
	v_pk_add_f32 v[2:3], v[2:3], v[6:7] neg_lo:[0,1] neg_hi:[0,1]
	s_nop 0
	v_xor_b32_e32 v6, 0x80000000, v3
	v_mov_b32_e32 v7, v2
	v_pk_add_f32 v[2:3], v[14:15], v[30:31]
	v_pk_add_f32 v[14:15], v[14:15], v[30:31] neg_lo:[0,1] neg_hi:[0,1]
	ds_write_b64 v34, v[2:3]
	v_pk_add_f32 v[30:31], v[16:17], v[50:51]
	ds_write_b64 v34, v[14:15] offset:8256
	v_pk_add_f32 v[16:17], v[16:17], v[50:51] neg_lo:[0,1] neg_hi:[0,1]
	ds_write_b64 v34, v[30:31] offset:4128
	v_pk_add_f32 v[50:51], v[18:19], v[26:27]
	ds_write_b64 v34, v[16:17] offset:12384
	v_pk_add_f32 v[18:19], v[18:19], v[26:27] neg_lo:[0,1] neg_hi:[0,1]
	ds_write_b64 v34, v[50:51] offset:2064
	v_pk_add_f32 v[26:27], v[22:23], v[20:21]
	ds_write_b64 v34, v[18:19] offset:10320
	v_pk_add_f32 v[20:21], v[22:23], v[20:21] neg_lo:[0,1] neg_hi:[0,1]
	ds_write_b64 v34, v[26:27] offset:6192
	v_pk_add_f32 v[22:23], v[8:9], v[28:29]
	ds_write_b64 v34, v[20:21] offset:14448
	v_pk_add_f32 v[8:9], v[8:9], v[28:29] neg_lo:[0,1] neg_hi:[0,1]
	ds_write_b64 v34, v[22:23] offset:1032
	v_pk_add_f32 v[28:29], v[10:11], v[24:25]
	ds_write_b64 v34, v[8:9] offset:9288
	v_pk_add_f32 v[10:11], v[10:11], v[24:25] neg_lo:[0,1] neg_hi:[0,1]
	ds_write_b64 v34, v[28:29] offset:5160
	v_pk_add_f32 v[24:25], v[4:5], v[12:13]
	ds_write_b64 v34, v[10:11] offset:13416
	v_pk_add_f32 v[4:5], v[4:5], v[12:13] neg_lo:[0,1] neg_hi:[0,1]
	ds_write_b64 v34, v[24:25] offset:3096
	v_pk_add_f32 v[12:13], v[0:1], v[6:7]
	ds_write_b64 v34, v[4:5] offset:11352
	v_pk_add_f32 v[0:1], v[0:1], v[6:7] neg_lo:[0,1] neg_hi:[0,1]
	ds_write_b64 v34, v[12:13] offset:7224
	ds_write_b64 v34, v[0:1] offset:15480
	s_andn2_b64 exec, exec, s[92:93]
	s_cbranch_execnz .LBB0_362

.LBB0_365:
	v_ashrrev_i32_e32 v0, 7, v37
	v_add_u32_e32 v66, 0x200, v37
	v_ashrrev_i32_e32 v2, 7, v66
	v_mad_u64_u32 v[0:1], s[40:41], v0, s25, v[60:61]
	v_mov_b32_e32 v26, v37
	v_mad_u64_u32 v[2:3], s[40:41], v2, s25, v[60:61]
	v_add_u32_e32 v1, 0x10200, v0
	ds_read_b64 v[22:23], v0
	ds_read_b64 v[4:5], v2
	ds_read_b64 v[20:21], v0 offset:16512
	ds_read_b64 v[6:7], v2 offset:16512
	ds_read_b64 v[24:25], v0 offset:33024
	ds_read_b64 v[8:9], v2 offset:33024
	ds_read_b64 v[28:29], v0 offset:49536
	ds_read_b64 v[10:11], v2 offset:49536
	ds_read_b64 v[30:31], v1
	v_add_u32_e32 v1, 0x10200, v2
	ds_read_b64 v[12:13], v1
	v_add_u32_e32 v1, 0x14280, v0
	ds_read_b64 v[32:33], v1
	v_add_u32_e32 v1, 0x14280, v2
	ds_read_b64 v[14:15], v1
	v_add_u32_e32 v1, 0x18300, v0
	ds_read_b64 v[34:35], v1
	v_add_u32_e32 v1, 0x18300, v2
	ds_read_b64 v[16:17], v1
	v_add_u32_e32 v1, 0x1c380, v0
	ds_read_b64 v[38:39], v1
	v_add_u32_e32 v1, 0x1c380, v2
	ds_read_b64 v[18:19], v1
	v_cvt_f32_i32_e32 v1, v26
	s_mov_b32 s40, s57
	s_mov_b32 s41, s56
	v_cmp_lt_i32_e32 vcc, s28, v37
	v_mul_f32_e32 v1, 0x38800000, v1
	v_cos_f32_e32 v26, v1
	v_sin_f32_e32 v27, v1
	v_cvt_f32_i32_e32 v1, v66
	s_or_b64 s[92:93], vcc, s[92:93]
	v_mov_b32_e32 v41, v26
	v_mov_b32_e32 v36, v27
	v_xor_b32_e32 v40, 0x80000000, v27
	v_pk_mul_f32 v[42:43], v[40:41], v[36:37] op_sel_hi:[1,0]
	v_mul_f32_e32 v1, 0x38800000, v1
	v_pk_fma_f32 v[42:43], v[26:27], v[26:27], v[42:43] op_sel_hi:[1,0,1]
	s_nop 0
	v_pk_mul_f32 v[48:49], v[42:43], v[42:43] op_sel:[1,1] op_sel_hi:[1,0] neg_lo:[0,1]
	v_pk_mul_f32 v[44:45], v[40:41], v[42:43] op_sel:[0,1]
	v_pk_fma_f32 v[48:49], v[42:43], v[42:43], v[48:49] op_sel_hi:[1,0,1]
	v_pk_fma_f32 v[44:45], v[26:27], v[42:43], v[44:45] op_sel_hi:[1,0,1]
	v_pk_mul_f32 v[50:51], v[40:41], v[48:49] op_sel:[0,1]
	s_waitcnt lgkmcnt(13)
	v_pk_mul_f32 v[40:41], v[40:41], v[20:21] op_sel:[0,1]
	v_pk_fma_f32 v[40:41], v[26:27], v[20:21], v[40:41] op_sel_hi:[1,0,1]
	s_waitcnt lgkmcnt(11)
	v_pk_mul_f32 v[20:21], v[24:25], v[42:43] op_sel:[1,1] op_sel_hi:[1,0] neg_lo:[0,1]
	v_pk_fma_f32 v[50:51], v[26:27], v[48:49], v[50:51] op_sel_hi:[1,0,1]
	v_pk_fma_f32 v[26:27], v[24:25], v[42:43], v[20:21] op_sel_hi:[0,1,1]
	s_waitcnt lgkmcnt(9)
	v_pk_mul_f32 v[20:21], v[28:29], v[44:45] op_sel:[1,1] op_sel_hi:[1,0] neg_lo:[0,1]
	v_pk_mul_f32 v[52:53], v[42:43], v[48:49] op_sel:[1,1] op_sel_hi:[0,1] neg_lo:[1,0]
	v_pk_fma_f32 v[24:25], v[28:29], v[44:45], v[20:21] op_sel_hi:[0,1,1]
	s_waitcnt lgkmcnt(7)
	v_pk_mul_f32 v[20:21], v[30:31], v[48:49] op_sel:[1,1] op_sel_hi:[1,0] neg_lo:[0,1]
	v_pk_fma_f32 v[52:53], v[42:43], v[48:49], v[52:53] op_sel_hi:[1,0,1]
	v_pk_fma_f32 v[28:29], v[30:31], v[48:49], v[20:21] op_sel_hi:[0,1,1]
	s_waitcnt lgkmcnt(5)
	v_pk_mul_f32 v[20:21], v[32:33], v[50:51] op_sel:[1,1] op_sel_hi:[1,0] neg_lo:[0,1]
	v_pk_mul_f32 v[136:137], v[48:49], v[44:45] op_sel:[1,1] op_sel_hi:[1,0] neg_lo:[0,1]
	v_pk_fma_f32 v[42:43], v[32:33], v[50:51], v[20:21] op_sel_hi:[0,1,1]
	v_pk_fma_f32 v[136:137], v[44:45], v[48:49], v[136:137] op_sel_hi:[1,0,1]
	s_waitcnt lgkmcnt(3)
	v_pk_mul_f32 v[20:21], v[34:35], v[52:53] op_sel:[1,1] op_sel_hi:[1,0] neg_lo:[0,1]
	s_nop 0
	v_pk_fma_f32 v[30:31], v[34:35], v[52:53], v[20:21] op_sel_hi:[0,1,1]
	s_waitcnt lgkmcnt(1)
	v_pk_mul_f32 v[20:21], v[38:39], v[136:137] op_sel:[1,1] op_sel_hi:[1,0] neg_lo:[0,1]
	v_pk_add_f32 v[34:35], v[40:41], v[42:43] neg_lo:[0,1] neg_hi:[0,1]
	v_pk_fma_f32 v[32:33], v[136:137], v[38:39], v[20:21] op_sel_hi:[1,0,1]
	v_pk_add_f32 v[38:39], v[26:27], v[30:31]
	v_pk_add_f32 v[26:27], v[26:27], v[30:31] neg_lo:[0,1] neg_hi:[0,1]
	v_pk_add_f32 v[20:21], v[22:23], v[28:29]
	v_xor_b32_e32 v30, 0x80000000, v27
	v_mov_b32_e32 v31, v26
	v_pk_add_f32 v[26:27], v[24:25], v[32:33]
	v_pk_add_f32 v[24:25], v[24:25], v[32:33] neg_lo:[0,1] neg_hi:[0,1]
	v_pk_add_f32 v[28:29], v[22:23], v[28:29] neg_lo:[0,1] neg_hi:[0,1]
	v_pk_add_f32 v[22:23], v[40:41], v[42:43]
	v_mul_f32_e32 v36, 0x3f3504f3, v34
	v_mul_f32_e32 v32, 0xbf3504f3, v25
	v_pk_fma_f32 v[34:35], v[34:35], s[40:41], v[36:37] op_sel:[1,0,0] op_sel_hi:[1,1,0]
	v_pk_fma_f32 v[24:25], v[24:25], s[40:41], v[32:33] op_sel_hi:[0,1,0]
	v_pk_add_f32 v[40:41], v[22:23], v[26:27] neg_lo:[0,1] neg_hi:[0,1]
	v_pk_add_f32 v[32:33], v[20:21], v[38:39] neg_lo:[0,1] neg_hi:[0,1]
	v_xor_b32_e32 v42, 0x80000000, v41
	v_mov_b32_e32 v43, v40
	v_pk_add_f32 v[40:41], v[28:29], v[30:31]
	v_pk_add_f32 v[28:29], v[28:29], v[30:31] neg_lo:[0,1] neg_hi:[0,1]
	v_pk_add_f32 v[30:31], v[34:35], v[24:25]
	v_pk_add_f32 v[24:25], v[34:35], v[24:25] neg_lo:[0,1] neg_hi:[0,1]
	v_pk_add_f32 v[30:31], v[40:41], v[30:31]
	v_xor_b32_e32 v34, 0x80000000, v25
	v_mov_b32_e32 v35, v24
	v_pk_add_f32 v[24:25], v[32:33], v[42:43]
	v_cos_f32_e32 v32, v1
	v_sin_f32_e32 v33, v1
	v_pk_add_f32 v[28:29], v[28:29], v[34:35]
	v_add_u32_e32 v37, 0x400, v37
	v_mov_b32_e32 v41, v32
	v_mov_b32_e32 v34, v33
	v_xor_b32_e32 v40, 0x80000000, v33
	v_pk_mul_f32 v[34:35], v[40:41], v[34:35] op_sel_hi:[1,0]
	s_nop 0
	v_pk_fma_f32 v[34:35], v[32:33], v[32:33], v[34:35] op_sel_hi:[1,0,1]
	s_nop 0
	v_xor_b32_e32 v44, 0x80000000, v35
	v_mov_b32_e32 v45, v34
	v_pk_mul_f32 v[46:47], v[34:35], v[44:45] op_sel:[1,0]
	v_pk_mul_f32 v[42:43], v[40:41], v[34:35] op_sel:[0,1]
	v_pk_fma_f32 v[46:47], v[34:35], v[34:35], v[46:47] op_sel_hi:[1,0,1]
	v_pk_fma_f32 v[42:43], v[32:33], v[34:35], v[42:43] op_sel_hi:[1,0,1]
	v_pk_mul_f32 v[48:49], v[40:41], v[46:47] op_sel:[0,1]
	v_pk_mul_f32 v[40:41], v[40:41], v[6:7] op_sel:[0,1]
	v_pk_fma_f32 v[48:49], v[32:33], v[46:47], v[48:49] op_sel_hi:[1,0,1]
	v_xor_b32_e32 v52, 0x80000000, v43
	v_mov_b32_e32 v53, v42
	v_pk_fma_f32 v[6:7], v[32:33], v[6:7], v[40:41] op_sel_hi:[1,0,1]
	v_pk_mul_f32 v[32:33], v[8:9], v[44:45] op_sel:[1,0]
	v_pk_mul_f32 v[50:51], v[44:45], v[46:47] op_sel:[0,1]
	v_pk_fma_f32 v[8:9], v[8:9], v[34:35], v[32:33] op_sel_hi:[0,1,1]
	v_pk_mul_f32 v[32:33], v[10:11], v[52:53] op_sel:[1,0]
	v_pk_fma_f32 v[50:51], v[34:35], v[46:47], v[50:51] op_sel_hi:[1,0,1]
	v_pk_fma_f32 v[10:11], v[10:11], v[42:43], v[32:33] op_sel_hi:[0,1,1]
	v_pk_mul_f32 v[32:33], v[12:13], v[46:47] op_sel:[1,1] op_sel_hi:[1,0] neg_lo:[0,1]
	v_pk_mul_f32 v[54:55], v[46:47], v[52:53] op_sel:[1,0]
	v_pk_fma_f32 v[12:13], v[12:13], v[46:47], v[32:33] op_sel_hi:[0,1,1]
	v_pk_mul_f32 v[32:33], v[14:15], v[48:49] op_sel:[1,1] op_sel_hi:[1,0] neg_lo:[0,1]
	v_pk_fma_f32 v[54:55], v[42:43], v[46:47], v[54:55] op_sel_hi:[1,0,1]
	v_pk_fma_f32 v[14:15], v[14:15], v[48:49], v[32:33] op_sel_hi:[0,1,1]
	v_pk_mul_f32 v[32:33], v[16:17], v[50:51] op_sel:[1,1] op_sel_hi:[1,0] neg_lo:[0,1]
	s_nop 0
	v_pk_fma_f32 v[16:17], v[16:17], v[50:51], v[32:33] op_sel_hi:[0,1,1]
	s_waitcnt lgkmcnt(0)
	ds_write_b64 v0, v[24:25] offset:33024
	ds_write_b64 v0, v[30:31] offset:16512
	ds_write_b64 v0, v[28:29] offset:49536
	v_pk_mul_f32 v[32:33], v[18:19], v[54:55] op_sel:[1,1] op_sel_hi:[1,0] neg_lo:[0,1]
	s_nop 0
	v_pk_fma_f32 v[18:19], v[54:55], v[18:19], v[32:33] op_sel_hi:[1,0,1]
	v_pk_add_f32 v[32:33], v[4:5], v[12:13]
	v_pk_add_f32 v[4:5], v[4:5], v[12:13] neg_lo:[0,1] neg_hi:[0,1]
	v_pk_add_f32 v[12:13], v[6:7], v[14:15]
	v_pk_add_f32 v[6:7], v[6:7], v[14:15] neg_lo:[0,1] neg_hi:[0,1]
	s_nop 0
	v_mul_f32_e32 v14, 0x3f3504f3, v6
	v_pk_fma_f32 v[6:7], v[6:7], s[40:41], v[14:15] op_sel:[1,0,0] op_sel_hi:[1,1,0]
	v_pk_add_f32 v[14:15], v[8:9], v[16:17]
	v_pk_add_f32 v[8:9], v[8:9], v[16:17] neg_lo:[0,1] neg_hi:[0,1]
	s_nop 0
	v_xor_b32_e32 v16, 0x80000000, v9
	v_mov_b32_e32 v17, v8
	v_pk_add_f32 v[8:9], v[10:11], v[18:19]
	v_pk_add_f32 v[10:11], v[10:11], v[18:19] neg_lo:[0,1] neg_hi:[0,1]
	v_pk_add_f32 v[34:35], v[12:13], v[8:9] neg_lo:[0,1] neg_hi:[0,1]
	v_mul_f32_e32 v18, 0xbf3504f3, v11
	v_pk_fma_f32 v[10:11], v[10:11], s[40:41], v[18:19] op_sel_hi:[0,1,0]
	v_xor_b32_e32 v40, 0x80000000, v35
	v_mov_b32_e32 v41, v34
	v_pk_add_f32 v[34:35], v[4:5], v[16:17]
	v_pk_add_f32 v[4:5], v[4:5], v[16:17] neg_lo:[0,1] neg_hi:[0,1]
	v_pk_add_f32 v[16:17], v[6:7], v[10:11]
	v_pk_add_f32 v[6:7], v[6:7], v[10:11] neg_lo:[0,1] neg_hi:[0,1]
	v_pk_add_f32 v[8:9], v[12:13], v[8:9]
	v_pk_add_f32 v[4:5], v[4:5], v[6:7] op_sel:[0,1] op_sel_hi:[1,0] neg_lo:[0,1]
	v_pk_add_f32 v[10:11], v[32:33], v[14:15]
	ds_write_b64 v2, v[4:5] offset:49536
	v_pk_add_f32 v[12:13], v[20:21], v[38:39]
	v_pk_add_f32 v[8:9], v[10:11], v[8:9]
	v_pk_add_f32 v[10:11], v[22:23], v[26:27]
	ds_write_b64 v2, v[8:9]
	v_pk_add_f32 v[18:19], v[32:33], v[14:15] neg_lo:[0,1] neg_hi:[0,1]
	v_pk_add_f32 v[10:11], v[12:13], v[10:11]
	v_pk_add_f32 v[6:7], v[18:19], v[40:41]
	ds_write_b64 v0, v[10:11]
	v_pk_add_f32 v[16:17], v[34:35], v[16:17]
	ds_write_b64 v2, v[6:7] offset:33024
	ds_write_b64 v2, v[16:17] offset:16512
	s_andn2_b64 exec, exec, s[92:93]
	s_cbranch_execnz .LBB0_365
.LBB0_366:
	s_or_b64 exec, exec, s[90:91]
	s_waitcnt lgkmcnt(0)
	s_barrier
	ds_read_b64 v[0:1], v214
	ds_read_b64 v[2:3], v214 offset:8
	ds_read_b64 v[4:5], v214 offset:16
	ds_read_b64 v[6:7], v214 offset:24
	ds_read_b64 v[8:9], v214 offset:32
	ds_read_b64 v[10:11], v214 offset:40
	ds_read_b64 v[12:13], v214 offset:48
	ds_read_b64 v[14:15], v214 offset:56
	ds_read_b64 v[16:17], v215
	ds_read_b64 v[18:19], v215 offset:8
	ds_read_b64 v[20:21], v215 offset:16
	ds_read_b64 v[22:23], v215 offset:24
	ds_read_b64 v[24:25], v215 offset:32
	ds_read_b64 v[26:27], v215 offset:40
	ds_read_b64 v[28:29], v215 offset:48
	ds_read_b64 v[30:31], v215 offset:56
	s_lshl_b32 s33, s80, 11
	s_add_i32 s40, s33, s82
	s_ashr_i32 s41, s40, 31
	s_lshl_b64 s[40:41], s[40:41], 14
	s_add_u32 s92, s8, s40
	s_addc_u32 s93, s9, s41
	s_add_u32 s90, s92, 0x1000000
	s_addc_u32 s91, s93, 0
	v_lshlrev_b64 v[32:33], 1, v[62:63]
	v_lshlrev_b64 v[34:35], 1, v[70:71]
	v_lshl_add_u64 v[36:37], s[92:93], 0, v[32:33]
	v_lshl_add_u64 v[38:39], s[90:91], 0, v[32:33]
	v_lshl_add_u64 v[40:41], s[92:93], 0, v[34:35]
	v_lshl_add_u64 v[42:43], s[90:91], 0, v[34:35]
	s_waitcnt lgkmcnt(8)
	v_cvt_pk_bf16_f32 v136, v0, v2
	v_cvt_pk_bf16_f32 v137, v4, v6
	v_cvt_pk_bf16_f32 v138, v8, v10
	v_cvt_pk_bf16_f32 v139, v12, v14
	v_cvt_pk_bf16_f32 v140, v1, v3
	v_cvt_pk_bf16_f32 v141, v5, v7
	v_cvt_pk_bf16_f32 v142, v9, v11
	v_cvt_pk_bf16_f32 v143, v13, v15
	global_store_dwordx4 v[36:37], v[136:139], off
	global_store_dwordx4 v[38:39], v[140:143], off
	s_waitcnt lgkmcnt(0)
	v_cvt_pk_bf16_f32 v144, v16, v18
	v_cvt_pk_bf16_f32 v145, v20, v22
	v_cvt_pk_bf16_f32 v146, v24, v26
	v_cvt_pk_bf16_f32 v147, v28, v30
	v_cvt_pk_bf16_f32 v150, v17, v19
	v_cvt_pk_bf16_f32 v151, v21, v23
	v_cvt_pk_bf16_f32 v152, v25, v27
	v_cvt_pk_bf16_f32 v153, v29, v31
	global_store_dwordx4 v[40:41], v[144:147], off
	global_store_dwordx4 v[42:43], v[150:153], off
	s_add_i32 s80, s80, 1
	s_cmp_eq_u32 s80, 4
	s_cbranch_scc1 .LBB0_398
	s_branch .LBB0_309
